# adds nt to the residual-stream XB / final-output stores (not re-read before eviction) on top of the nt read-once loads
# speedup vs baseline: 1.0089x; 1.0089x over previous
; template <int OFF = 0, class V> __device__ __forceinline__ void st_wt8(void* p, V v) { static_assert(sizeof(V) == 8, ""); asm volatile("global_store_dwordx2 %0, %1, off offset:%2 sc1\n\ts_nop 1" :: "v"(p), "v"(v), "i"(OFF)); }
; __device__ __forceinline__ unsigned pk2(float lo, float hi) { return pg8::cvt_pk_bf16(lo, hi); }
; #define ROW_OUT(m_, r_) row_to_bf16(r_, XB + (size_t)(m_) * DM, RS + (m_), (unsigned*)(ws + WS_XQ) + (size_t)(m_) * (DM / 4), (float*)(ws + WS_AS) + (m_), lane)
; __device__ __forceinline__ void row_load(const float* __restrict__ xrow, int lane, f32x4 (&ov)[16]) {
; #pragma unroll
;     for (int j = 0; j < 16; ++j) ov[j] = *(const f32x4*)(xrow + (lane + 64 * j) * 4);
; }
; __device__ __forceinline__ void row_to_bf16(const f32x4 (&ov)[16], bf16* __restrict__ orow, float* rs_out, unsigned* __restrict__ xq, float* as_out, int lane) {
;     float ss = 0.f, am = 0.f;
; #pragma unroll
;     for (int j = 0; j < 16; ++j) { const int c = (lane + 64 * j) * 4; const f32x4 v = ov[j];
;         ss += (v.x * v.x + v.y * v.y) + (v.z * v.z + v.w * v.w); am = fmaxf(fmaxf(am, fmaxf(fabsf(v.x), fabsf(v.y))), fmaxf(fabsf(v.z), fabsf(v.w)));
;         v2u o; o.x = pk2(v.x, v.y); o.y = pk2(v.z, v.w); st_wt8(orow + c, o); }
; __global__ void __launch_bounds__(NWAVES * 64, 2) mk_fwd(Args args) {
;     ...
;             for (int k = 0; k < n; k += 2) { const int m1 = min(gw + (k + 1) * NGW, lastm), m2 = min(gw + (k + 2) * NGW, lastm);
;                 row_load(x_in + (size_t)m1 * DM, lane, rB); ROW_OUT(gw + k * NGW, rA);
;                 row_load(x_in + (size_t)m2 * DM, lane, rA); ROW_OUT(m1, rB); }
.LBB0_62:
	s_add_i32 s4, s56, s52
	v_min_i32_e32 v158, s4, v165
	v_ashrrev_i32_e32 v159, 31, v158
	v_lshlrev_b64 v[28:29], 14, v[158:159]
	v_lshl_add_u64 v[28:29], s[12:13], 0, v[28:29]
	v_lshl_add_u64 v[30:31], v[130:131], 2, v[28:29]
	global_load_dwordx4 v[124:127], v[30:31], off nt
	global_load_dwordx4 v[120:123], v[30:31], off offset:1024 nt
	global_load_dwordx4 v[116:119], v[30:31], off offset:2048 nt
	global_load_dwordx4 v[112:115], v[30:31], off offset:3072 nt
	v_lshl_add_u64 v[30:31], v[132:133], 2, v[28:29]
	v_lshl_add_u64 v[36:37], v[134:135], 2, v[28:29]
	global_load_dwordx4 v[108:111], v[30:31], off nt
	global_load_dwordx4 v[100:103], v[36:37], off nt
	v_lshl_add_u64 v[30:31], v[136:137], 2, v[28:29]
	v_lshl_add_u64 v[36:37], v[138:139], 2, v[28:29]
	global_load_dwordx4 v[96:99], v[30:31], off nt
	global_load_dwordx4 v[88:91], v[36:37], off nt
	v_lshl_add_u64 v[30:31], v[140:141], 2, v[28:29]
	v_lshl_add_u64 v[36:37], v[142:143], 2, v[28:29]
	global_load_dwordx4 v[80:83], v[30:31], off nt
	global_load_dwordx4 v[72:75], v[36:37], off nt
	v_lshl_add_u64 v[30:31], v[144:145], 2, v[28:29]
	s_ashr_i32 s53, s52, 31
	v_lshl_add_u64 v[36:37], v[146:147], 2, v[28:29]
	global_load_dwordx4 v[64:67], v[30:31], off nt
	global_load_dwordx4 v[60:63], v[36:37], off nt
	v_lshl_add_u64 v[30:31], v[148:149], 2, v[28:29]
	s_lshl_b64 s[4:5], s[52:53], 13
	v_lshl_add_u64 v[36:37], v[150:151], 2, v[28:29]
	global_load_dwordx4 v[52:55], v[30:31], off nt
	global_load_dwordx4 v[44:47], v[36:37], off nt
	v_lshl_add_u64 v[30:31], v[152:153], 2, v[28:29]
	v_lshl_add_u64 v[28:29], v[154:155], 2, v[28:29]
	s_add_u32 s4, s16, s4
	global_load_dwordx4 v[36:39], v[30:31], off nt
	s_nop 0
	global_load_dwordx4 v[28:31], v[28:29], off nt
	s_addc_u32 s5, s17, s5
	s_waitcnt vmcnt(16)
	v_cvt_pk_bf16_f32 v160, v104, v105
	v_cvt_pk_bf16_f32 v161, v106, v107
	v_lshl_add_u64 v[162:163], v[130:131], 1, s[4:5]
	global_store_dwordx2 v[162:163], v[160:161], off offset:0 sc1 nt
	s_nop 1
	v_cvt_pk_bf16_f32 v160, v92, v93
	v_cvt_pk_bf16_f32 v161, v94, v95
	v_lshl_add_u64 v[168:169], v[162:163], 0, s[20:21]
	global_store_dwordx2 v[168:169], v[160:161], off offset:0 sc1 nt
	s_nop 1
	v_cvt_pk_bf16_f32 v160, v84, v85
	v_cvt_pk_bf16_f32 v161, v86, v87
	v_lshl_add_u64 v[168:169], v[162:163], 0, s[22:23]
	global_store_dwordx2 v[168:169], v[160:161], off offset:0 sc1 nt
	s_nop 1
	v_cvt_pk_bf16_f32 v160, v76, v77
	v_cvt_pk_bf16_f32 v161, v78, v79
	v_lshl_add_u64 v[168:169], v[162:163], 0, s[24:25]
	global_store_dwordx2 v[168:169], v[160:161], off offset:0 sc1 nt
	s_nop 1
	v_cvt_pk_bf16_f32 v160, v68, v69
	v_cvt_pk_bf16_f32 v161, v70, v71
	v_lshl_add_u64 v[168:169], v[162:163], 0, s[26:27]
	global_store_dwordx2 v[168:169], v[160:161], off offset:0 sc1 nt
	s_nop 1
	v_cvt_pk_bf16_f32 v160, v56, v57
	v_cvt_pk_bf16_f32 v161, v58, v59
	v_lshl_add_u64 v[168:169], v[162:163], 0, s[28:29]
	global_store_dwordx2 v[168:169], v[160:161], off offset:0 sc1 nt
	s_nop 1
	v_cvt_pk_bf16_f32 v160, v48, v49
	v_cvt_pk_bf16_f32 v161, v50, v51
	v_lshl_add_u64 v[168:169], v[162:163], 0, s[30:31]
	global_store_dwordx2 v[168:169], v[160:161], off offset:0 sc1 nt
	s_nop 1
	v_max_f32_e64 v160, |v105|, |v105|
	v_max_f32_e64 v161, |v104|, |v104|
	v_max_f32_e32 v160, v161, v160
	v_max_f32_e64 v161, |v107|, |v107|
	v_max_f32_e64 v168, |v106|, |v106|
	v_max_f32_e32 v161, v168, v161
	v_max3_f32 v160, v160, 0, v161
	v_max_f32_e64 v161, |v93|, |v93|
	v_max_f32_e64 v168, |v92|, |v92|
	v_max_f32_e32 v161, v168, v161
	v_max_f32_e64 v168, |v95|, |v95|
	v_max_f32_e64 v169, |v94|, |v94|
	v_max_f32_e32 v168, v169, v168
	v_max3_f32 v160, v160, v161, v168
	v_max_f32_e64 v161, |v85|, |v85|
	v_max_f32_e64 v168, |v84|, |v84|
	v_max_f32_e32 v161, v168, v161
	v_max_f32_e64 v168, |v87|, |v87|
	v_max_f32_e64 v169, |v86|, |v86|
	v_max_f32_e32 v168, v169, v168
	v_max3_f32 v160, v160, v161, v168
	v_max_f32_e64 v161, |v77|, |v77|
	v_max_f32_e64 v168, |v76|, |v76|
	v_max_f32_e32 v161, v168, v161
	v_max_f32_e64 v168, |v79|, |v79|
	v_max_f32_e64 v169, |v78|, |v78|
	v_max_f32_e32 v168, v169, v168
	v_max3_f32 v160, v160, v161, v168
	v_max_f32_e64 v161, |v69|, |v69|
	v_max_f32_e64 v168, |v68|, |v68|
	v_max_f32_e32 v161, v168, v161
	v_max_f32_e64 v168, |v71|, |v71|
	v_max_f32_e64 v169, |v70|, |v70|
	v_max_f32_e32 v168, v169, v168
	v_max3_f32 v160, v160, v161, v168
	v_max_f32_e64 v161, |v57|, |v57|
	v_max_f32_e64 v168, |v56|, |v56|
	v_max_f32_e32 v161, v168, v161
	v_max_f32_e64 v168, |v59|, |v59|
	v_max_f32_e64 v169, |v58|, |v58|
	v_max_f32_e32 v168, v169, v168
	v_max3_f32 v160, v160, v161, v168
	v_max_f32_e64 v161, |v49|, |v49|
	v_max_f32_e64 v168, |v48|, |v48|
	v_max_f32_e32 v161, v168, v161
	v_max_f32_e64 v168, |v51|, |v51|
	v_max_f32_e64 v169, |v50|, |v50|
	v_max_f32_e32 v168, v169, v168
	v_max3_f32 v160, v160, v161, v168
	v_max_f32_e64 v161, |v41|, |v41|
	v_max_f32_e64 v168, |v40|, |v40|
	v_max_f32_e32 v161, v168, v161
	v_max_f32_e64 v168, |v43|, |v43|
	v_max_f32_e64 v169, |v42|, |v42|
	v_max_f32_e32 v168, v169, v168
	v_max3_f32 v168, v160, v161, v168
	v_cvt_pk_bf16_f32 v160, v40, v41
	v_cvt_pk_bf16_f32 v161, v42, v43
	v_lshl_add_u64 v[162:163], v[162:163], 0, s[34:35]
	global_store_dwordx2 v[162:163], v[160:161], off offset:0 sc1 nt
	s_nop 1
	v_max_f32_e64 v160, |v33|, |v33|
	v_max_f32_e64 v161, |v32|, |v32|
	v_max_f32_e32 v160, v161, v160
	v_max_f32_e64 v161, |v35|, |v35|
	v_max_f32_e64 v162, |v34|, |v34|
	v_max_f32_e32 v161, v162, v161
	v_max3_f32 v168, v168, v160, v161
	v_cvt_pk_bf16_f32 v160, v32, v33
	v_cvt_pk_bf16_f32 v161, v34, v35
	v_lshl_add_u64 v[162:163], v[140:141], 1, s[4:5]
	global_store_dwordx2 v[162:163], v[160:161], off offset:0 sc1 nt
; template <int O> __device__ __forceinline__ float xsw(float v) { return __int_as_float(__builtin_amdgcn_ds_swizzle(__float_as_int(v), (O << 10) | 0x1f)); }
; __device__ __forceinline__ float xmax32(float v) { auto rr = __builtin_amdgcn_permlane32_swap(__float_as_uint(v), __float_as_uint(v), false, false); return fmaxf(__uint_as_float(rr[0]), __uint_as_float(rr[1])); }
; template <int OFF = 0, class V> __device__ __forceinline__ void st_wt8(void* p, V v) { static_assert(sizeof(V) == 8, ""); asm volatile("global_store_dwordx2 %0, %1, off offset:%2 sc1\n\ts_nop 1" :: "v"(p), "v"(v), "i"(OFF)); }
; __device__ __forceinline__ unsigned pk2(float lo, float hi) { return pg8::cvt_pk_bf16(lo, hi); }
; __device__ __forceinline__ float wave_max(float v) {
;     v = fmaxf(v, xsw<1>(v)); v = fmaxf(v, xsw<2>(v)); v = fmaxf(v, xsw<4>(v)); v = fmaxf(v, xsw<8>(v)); v = fmaxf(v, xsw<16>(v));
;     return xmax32(v);
; }
; __device__ __forceinline__ void row_to_bf16(const f32x4 (&ov)[16], bf16* __restrict__ orow, float* rs_out, unsigned* __restrict__ xq, float* as_out, int lane) {
;     float ss = 0.f, am = 0.f;
; #pragma unroll
;     for (int j = 0; j < 16; ++j) { const int c = (lane + 64 * j) * 4; const f32x4 v = ov[j];
;         ss += (v.x * v.x + v.y * v.y) + (v.z * v.z + v.w * v.w); am = fmaxf(fmaxf(am, fmaxf(fabsf(v.x), fabsf(v.y))), fmaxf(fabsf(v.z), fabsf(v.w)));
;         v2u o; o.x = pk2(v.x, v.y); o.y = pk2(v.z, v.w); st_wt8(orow + c, o); }
;     ss = wave_sum(ss); am = fmaxf(wave_max(am), 1e-20f); const float qs = 127.0f / am;
	s_nop 1
	v_max_f32_e64 v160, |v25|, |v25|
	v_max_f32_e64 v161, |v24|, |v24|
	v_max_f32_e32 v160, v161, v160
	v_max_f32_e64 v161, |v27|, |v27|
	v_max_f32_e64 v162, |v26|, |v26|
	v_max_f32_e32 v161, v162, v161
	v_max3_f32 v168, v168, v160, v161
	v_cvt_pk_bf16_f32 v160, v24, v25
	v_cvt_pk_bf16_f32 v161, v26, v27
	v_lshl_add_u64 v[162:163], v[142:143], 1, s[4:5]
	global_store_dwordx2 v[162:163], v[160:161], off offset:0 sc1 nt
	s_nop 1
	v_max_f32_e64 v160, |v21|, |v21|
	v_max_f32_e64 v161, |v20|, |v20|
	v_max_f32_e32 v160, v161, v160
	v_max_f32_e64 v161, |v23|, |v23|
	v_max_f32_e64 v162, |v22|, |v22|
	v_max_f32_e64 v169, |v17|, |v17|
	v_max_f32_e64 v170, |v16|, |v16|
	v_max_f32_e32 v161, v162, v161
	v_max_f32_e32 v169, v170, v169
	v_max_f32_e64 v170, |v19|, |v19|
	v_max_f32_e64 v171, |v18|, |v18|
	v_max3_f32 v168, v168, v160, v161
	v_max_f32_e32 v170, v171, v170
	v_max3_f32 v168, v168, v169, v170
	v_max_f32_e64 v169, |v13|, |v13|
	v_max_f32_e64 v170, |v12|, |v12|
	v_max_f32_e32 v169, v170, v169
	v_max_f32_e64 v170, |v15|, |v15|
	v_max_f32_e64 v171, |v14|, |v14|
	v_max_f32_e32 v170, v171, v170
	v_max3_f32 v168, v168, v169, v170
	v_max_f32_e64 v169, |v9|, |v9|
	v_max_f32_e64 v170, |v8|, |v8|
	v_max_f32_e32 v169, v170, v169
	v_max_f32_e64 v170, |v11|, |v11|
	v_max_f32_e64 v171, |v10|, |v10|
	v_max_f32_e32 v170, v171, v170
	v_max3_f32 v168, v168, v169, v170
	v_max_f32_e64 v169, |v5|, |v5|
	v_max_f32_e64 v170, |v4|, |v4|
	v_max_f32_e32 v169, v170, v169
	v_max_f32_e64 v170, |v7|, |v7|
	v_max_f32_e64 v171, |v6|, |v6|
	v_max_f32_e32 v170, v171, v170
	v_max3_f32 v168, v168, v169, v170
	v_max_f32_e64 v169, |v1|, |v1|
	v_max_f32_e64 v170, |v0|, |v0|
	v_max_f32_e32 v169, v170, v169
	v_max_f32_e64 v170, |v3|, |v3|
	v_max_f32_e64 v171, |v2|, |v2|
	v_max_f32_e32 v170, v171, v170
	v_max3_f32 v168, v168, v169, v170
	ds_swizzle_b32 v169, v168 offset:swizzle(SWAP,1)
	v_cvt_pk_bf16_f32 v160, v20, v21
	v_cvt_pk_bf16_f32 v161, v22, v23
	v_lshl_add_u64 v[162:163], v[144:145], 1, s[4:5]
	global_store_dwordx2 v[162:163], v[160:161], off offset:0 sc1 nt
	s_nop 1
	s_waitcnt lgkmcnt(0)
	v_max_f32_e32 v169, v169, v169
	v_max_f32_e32 v168, v168, v169
	ds_swizzle_b32 v169, v168 offset:swizzle(SWAP,2)
	v_cvt_pk_bf16_f32 v160, v16, v17
	v_cvt_pk_bf16_f32 v161, v18, v19
	v_lshl_add_u64 v[162:163], v[146:147], 1, s[4:5]
	global_store_dwordx2 v[162:163], v[160:161], off offset:0 sc1 nt
	s_nop 1
	s_waitcnt lgkmcnt(0)
	v_max_f32_e32 v169, v169, v169
	v_max_f32_e32 v168, v168, v169
	ds_swizzle_b32 v169, v168 offset:swizzle(SWAP,4)
	v_cvt_pk_bf16_f32 v160, v12, v13
	v_cvt_pk_bf16_f32 v161, v14, v15
	v_lshl_add_u64 v[162:163], v[148:149], 1, s[4:5]
	global_store_dwordx2 v[162:163], v[160:161], off offset:0 sc1 nt
	s_nop 1
	s_waitcnt lgkmcnt(0)
	v_max_f32_e32 v169, v169, v169
	v_max_f32_e32 v168, v168, v169
	ds_swizzle_b32 v169, v168 offset:swizzle(SWAP,8)
	v_cvt_pk_bf16_f32 v160, v8, v9
	v_cvt_pk_bf16_f32 v161, v10, v11
	v_lshl_add_u64 v[162:163], v[150:151], 1, s[4:5]
	global_store_dwordx2 v[162:163], v[160:161], off offset:0 sc1 nt
	s_nop 1
	s_waitcnt lgkmcnt(0)
	v_max_f32_e32 v169, v169, v169
	v_max_f32_e32 v170, v168, v169
	ds_swizzle_b32 v171, v170 offset:swizzle(SWAP,16)
	v_cvt_pk_bf16_f32 v160, v4, v5
	v_cvt_pk_bf16_f32 v161, v6, v7
	v_lshl_add_u64 v[162:163], v[152:153], 1, s[4:5]
	global_store_dwordx2 v[162:163], v[160:161], off offset:0 sc1 nt
	s_nop 1
	s_waitcnt lgkmcnt(0)
	v_max_f32_e32 v160, v171, v171
	v_max_f32_e32 v160, v170, v160
	v_mov_b32_e32 v161, v160
	s_nop 1
	v_permlane32_swap_b32_e32 v160, v161
	v_max3_f32 v160, v160, v161, s58
	v_mul_f32_e32 v161, v105, v105
	v_mul_f32_e32 v170, v107, v107
	v_fmac_f32_e32 v161, v104, v104
	v_fmac_f32_e32 v170, v106, v106
	v_add_f32_e32 v161, v161, v170
	v_mul_f32_e32 v170, v93, v93
	v_mul_f32_e32 v171, v95, v95
	v_fmac_f32_e32 v170, v92, v92
	v_fmac_f32_e32 v171, v94, v94
	v_add_f32_e32 v170, v170, v171
	v_add_f32_e32 v161, v161, v170
	v_mul_f32_e32 v170, v85, v85
	v_mul_f32_e32 v171, v87, v87
	v_fmac_f32_e32 v170, v84, v84
	v_fmac_f32_e32 v171, v86, v86
	v_add_f32_e32 v170, v170, v171
	v_add_f32_e32 v161, v161, v170
	v_mul_f32_e32 v170, v77, v77
	v_mul_f32_e32 v171, v79, v79
	v_fmac_f32_e32 v170, v76, v76
	v_fmac_f32_e32 v171, v78, v78
	v_add_f32_e32 v170, v170, v171
	v_add_f32_e32 v161, v161, v170
	v_mul_f32_e32 v170, v69, v69
	v_mul_f32_e32 v171, v71, v71
	v_fmac_f32_e32 v170, v68, v68
	v_fmac_f32_e32 v171, v70, v70
	v_add_f32_e32 v170, v170, v171
	v_add_f32_e32 v161, v161, v170
	v_mul_f32_e32 v170, v57, v57
	v_mul_f32_e32 v171, v59, v59
	v_fmac_f32_e32 v170, v56, v56
	v_fmac_f32_e32 v171, v58, v58
	v_add_f32_e32 v170, v170, v171
	v_add_f32_e32 v161, v161, v170
	v_mul_f32_e32 v170, v49, v49
	v_mul_f32_e32 v171, v51, v51
	v_fmac_f32_e32 v170, v48, v48
	v_fmac_f32_e32 v171, v50, v50
	v_add_f32_e32 v170, v170, v171
	v_add_f32_e32 v161, v161, v170
	v_mul_f32_e32 v170, v41, v41
	v_mul_f32_e32 v171, v43, v43
	v_fmac_f32_e32 v170, v40, v40
	v_fmac_f32_e32 v171, v42, v42
	v_add_f32_e32 v170, v170, v171
	v_add_f32_e32 v161, v161, v170
	v_mul_f32_e32 v170, v33, v33
	v_mul_f32_e32 v171, v35, v35
	v_fmac_f32_e32 v170, v32, v32
	v_fmac_f32_e32 v171, v34, v34
	v_add_f32_e32 v170, v170, v171
	v_add_f32_e32 v161, v161, v170
	v_mul_f32_e32 v170, v25, v25
	v_mul_f32_e32 v171, v27, v27
	v_fmac_f32_e32 v170, v24, v24
	v_fmac_f32_e32 v171, v26, v26
	v_add_f32_e32 v170, v170, v171
	v_add_f32_e32 v161, v161, v170
	v_mul_f32_e32 v170, v21, v21
	v_mul_f32_e32 v171, v23, v23
	v_fmac_f32_e32 v170, v20, v20
	v_fmac_f32_e32 v171, v22, v22
	v_add_f32_e32 v170, v170, v171
	v_add_f32_e32 v161, v161, v170
	v_mul_f32_e32 v170, v17, v17
	v_mul_f32_e32 v171, v19, v19
	v_fmac_f32_e32 v170, v16, v16
	v_fmac_f32_e32 v171, v18, v18
	v_add_f32_e32 v170, v170, v171
	v_add_f32_e32 v161, v161, v170
	v_mul_f32_e32 v170, v13, v13
	v_mul_f32_e32 v171, v15, v15
	v_fmac_f32_e32 v170, v12, v12
	v_fmac_f32_e32 v171, v14, v14
	v_add_f32_e32 v170, v170, v171
	v_add_f32_e32 v161, v161, v170
	v_mul_f32_e32 v170, v9, v9
	v_mul_f32_e32 v171, v11, v11
	v_fmac_f32_e32 v170, v8, v8
	v_fmac_f32_e32 v171, v10, v10
	v_add_f32_e32 v170, v170, v171
	v_add_f32_e32 v161, v161, v170
	v_mul_f32_e32 v170, v5, v5
	v_mul_f32_e32 v171, v7, v7
	v_fmac_f32_e32 v170, v4, v4
	v_fmac_f32_e32 v171, v6, v6
	v_add_f32_e32 v170, v170, v171
	v_add_f32_e32 v161, v161, v170
	v_mul_f32_e32 v170, v1, v1
	v_mul_f32_e32 v171, v3, v3
	v_fmac_f32_e32 v170, v0, v0
	v_fmac_f32_e32 v171, v2, v2
	v_add_f32_e32 v170, v170, v171
	v_add_f32_e32 v161, v161, v170
	ds_swizzle_b32 v170, v161 offset:swizzle(SWAP,1)
	v_cvt_pk_bf16_f32 v162, v0, v1
	v_cvt_pk_bf16_f32 v163, v2, v3
	v_lshl_add_u64 v[168:169], v[154:155], 1, s[4:5]
	global_store_dwordx2 v[168:169], v[162:163], off offset:0 sc1 nt
	s_nop 1
	s_waitcnt lgkmcnt(0)
; template <int O> __device__ __forceinline__ float xsw(float v) { return __int_as_float(__builtin_amdgcn_ds_swizzle(__float_as_int(v), (O << 10) | 0x1f)); }
; __device__ __forceinline__ float xsum32(float v) { auto rr = __builtin_amdgcn_permlane32_swap(__float_as_uint(v), __float_as_uint(v), false, false); return __uint_as_float(rr[0]) + __uint_as_float(rr[1]); }
; __device__ __forceinline__ void st_wt4(void* p, unsigned v) { asm volatile("global_store_dword %0, %1, off sc1\n\ts_nop 1" :: "v"(p), "v"(v)); }
; __device__ __forceinline__ float wave_sum(float v) {
;     v += xsw<1>(v); v += xsw<2>(v); v += xsw<4>(v); v += xsw<8>(v); v += xsw<16>(v);
;     return xsum32(v);
; __device__ __forceinline__ void row_to_bf16(const f32x4 (&ov)[16], bf16* __restrict__ orow, float* rs_out, unsigned* __restrict__ xq, float* as_out, int lane) {
;     ...
;     ss = wave_sum(ss); am = fmaxf(wave_max(am), 1e-20f); const float qs = 127.0f / am;
; #pragma unroll
;     for (int j = 0; j < 16; ++j) { const int q0 = (int)rintf(ov[j].x * qs), q1 = (int)rintf(ov[j].y * qs), q2 = (int)rintf(ov[j].z * qs), q3 = (int)rintf(ov[j].w * qs);
;         st_wt4(xq + lane + 64 * j, ((unsigned)q0 & 255u) | (((unsigned)q1 & 255u) << 8) | (((unsigned)q2 & 255u) << 16) | ((unsigned)q3 << 24)); }
	v_add_f32_e32 v161, v161, v170
	ds_swizzle_b32 v162, v161 offset:swizzle(SWAP,2)
	v_div_scale_f32 v171, s[4:5], v160, v160, s59
	v_rcp_f32_e32 v172, v171
	s_lshl_b64 s[4:5], s[52:53], 12
	s_waitcnt lgkmcnt(0)
	v_add_f32_e32 v161, v161, v162
	ds_swizzle_b32 v162, v161 offset:swizzle(SWAP,4)
	v_fma_f32 v163, -v171, v172, 1.0
	v_fmac_f32_e32 v172, v163, v172
	v_div_scale_f32 v163, vcc, s59, v160, s59
	s_waitcnt lgkmcnt(0)
	v_add_f32_e32 v161, v161, v162
	ds_swizzle_b32 v162, v161 offset:swizzle(SWAP,8)
	v_mul_f32_e32 v168, v163, v172
	v_fma_f32 v169, -v171, v168, v163
	v_fmac_f32_e32 v168, v169, v172
	v_fma_f32 v163, -v171, v168, v163
	s_waitcnt lgkmcnt(0)
	v_add_f32_e32 v161, v161, v162
	ds_swizzle_b32 v162, v161 offset:swizzle(SWAP,16)
	v_div_fmas_f32 v163, v163, v172, v168
	v_div_fixup_f32 v163, v163, v160, s59
	v_mul_f32_e32 v105, v105, v163
	v_mul_f32_e32 v104, v104, v163
	v_mul_f32_e32 v168, v106, v163
	v_mul_f32_e32 v169, v107, v163
	v_rndne_f32_e32 v105, v105
	s_waitcnt lgkmcnt(0)
	v_add_f32_e32 v106, v161, v162
	v_rndne_f32_e32 v104, v104
	v_rndne_f32_e32 v161, v169
	v_cvt_i32_f32_e32 v162, v105
	v_rndne_f32_e32 v105, v168
	v_cvt_i32_f32_e32 v104, v104
	v_cvt_i32_f32_e32 v161, v161
	v_cvt_i32_f32_sdwa v168, v105 dst_sel:WORD_1 dst_unused:UNUSED_PAD src0_sel:DWORD
	v_lshlrev_b32_e32 v162, 8, v162
	v_and_b32_e32 v162, 0xff00, v162
	v_perm_b32 v161, v161, v104, s60
	v_and_b32_e32 v168, 0xff0000, v168
	v_mul_f32_e32 v92, v92, v163
	v_or3_b32 v161, v161, v162, v168
	v_rndne_f32_e32 v92, v92
	v_lshl_add_u64 v[104:105], v[156:157], 0, s[4:5]
	global_store_dword v[104:105], v161, off sc1
	s_nop 1
	v_cvt_i32_f32_e32 v161, v92
	v_mul_f32_e32 v92, v93, v163
	v_rndne_f32_e32 v92, v92
	v_cvt_i32_f32_e32 v162, v92
	v_mul_f32_e32 v92, v94, v163
	v_rndne_f32_e32 v92, v92
	v_cvt_i32_f32_sdwa v94, v92 dst_sel:WORD_1 dst_unused:UNUSED_PAD src0_sel:DWORD
	v_mul_f32_e32 v92, v95, v163
	v_rndne_f32_e32 v92, v92
	v_cvt_i32_f32_e32 v95, v92
	v_lshlrev_b32_e32 v162, 8, v162
	v_mul_f32_e32 v84, v84, v163
	v_lshl_add_u64 v[92:93], v[104:105], 0, s[36:37]
	v_and_b32_e32 v162, 0xff00, v162
	v_and_b32_e32 v94, 0xff0000, v94
	v_perm_b32 v95, v95, v161, s60
	v_rndne_f32_e32 v84, v84
	v_or3_b32 v94, v95, v162, v94
	global_store_dword v[92:93], v94, off sc1
	s_nop 1
	v_cvt_i32_f32_e32 v92, v84
	v_mul_f32_e32 v84, v85, v163
	v_rndne_f32_e32 v84, v84
	v_cvt_i32_f32_e32 v93, v84
	v_mul_f32_e32 v84, v86, v163
	v_rndne_f32_e32 v84, v84
	v_cvt_i32_f32_sdwa v86, v84 dst_sel:WORD_1 dst_unused:UNUSED_PAD src0_sel:DWORD
	v_mul_f32_e32 v84, v87, v163
	v_rndne_f32_e32 v84, v84
	v_cvt_i32_f32_e32 v87, v84
	v_lshlrev_b32_e32 v93, 8, v93
	v_mul_f32_e32 v76, v76, v163
	v_lshl_add_u64 v[84:85], v[104:105], 0, s[20:21]
	v_and_b32_e32 v93, 0xff00, v93
	v_and_b32_e32 v86, 0xff0000, v86
	v_perm_b32 v87, v87, v92, s60
	v_rndne_f32_e32 v76, v76
	v_or3_b32 v86, v87, v93, v86
	global_store_dword v[84:85], v86, off sc1
	s_nop 1
	v_cvt_i32_f32_e32 v84, v76
	v_mul_f32_e32 v76, v77, v163
	v_rndne_f32_e32 v76, v76
	v_cvt_i32_f32_e32 v85, v76
	v_mul_f32_e32 v76, v78, v163
	v_rndne_f32_e32 v76, v76
	v_cvt_i32_f32_sdwa v78, v76 dst_sel:WORD_1 dst_unused:UNUSED_PAD src0_sel:DWORD
	v_mul_f32_e32 v76, v79, v163
	v_rndne_f32_e32 v76, v76
	v_cvt_i32_f32_e32 v79, v76
	v_lshlrev_b32_e32 v85, 8, v85
	v_mul_f32_e32 v68, v68, v163
	v_lshl_add_u64 v[76:77], v[104:105], 0, s[38:39]
	v_and_b32_e32 v85, 0xff00, v85
	v_and_b32_e32 v78, 0xff0000, v78
	v_perm_b32 v79, v79, v84, s60
	v_rndne_f32_e32 v68, v68
	v_or3_b32 v78, v79, v85, v78
	global_store_dword v[76:77], v78, off sc1
	s_nop 1
	v_cvt_i32_f32_e32 v76, v68
	v_mul_f32_e32 v68, v69, v163
	v_rndne_f32_e32 v68, v68
	v_cvt_i32_f32_e32 v77, v68
	v_mul_f32_e32 v68, v70, v163
	v_rndne_f32_e32 v68, v68
	v_cvt_i32_f32_sdwa v70, v68 dst_sel:WORD_1 dst_unused:UNUSED_PAD src0_sel:DWORD
	v_mul_f32_e32 v68, v71, v163
	v_rndne_f32_e32 v68, v68
	v_cvt_i32_f32_e32 v71, v68
	v_lshlrev_b32_e32 v77, 8, v77
	v_mul_f32_e32 v56, v56, v163
	v_lshl_add_u64 v[68:69], v[104:105], 0, s[22:23]
	v_and_b32_e32 v77, 0xff00, v77
	v_and_b32_e32 v70, 0xff0000, v70
	v_perm_b32 v71, v71, v76, s60
	v_rndne_f32_e32 v56, v56
	v_or3_b32 v70, v71, v77, v70
	global_store_dword v[68:69], v70, off sc1
	s_nop 1
	v_cvt_i32_f32_e32 v68, v56
	v_mul_f32_e32 v56, v57, v163
	v_rndne_f32_e32 v56, v56
	v_cvt_i32_f32_e32 v69, v56
	v_mul_f32_e32 v56, v58, v163
	v_rndne_f32_e32 v56, v56
	v_cvt_i32_f32_sdwa v58, v56 dst_sel:WORD_1 dst_unused:UNUSED_PAD src0_sel:DWORD
	v_mul_f32_e32 v56, v59, v163
	v_rndne_f32_e32 v56, v56
	v_cvt_i32_f32_e32 v59, v56
	v_lshlrev_b32_e32 v69, 8, v69
	v_mul_f32_e32 v48, v48, v163
	v_lshl_add_u64 v[56:57], v[104:105], 0, s[40:41]
	v_and_b32_e32 v69, 0xff00, v69
	v_and_b32_e32 v58, 0xff0000, v58
	v_perm_b32 v59, v59, v68, s60
	v_rndne_f32_e32 v48, v48
	v_or3_b32 v58, v59, v69, v58
	global_store_dword v[56:57], v58, off sc1
	s_nop 1
	v_cvt_i32_f32_e32 v56, v48
	v_mul_f32_e32 v48, v49, v163
	v_rndne_f32_e32 v48, v48
	v_cvt_i32_f32_e32 v57, v48
	v_mul_f32_e32 v48, v50, v163
	v_rndne_f32_e32 v48, v48
	v_cvt_i32_f32_sdwa v50, v48 dst_sel:WORD_1 dst_unused:UNUSED_PAD src0_sel:DWORD
	v_mul_f32_e32 v48, v51, v163
	v_rndne_f32_e32 v48, v48
	v_cvt_i32_f32_e32 v51, v48
	v_lshlrev_b32_e32 v57, 8, v57
	v_mul_f32_e32 v40, v40, v163
	v_lshl_add_u64 v[48:49], v[104:105], 0, s[24:25]
	v_and_b32_e32 v57, 0xff00, v57
	v_and_b32_e32 v50, 0xff0000, v50
	v_perm_b32 v51, v51, v56, s60
	v_rndne_f32_e32 v40, v40
	v_or3_b32 v50, v51, v57, v50
	global_store_dword v[48:49], v50, off sc1
	s_nop 1
	v_cvt_i32_f32_e32 v48, v40
	v_mul_f32_e32 v40, v41, v163
	v_rndne_f32_e32 v40, v40
	v_cvt_i32_f32_e32 v49, v40
; __device__ __forceinline__ void st_wt4(void* p, unsigned v) { asm volatile("global_store_dword %0, %1, off sc1\n\ts_nop 1" :: "v"(p), "v"(v)); }
; __device__ __forceinline__ void row_to_bf16(const f32x4 (&ov)[16], bf16* __restrict__ orow, float* rs_out, unsigned* __restrict__ xq, float* as_out, int lane) {
;     ...
; #pragma unroll
;     for (int j = 0; j < 16; ++j) { const int q0 = (int)rintf(ov[j].x * qs), q1 = (int)rintf(ov[j].y * qs), q2 = (int)rintf(ov[j].z * qs), q3 = (int)rintf(ov[j].w * qs);
;         st_wt4(xq + lane + 64 * j, ((unsigned)q0 & 255u) | (((unsigned)q1 & 255u) << 8) | (((unsigned)q2 & 255u) << 16) | ((unsigned)q3 << 24)); }
;     if (lane == 0) { *rs_out = 1.0f / sqrtf(ss * (1.0f / DM) + EPS); *as_out = am * (1.0f / 127.0f); }
	v_mul_f32_e32 v40, v42, v163
	v_rndne_f32_e32 v40, v40
	v_cvt_i32_f32_sdwa v42, v40 dst_sel:WORD_1 dst_unused:UNUSED_PAD src0_sel:DWORD
	v_mul_f32_e32 v40, v43, v163
	v_rndne_f32_e32 v40, v40
	v_cvt_i32_f32_e32 v43, v40
	v_lshlrev_b32_e32 v49, 8, v49
	v_mul_f32_e32 v32, v32, v163
	v_lshl_add_u64 v[40:41], v[104:105], 0, s[42:43]
	v_and_b32_e32 v49, 0xff00, v49
	v_and_b32_e32 v42, 0xff0000, v42
	v_perm_b32 v43, v43, v48, s60
	v_rndne_f32_e32 v32, v32
	v_or3_b32 v42, v43, v49, v42
	global_store_dword v[40:41], v42, off sc1
	s_nop 1
	v_cvt_i32_f32_e32 v40, v32
	v_mul_f32_e32 v32, v33, v163
	v_rndne_f32_e32 v32, v32
	v_cvt_i32_f32_e32 v41, v32
	v_mul_f32_e32 v32, v34, v163
	v_rndne_f32_e32 v32, v32
	v_cvt_i32_f32_sdwa v34, v32 dst_sel:WORD_1 dst_unused:UNUSED_PAD src0_sel:DWORD
	v_mul_f32_e32 v32, v35, v163
	v_rndne_f32_e32 v32, v32
	v_cvt_i32_f32_e32 v35, v32
	v_lshlrev_b32_e32 v41, 8, v41
	v_mul_f32_e32 v24, v24, v163
	v_lshl_add_u64 v[32:33], v[104:105], 0, s[26:27]
	v_and_b32_e32 v41, 0xff00, v41
	v_and_b32_e32 v34, 0xff0000, v34
	v_perm_b32 v35, v35, v40, s60
	v_rndne_f32_e32 v24, v24
	v_or3_b32 v34, v35, v41, v34
	global_store_dword v[32:33], v34, off sc1
	s_nop 1
	v_cvt_i32_f32_e32 v32, v24
	v_mul_f32_e32 v24, v25, v163
	v_rndne_f32_e32 v24, v24
	v_cvt_i32_f32_e32 v33, v24
	v_mul_f32_e32 v24, v26, v163
	v_rndne_f32_e32 v24, v24
	v_cvt_i32_f32_sdwa v26, v24 dst_sel:WORD_1 dst_unused:UNUSED_PAD src0_sel:DWORD
	v_mul_f32_e32 v24, v27, v163
	v_rndne_f32_e32 v24, v24
	v_cvt_i32_f32_e32 v27, v24
	v_lshlrev_b32_e32 v33, 8, v33
	v_mul_f32_e32 v20, v20, v163
	v_lshl_add_u64 v[24:25], v[104:105], 0, s[44:45]
	v_and_b32_e32 v33, 0xff00, v33
	v_and_b32_e32 v26, 0xff0000, v26
	v_perm_b32 v27, v27, v32, s60
	v_rndne_f32_e32 v20, v20
	v_or3_b32 v26, v27, v33, v26
	global_store_dword v[24:25], v26, off sc1
	s_nop 1
	v_cvt_i32_f32_e32 v24, v20
	v_mul_f32_e32 v20, v21, v163
	v_rndne_f32_e32 v20, v20
	v_cvt_i32_f32_e32 v25, v20
	v_mul_f32_e32 v20, v22, v163
	v_rndne_f32_e32 v20, v20
	v_cvt_i32_f32_sdwa v22, v20 dst_sel:WORD_1 dst_unused:UNUSED_PAD src0_sel:DWORD
	v_mul_f32_e32 v20, v23, v163
	v_rndne_f32_e32 v20, v20
	v_cvt_i32_f32_e32 v23, v20
	v_lshlrev_b32_e32 v25, 8, v25
	v_mul_f32_e32 v16, v16, v163
	v_lshl_add_u64 v[20:21], v[104:105], 0, s[28:29]
	v_and_b32_e32 v25, 0xff00, v25
	v_and_b32_e32 v22, 0xff0000, v22
	v_perm_b32 v23, v23, v24, s60
	v_rndne_f32_e32 v16, v16
	v_or3_b32 v22, v23, v25, v22
	global_store_dword v[20:21], v22, off sc1
	s_nop 1
	v_cvt_i32_f32_e32 v20, v16
	v_mul_f32_e32 v16, v17, v163
	v_rndne_f32_e32 v16, v16
	v_cvt_i32_f32_e32 v21, v16
	v_mul_f32_e32 v16, v18, v163
	v_rndne_f32_e32 v16, v16
	v_cvt_i32_f32_sdwa v18, v16 dst_sel:WORD_1 dst_unused:UNUSED_PAD src0_sel:DWORD
	v_mul_f32_e32 v16, v19, v163
	v_rndne_f32_e32 v16, v16
	v_cvt_i32_f32_e32 v19, v16
	v_lshlrev_b32_e32 v21, 8, v21
	v_mul_f32_e32 v12, v12, v163
	v_lshl_add_u64 v[16:17], v[104:105], 0, s[46:47]
	v_and_b32_e32 v21, 0xff00, v21
	v_and_b32_e32 v18, 0xff0000, v18
	v_perm_b32 v19, v19, v20, s60
	v_rndne_f32_e32 v12, v12
	v_or3_b32 v18, v19, v21, v18
	global_store_dword v[16:17], v18, off sc1
	s_nop 1
	v_cvt_i32_f32_e32 v16, v12
	v_mul_f32_e32 v12, v13, v163
	v_rndne_f32_e32 v12, v12
	v_cvt_i32_f32_e32 v17, v12
	v_mul_f32_e32 v12, v14, v163
	v_rndne_f32_e32 v12, v12
	v_cvt_i32_f32_sdwa v14, v12 dst_sel:WORD_1 dst_unused:UNUSED_PAD src0_sel:DWORD
	v_mul_f32_e32 v12, v15, v163
	v_rndne_f32_e32 v12, v12
	v_cvt_i32_f32_e32 v15, v12
	v_lshlrev_b32_e32 v17, 8, v17
	v_mul_f32_e32 v8, v8, v163
	v_lshl_add_u64 v[12:13], v[104:105], 0, s[30:31]
	v_and_b32_e32 v17, 0xff00, v17
	v_and_b32_e32 v14, 0xff0000, v14
	v_perm_b32 v15, v15, v16, s60
	v_rndne_f32_e32 v8, v8
	v_or3_b32 v14, v15, v17, v14
	global_store_dword v[12:13], v14, off sc1
	s_nop 1
	v_cvt_i32_f32_e32 v12, v8
	v_mul_f32_e32 v8, v9, v163
	v_rndne_f32_e32 v8, v8
	v_cvt_i32_f32_e32 v13, v8
	v_mul_f32_e32 v8, v10, v163
	v_rndne_f32_e32 v8, v8
	v_cvt_i32_f32_sdwa v10, v8 dst_sel:WORD_1 dst_unused:UNUSED_PAD src0_sel:DWORD
	v_mul_f32_e32 v8, v11, v163
	v_rndne_f32_e32 v8, v8
	v_cvt_i32_f32_e32 v11, v8
	v_lshlrev_b32_e32 v13, 8, v13
	v_mul_f32_e32 v4, v4, v163
	v_lshl_add_u64 v[8:9], v[104:105], 0, s[48:49]
	v_and_b32_e32 v13, 0xff00, v13
	v_and_b32_e32 v10, 0xff0000, v10
	v_perm_b32 v11, v11, v12, s60
	v_rndne_f32_e32 v4, v4
	v_or3_b32 v10, v11, v13, v10
	global_store_dword v[8:9], v10, off sc1
	s_nop 1
	v_cvt_i32_f32_e32 v8, v4
	v_mul_f32_e32 v4, v5, v163
	v_rndne_f32_e32 v4, v4
	v_cvt_i32_f32_e32 v9, v4
	v_mul_f32_e32 v4, v6, v163
	v_rndne_f32_e32 v4, v4
	v_cvt_i32_f32_sdwa v6, v4 dst_sel:WORD_1 dst_unused:UNUSED_PAD src0_sel:DWORD
	v_mul_f32_e32 v4, v7, v163
	v_rndne_f32_e32 v4, v4
	v_cvt_i32_f32_e32 v7, v4
	v_lshlrev_b32_e32 v9, 8, v9
	v_mul_f32_e32 v0, v0, v163
	v_lshl_add_u64 v[4:5], v[104:105], 0, s[34:35]
	v_and_b32_e32 v9, 0xff00, v9
	v_and_b32_e32 v6, 0xff0000, v6
	v_perm_b32 v7, v7, v8, s60
	v_rndne_f32_e32 v0, v0
	v_or3_b32 v6, v7, v9, v6
	global_store_dword v[4:5], v6, off sc1
	s_nop 1
	v_cvt_i32_f32_e32 v4, v0
	v_mul_f32_e32 v0, v1, v163
	v_rndne_f32_e32 v0, v0
	v_cvt_i32_f32_e32 v5, v0
	v_mul_f32_e32 v0, v2, v163
	v_rndne_f32_e32 v0, v0
	v_cvt_i32_f32_sdwa v2, v0 dst_sel:WORD_1 dst_unused:UNUSED_PAD src0_sel:DWORD
	v_mul_f32_e32 v0, v3, v163
	v_rndne_f32_e32 v0, v0
	v_cvt_i32_f32_e32 v3, v0
	v_mov_b32_e32 v107, v106
	v_lshlrev_b32_e32 v5, 8, v5
	s_nop 0
	v_permlane32_swap_b32_e32 v106, v107
	v_and_b32_e32 v5, 0xff00, v5
	v_and_b32_e32 v2, 0xff0000, v2
	v_perm_b32 v3, v3, v4, s60
	v_lshl_add_u64 v[0:1], v[104:105], 0, s[50:51]
	v_or3_b32 v2, v3, v5, v2
	global_store_dword v[0:1], v2, off sc1
	s_nop 1
	s_and_saveexec_b64 s[54:55], s[2:3]
	s_cbranch_execz .LBB0_64
	v_add_f32_e32 v0, v106, v107
	v_fmamk_f32 v0, v0, 0x39800000, v166
	v_mul_f32_e32 v1, 0x4f800000, v0
	v_cmp_gt_f32_e32 vcc, s61, v0
	s_lshl_b64 s[62:63], s[52:53], 2
	s_add_u32 s64, s18, s62
	v_cndmask_b32_e32 v0, v0, v1, vcc
	v_sqrt_f32_e32 v1, v0
	s_addc_u32 s65, s19, s63
	v_add_u32_e32 v2, -1, v1
	v_fma_f32 v3, -v2, v1, v0
	v_cmp_ge_f32_e64 s[4:5], 0, v3
	v_add_u32_e32 v3, 1, v1
	s_nop 0
	v_cndmask_b32_e64 v2, v1, v2, s[4:5]
	v_fma_f32 v1, -v3, v1, v0
	v_cmp_lt_f32_e64 s[4:5], 0, v1
	s_nop 1
	v_cndmask_b32_e64 v1, v2, v3, s[4:5]
	v_mul_f32_e32 v2, 0x37800000, v1
	v_cndmask_b32_e32 v1, v1, v2, vcc
	v_cmp_class_f32_e32 vcc, v0, v167
	s_nop 1
	v_cndmask_b32_e32 v0, v1, v0, vcc
	v_div_scale_f32 v1, s[4:5], v0, v0, 1.0
	v_rcp_f32_e32 v2, v1
	s_add_u32 s4, s14, s62
	s_addc_u32 s5, s15, s63
	v_fma_f32 v3, -v1, v2, 1.0
	v_fmac_f32_e32 v2, v3, v2
	v_div_scale_f32 v3, vcc, 1.0, v0, 1.0
	v_mul_f32_e32 v4, v3, v2
	v_fma_f32 v5, -v1, v4, v3
	v_fmac_f32_e32 v4, v5, v2
	v_fma_f32 v1, -v1, v4, v3
	v_div_fmas_f32 v1, v1, v2, v4
	v_div_fixup_f32 v0, v1, v0, 1.0
	global_store_dword v129, v0, s[4:5]
	v_mul_f32_e32 v0, 0x3c010204, v160
	global_store_dword v129, v0, s[64:65]
; template <int OFF = 0, class V> __device__ __forceinline__ void st_wt8(void* p, V v) { static_assert(sizeof(V) == 8, ""); asm volatile("global_store_dwordx2 %0, %1, off offset:%2 sc1\n\ts_nop 1" :: "v"(p), "v"(v), "i"(OFF)); }
; __device__ __forceinline__ unsigned pk2(float lo, float hi) { return pg8::cvt_pk_bf16(lo, hi); }
; #define ROW_OUT(m_, r_) row_to_bf16(r_, XB + (size_t)(m_) * DM, RS + (m_), (unsigned*)(ws + WS_XQ) + (size_t)(m_) * (DM / 4), (float*)(ws + WS_AS) + (m_), lane)
; __device__ __forceinline__ void row_load(const float* __restrict__ xrow, int lane, f32x4 (&ov)[16]) {
; #pragma unroll
;     for (int j = 0; j < 16; ++j) ov[j] = *(const f32x4*)(xrow + (lane + 64 * j) * 4);
; }
; __device__ __forceinline__ void row_to_bf16(const f32x4 (&ov)[16], bf16* __restrict__ orow, float* rs_out, unsigned* __restrict__ xq, float* as_out, int lane) {
;     float ss = 0.f, am = 0.f;
; #pragma unroll
;     for (int j = 0; j < 16; ++j) { const int c = (lane + 64 * j) * 4; const f32x4 v = ov[j];
;         ss += (v.x * v.x + v.y * v.y) + (v.z * v.z + v.w * v.w); am = fmaxf(fmaxf(am, fmaxf(fabsf(v.x), fabsf(v.y))), fmaxf(fabsf(v.z), fabsf(v.w)));
;         v2u o; o.x = pk2(v.x, v.y); o.y = pk2(v.z, v.w); st_wt8(orow + c, o); }
; __global__ void __launch_bounds__(NWAVES * 64, 2) mk_fwd(Args args) {
;     ...
;             for (int k = 0; k < n; k += 2) { const int m1 = min(gw + (k + 1) * NGW, lastm), m2 = min(gw + (k + 2) * NGW, lastm);
;                 row_load(x_in + (size_t)m1 * DM, lane, rB); ROW_OUT(gw + k * NGW, rA);
;                 row_load(x_in + (size_t)m2 * DM, lane, rA); ROW_OUT(m1, rB); }
.LBB0_64:
	s_or_b64 exec, exec, s[54:55]
	s_add_i32 s52, s9, s52
	v_min_i32_e32 v0, s52, v165
	v_ashrrev_i32_e32 v1, 31, v0
	v_lshlrev_b64 v[0:1], 14, v[0:1]
	v_lshl_add_u64 v[0:1], s[12:13], 0, v[0:1]
	v_lshl_add_u64 v[2:3], v[130:131], 2, v[0:1]
	global_load_dwordx4 v[104:107], v[2:3], off nt
	global_load_dwordx4 v[92:95], v[2:3], off offset:1024 nt
	global_load_dwordx4 v[84:87], v[2:3], off offset:2048 nt
	global_load_dwordx4 v[76:79], v[2:3], off offset:3072 nt
	v_lshl_add_u64 v[2:3], v[132:133], 2, v[0:1]
	v_lshl_add_u64 v[4:5], v[134:135], 2, v[0:1]
	global_load_dwordx4 v[68:71], v[2:3], off nt
	global_load_dwordx4 v[56:59], v[4:5], off nt
	v_lshl_add_u64 v[2:3], v[136:137], 2, v[0:1]
	s_waitcnt vmcnt(21)
	v_mul_f32_e32 v168, v125, v125
	v_mul_f32_e32 v169, v127, v127
	v_lshl_add_u64 v[4:5], v[138:139], 2, v[0:1]
	global_load_dwordx4 v[48:51], v[2:3], off nt
	global_load_dwordx4 v[40:43], v[4:5], off nt
	v_lshl_add_u64 v[2:3], v[140:141], 2, v[0:1]
	v_fmac_f32_e32 v168, v124, v124
	v_fmac_f32_e32 v169, v126, v126
	v_lshl_add_u64 v[4:5], v[142:143], 2, v[0:1]
	global_load_dwordx4 v[32:35], v[2:3], off nt
	global_load_dwordx4 v[24:27], v[4:5], off nt
	v_lshl_add_u64 v[2:3], v[144:145], 2, v[0:1]
	v_add_f32_e32 v172, v168, v169
	v_max_f32_e64 v168, |v125|, |v125|
	v_max_f32_e64 v169, |v124|, |v124|
	v_lshlrev_b64 v[160:161], 12, v[158:159]
	v_lshl_add_u64 v[4:5], v[146:147], 2, v[0:1]
	global_load_dwordx4 v[20:23], v[2:3], off nt
	global_load_dwordx4 v[16:19], v[4:5], off nt
	v_lshl_add_u64 v[2:3], v[148:149], 2, v[0:1]
	v_max_f32_e32 v168, v169, v168
	v_max_f32_e64 v169, |v127|, |v127|
	v_max_f32_e64 v170, |v126|, |v126|
	v_lshl_add_u64 v[4:5], v[150:151], 2, v[0:1]
	global_load_dwordx4 v[12:15], v[2:3], off nt
	global_load_dwordx4 v[8:11], v[4:5], off nt
	v_lshl_add_u64 v[2:3], v[152:153], 2, v[0:1]
	v_lshl_add_u64 v[0:1], v[154:155], 2, v[0:1]
	v_lshlrev_b64 v[162:163], 1, v[160:161]
	v_max_f32_e32 v169, v170, v169
	global_load_dwordx4 v[4:7], v[2:3], off nt
	s_nop 0
	global_load_dwordx4 v[0:3], v[0:1], off nt
	v_lshl_add_u64 v[162:163], s[16:17], 0, v[162:163]
	v_max3_f32 v173, v168, 0, v169
	v_cvt_pk_bf16_f32 v168, v124, v125
	v_cvt_pk_bf16_f32 v169, v126, v127
	v_lshl_add_u64 v[170:171], v[130:131], 1, v[162:163]
	global_store_dwordx2 v[170:171], v[168:169], off offset:0 sc1 nt
	s_nop 1
	s_waitcnt vmcnt(30)
	v_mul_f32_e32 v168, v121, v121
	v_mul_f32_e32 v169, v123, v123
	v_fmac_f32_e32 v168, v120, v120
	v_fmac_f32_e32 v169, v122, v122
	v_add_f32_e32 v168, v168, v169
	v_add_f32_e32 v174, v172, v168
	v_max_f32_e64 v168, |v121|, |v121|
	v_max_f32_e64 v169, |v120|, |v120|
	v_max_f32_e32 v168, v169, v168
	v_max_f32_e64 v169, |v123|, |v123|
	v_max_f32_e64 v172, |v122|, |v122|
	v_max_f32_e32 v169, v172, v169
	v_max3_f32 v175, v173, v168, v169
	v_cvt_pk_bf16_f32 v168, v120, v121
	v_cvt_pk_bf16_f32 v169, v122, v123
	v_lshl_add_u64 v[172:173], v[170:171], 0, s[20:21]
	global_store_dwordx2 v[172:173], v[168:169], off offset:0 sc1 nt
	s_nop 1
	s_waitcnt vmcnt(29)
	v_mul_f32_e32 v168, v117, v117
	v_mul_f32_e32 v169, v119, v119
	v_fmac_f32_e32 v168, v116, v116
	v_fmac_f32_e32 v169, v118, v118
	v_add_f32_e32 v168, v168, v169
	v_add_f32_e32 v174, v174, v168
	v_max_f32_e64 v168, |v117|, |v117|
	v_max_f32_e64 v169, |v116|, |v116|
	v_max_f32_e32 v168, v169, v168
	v_max_f32_e64 v169, |v119|, |v119|
	v_max_f32_e64 v172, |v118|, |v118|
	v_max_f32_e32 v169, v172, v169
	v_max3_f32 v175, v175, v168, v169
	v_cvt_pk_bf16_f32 v168, v116, v117
	v_cvt_pk_bf16_f32 v169, v118, v119
	v_lshl_add_u64 v[172:173], v[170:171], 0, s[22:23]
	global_store_dwordx2 v[172:173], v[168:169], off offset:0 sc1 nt
	s_nop 1
	s_waitcnt vmcnt(28)
	v_mul_f32_e32 v168, v113, v113
	v_mul_f32_e32 v169, v115, v115
	v_fmac_f32_e32 v168, v112, v112
	v_fmac_f32_e32 v169, v114, v114
	v_add_f32_e32 v168, v168, v169
	v_add_f32_e32 v174, v174, v168
	v_max_f32_e64 v168, |v113|, |v113|
	v_max_f32_e64 v169, |v112|, |v112|
	v_max_f32_e32 v168, v169, v168
	v_max_f32_e64 v169, |v115|, |v115|
	v_max_f32_e64 v172, |v114|, |v114|
	v_max_f32_e32 v169, v172, v169
	v_max3_f32 v175, v175, v168, v169
	v_cvt_pk_bf16_f32 v168, v112, v113
	v_cvt_pk_bf16_f32 v169, v114, v115
	v_lshl_add_u64 v[172:173], v[170:171], 0, s[24:25]
	global_store_dwordx2 v[172:173], v[168:169], off offset:0 sc1 nt
	s_nop 1
	s_waitcnt vmcnt(27)
	v_mul_f32_e32 v168, v109, v109
	v_mul_f32_e32 v169, v111, v111
	v_fmac_f32_e32 v168, v108, v108
	v_fmac_f32_e32 v169, v110, v110
	v_add_f32_e32 v168, v168, v169
	v_add_f32_e32 v174, v174, v168
	v_max_f32_e64 v168, |v109|, |v109|
	v_max_f32_e64 v169, |v108|, |v108|
	v_max_f32_e32 v168, v169, v168
	v_max_f32_e64 v169, |v111|, |v111|
	v_max_f32_e64 v172, |v110|, |v110|
	v_max_f32_e32 v169, v172, v169
	v_max3_f32 v175, v175, v168, v169
	v_cvt_pk_bf16_f32 v168, v108, v109
	v_cvt_pk_bf16_f32 v169, v110, v111
	v_lshl_add_u64 v[172:173], v[170:171], 0, s[26:27]
	global_store_dwordx2 v[172:173], v[168:169], off offset:0 sc1 nt
	s_nop 1
	s_waitcnt vmcnt(26)
	v_mul_f32_e32 v168, v101, v101
	v_mul_f32_e32 v169, v103, v103
	v_fmac_f32_e32 v168, v100, v100
	v_fmac_f32_e32 v169, v102, v102
	v_add_f32_e32 v168, v168, v169
	v_add_f32_e32 v174, v174, v168
	v_max_f32_e64 v168, |v101|, |v101|
	v_max_f32_e64 v169, |v100|, |v100|
	v_max_f32_e32 v168, v169, v168
	v_max_f32_e64 v169, |v103|, |v103|
	v_max_f32_e64 v172, |v102|, |v102|
	v_max_f32_e32 v169, v172, v169
	v_max3_f32 v175, v175, v168, v169
	v_cvt_pk_bf16_f32 v168, v100, v101
	v_cvt_pk_bf16_f32 v169, v102, v103
	v_lshl_add_u64 v[172:173], v[170:171], 0, s[28:29]
	global_store_dwordx2 v[172:173], v[168:169], off offset:0 sc1 nt
	s_nop 1
	s_waitcnt vmcnt(25)
; template <int OFF = 0, class V> __device__ __forceinline__ void st_wt8(void* p, V v) { static_assert(sizeof(V) == 8, ""); asm volatile("global_store_dwordx2 %0, %1, off offset:%2 sc1\n\ts_nop 1" :: "v"(p), "v"(v), "i"(OFF)); }
; __device__ __forceinline__ unsigned pk2(float lo, float hi) { return pg8::cvt_pk_bf16(lo, hi); }
; __device__ __forceinline__ void row_to_bf16(const f32x4 (&ov)[16], bf16* __restrict__ orow, float* rs_out, unsigned* __restrict__ xq, float* as_out, int lane) {
;     float ss = 0.f, am = 0.f;
; #pragma unroll
;     for (int j = 0; j < 16; ++j) { const int c = (lane + 64 * j) * 4; const f32x4 v = ov[j];
;         ss += (v.x * v.x + v.y * v.y) + (v.z * v.z + v.w * v.w); am = fmaxf(fmaxf(am, fmaxf(fabsf(v.x), fabsf(v.y))), fmaxf(fabsf(v.z), fabsf(v.w)));
;         v2u o; o.x = pk2(v.x, v.y); o.y = pk2(v.z, v.w); st_wt8(orow + c, o); }
	v_mul_f32_e32 v168, v97, v97
	v_mul_f32_e32 v169, v99, v99
	v_fmac_f32_e32 v168, v96, v96
	v_fmac_f32_e32 v169, v98, v98
	v_add_f32_e32 v168, v168, v169
	v_add_f32_e32 v174, v174, v168
	v_max_f32_e64 v168, |v97|, |v97|
	v_max_f32_e64 v169, |v96|, |v96|
	v_max_f32_e32 v168, v169, v168
	v_max_f32_e64 v169, |v99|, |v99|
	v_max_f32_e64 v172, |v98|, |v98|
	v_max_f32_e32 v169, v172, v169
	v_max3_f32 v175, v175, v168, v169
	v_cvt_pk_bf16_f32 v168, v96, v97
	v_cvt_pk_bf16_f32 v169, v98, v99
	v_lshl_add_u64 v[172:173], v[170:171], 0, s[30:31]
	global_store_dwordx2 v[172:173], v[168:169], off offset:0 sc1 nt
	s_nop 1
	s_waitcnt vmcnt(24)
	v_mul_f32_e32 v168, v89, v89
	v_mul_f32_e32 v169, v91, v91
	v_fmac_f32_e32 v168, v88, v88
	v_fmac_f32_e32 v169, v90, v90
	v_add_f32_e32 v168, v168, v169
	v_add_f32_e32 v172, v174, v168
	v_max_f32_e64 v168, |v89|, |v89|
	v_max_f32_e64 v169, |v88|, |v88|
	v_max_f32_e32 v168, v169, v168
	v_max_f32_e64 v169, |v91|, |v91|
	v_max_f32_e64 v173, |v90|, |v90|
	v_max_f32_e32 v169, v173, v169
	v_max3_f32 v173, v175, v168, v169
	v_cvt_pk_bf16_f32 v168, v88, v89
	v_cvt_pk_bf16_f32 v169, v90, v91
	v_lshl_add_u64 v[170:171], v[170:171], 0, s[34:35]
	global_store_dwordx2 v[170:171], v[168:169], off offset:0 sc1 nt
	s_nop 1
	s_waitcnt vmcnt(23)
	v_mul_f32_e32 v168, v81, v81
	v_mul_f32_e32 v169, v83, v83
	v_fmac_f32_e32 v168, v80, v80
	v_fmac_f32_e32 v169, v82, v82
	v_add_f32_e32 v168, v168, v169
	v_add_f32_e32 v172, v172, v168
	v_max_f32_e64 v168, |v81|, |v81|
	v_max_f32_e64 v169, |v80|, |v80|
	v_max_f32_e32 v168, v169, v168
	v_max_f32_e64 v169, |v83|, |v83|
	v_max_f32_e64 v170, |v82|, |v82|
	v_max_f32_e32 v169, v170, v169
	v_max3_f32 v173, v173, v168, v169
	v_cvt_pk_bf16_f32 v168, v80, v81
	v_cvt_pk_bf16_f32 v169, v82, v83
	v_lshl_add_u64 v[170:171], v[140:141], 1, v[162:163]
	global_store_dwordx2 v[170:171], v[168:169], off offset:0 sc1 nt
	s_nop 1
	s_waitcnt vmcnt(22)
	v_mul_f32_e32 v168, v73, v73
	v_mul_f32_e32 v169, v75, v75
	v_fmac_f32_e32 v168, v72, v72
	v_fmac_f32_e32 v169, v74, v74
	v_add_f32_e32 v168, v168, v169
	v_add_f32_e32 v172, v172, v168
	v_max_f32_e64 v168, |v73|, |v73|
	v_max_f32_e64 v169, |v72|, |v72|
	v_max_f32_e32 v168, v169, v168
	v_max_f32_e64 v169, |v75|, |v75|
	v_max_f32_e64 v170, |v74|, |v74|
	v_max_f32_e32 v169, v170, v169
	v_max3_f32 v173, v173, v168, v169
	v_cvt_pk_bf16_f32 v168, v72, v73
	v_cvt_pk_bf16_f32 v169, v74, v75
	v_lshl_add_u64 v[170:171], v[142:143], 1, v[162:163]
	global_store_dwordx2 v[170:171], v[168:169], off offset:0 sc1 nt
	s_nop 1
	s_waitcnt vmcnt(21)
	v_mul_f32_e32 v168, v65, v65
	v_mul_f32_e32 v169, v67, v67
	v_fmac_f32_e32 v168, v64, v64
	v_fmac_f32_e32 v169, v66, v66
	v_add_f32_e32 v168, v168, v169
	v_add_f32_e32 v172, v172, v168
	v_max_f32_e64 v168, |v65|, |v65|
	v_max_f32_e64 v169, |v64|, |v64|
	v_max_f32_e32 v168, v169, v168
	v_max_f32_e64 v169, |v67|, |v67|
	v_max_f32_e64 v170, |v66|, |v66|
	v_max_f32_e32 v169, v170, v169
	v_max3_f32 v173, v173, v168, v169
	v_cvt_pk_bf16_f32 v168, v64, v65
	v_cvt_pk_bf16_f32 v169, v66, v67
	v_lshl_add_u64 v[170:171], v[144:145], 1, v[162:163]
	global_store_dwordx2 v[170:171], v[168:169], off offset:0 sc1 nt
	s_nop 1
	s_waitcnt vmcnt(20)
	v_mul_f32_e32 v168, v61, v61
	v_mul_f32_e32 v169, v63, v63
	v_fmac_f32_e32 v168, v60, v60
	v_fmac_f32_e32 v169, v62, v62
	v_add_f32_e32 v168, v168, v169
	v_add_f32_e32 v172, v172, v168
	v_max_f32_e64 v168, |v61|, |v61|
	v_max_f32_e64 v169, |v60|, |v60|
	v_max_f32_e32 v168, v169, v168
	v_max_f32_e64 v169, |v63|, |v63|
	v_max_f32_e64 v170, |v62|, |v62|
	v_max_f32_e32 v169, v170, v169
	v_max3_f32 v173, v173, v168, v169
	v_cvt_pk_bf16_f32 v168, v60, v61
	v_cvt_pk_bf16_f32 v169, v62, v63
	v_lshl_add_u64 v[170:171], v[146:147], 1, v[162:163]
	global_store_dwordx2 v[170:171], v[168:169], off offset:0 sc1 nt
	s_nop 1
	s_waitcnt vmcnt(19)
	v_mul_f32_e32 v168, v53, v53
	v_mul_f32_e32 v169, v55, v55
	v_fmac_f32_e32 v168, v52, v52
	v_fmac_f32_e32 v169, v54, v54
	v_add_f32_e32 v168, v168, v169
	v_add_f32_e32 v172, v172, v168
	v_max_f32_e64 v168, |v53|, |v53|
	v_max_f32_e64 v169, |v52|, |v52|
	v_max_f32_e32 v168, v169, v168
	v_max_f32_e64 v169, |v55|, |v55|
	v_max_f32_e64 v170, |v54|, |v54|
	v_max_f32_e32 v169, v170, v169
	v_max3_f32 v173, v173, v168, v169
	v_cvt_pk_bf16_f32 v168, v52, v53
	v_cvt_pk_bf16_f32 v169, v54, v55
	v_lshl_add_u64 v[170:171], v[148:149], 1, v[162:163]
	global_store_dwordx2 v[170:171], v[168:169], off offset:0 sc1 nt
	s_nop 1
	s_waitcnt vmcnt(18)
	v_mul_f32_e32 v168, v45, v45
	v_mul_f32_e32 v169, v47, v47
	v_fmac_f32_e32 v168, v44, v44
	v_fmac_f32_e32 v169, v46, v46
	v_add_f32_e32 v168, v168, v169
	v_add_f32_e32 v169, v172, v168
	v_max_f32_e64 v168, |v45|, |v45|
	v_max_f32_e64 v170, |v44|, |v44|
	v_max_f32_e32 v168, v170, v168
	v_max_f32_e64 v170, |v47|, |v47|
	v_max_f32_e64 v171, |v46|, |v46|
	v_max_f32_e32 v170, v171, v170
	s_waitcnt vmcnt(17)
	v_mul_f32_e32 v171, v37, v37
	v_mul_f32_e32 v172, v39, v39
	v_fmac_f32_e32 v171, v36, v36
	v_fmac_f32_e32 v172, v38, v38
	v_add_f32_e32 v171, v171, v172
	v_add_f32_e32 v169, v169, v171
	v_max_f32_e64 v171, |v37|, |v37|
	v_max_f32_e64 v172, |v36|, |v36|
	v_max3_f32 v170, v173, v168, v170
	v_max_f32_e32 v171, v172, v171
	v_max_f32_e64 v172, |v39|, |v39|
	v_max_f32_e64 v173, |v38|, |v38|
	v_max_f32_e32 v172, v173, v172
	v_max3_f32 v170, v170, v171, v172
	s_waitcnt vmcnt(16)
; template <int O> __device__ __forceinline__ float xsw(float v) { return __int_as_float(__builtin_amdgcn_ds_swizzle(__float_as_int(v), (O << 10) | 0x1f)); }
; __device__ __forceinline__ float xsum32(float v) { auto rr = __builtin_amdgcn_permlane32_swap(__float_as_uint(v), __float_as_uint(v), false, false); return __uint_as_float(rr[0]) + __uint_as_float(rr[1]); }
; __device__ __forceinline__ float xmax32(float v) { auto rr = __builtin_amdgcn_permlane32_swap(__float_as_uint(v), __float_as_uint(v), false, false); return fmaxf(__uint_as_float(rr[0]), __uint_as_float(rr[1])); }
; template <int OFF = 0, class V> __device__ __forceinline__ void st_wt8(void* p, V v) { static_assert(sizeof(V) == 8, ""); asm volatile("global_store_dwordx2 %0, %1, off offset:%2 sc1\n\ts_nop 1" :: "v"(p), "v"(v), "i"(OFF)); }
; __device__ __forceinline__ void st_wt4(void* p, unsigned v) { asm volatile("global_store_dword %0, %1, off sc1\n\ts_nop 1" :: "v"(p), "v"(v)); }
; __device__ __forceinline__ unsigned pk2(float lo, float hi) { return pg8::cvt_pk_bf16(lo, hi); }
; __device__ __forceinline__ float wave_sum(float v) {
;     v += xsw<1>(v); v += xsw<2>(v); v += xsw<4>(v); v += xsw<8>(v); v += xsw<16>(v);
;     return xsum32(v);
; __device__ __forceinline__ float wave_max(float v) {
;     v = fmaxf(v, xsw<1>(v)); v = fmaxf(v, xsw<2>(v)); v = fmaxf(v, xsw<4>(v)); v = fmaxf(v, xsw<8>(v)); v = fmaxf(v, xsw<16>(v));
;     return xmax32(v);
; }
; __device__ __forceinline__ void row_to_bf16(const f32x4 (&ov)[16], bf16* __restrict__ orow, float* rs_out, unsigned* __restrict__ xq, float* as_out, int lane) {
;     ...
;     for (int j = 0; j < 16; ++j) { const int c = (lane + 64 * j) * 4; const f32x4 v = ov[j];
;         ss += (v.x * v.x + v.y * v.y) + (v.z * v.z + v.w * v.w); am = fmaxf(fmaxf(am, fmaxf(fabsf(v.x), fabsf(v.y))), fmaxf(fabsf(v.z), fabsf(v.w)));
;         v2u o; o.x = pk2(v.x, v.y); o.y = pk2(v.z, v.w); st_wt8(orow + c, o); }
;     ss = wave_sum(ss); am = fmaxf(wave_max(am), 1e-20f); const float qs = 127.0f / am;
; #pragma unroll
;     for (int j = 0; j < 16; ++j) { const int q0 = (int)rintf(ov[j].x * qs), q1 = (int)rintf(ov[j].y * qs), q2 = (int)rintf(ov[j].z * qs), q3 = (int)rintf(ov[j].w * qs);
;         st_wt4(xq + lane + 64 * j, ((unsigned)q0 & 255u) | (((unsigned)q1 & 255u) << 8) | (((unsigned)q2 & 255u) << 16) | ((unsigned)q3 << 24)); }
	v_mul_f32_e32 v171, v29, v29
	v_mul_f32_e32 v172, v31, v31
	v_fmac_f32_e32 v171, v28, v28
	v_fmac_f32_e32 v172, v30, v30
	v_add_f32_e32 v171, v171, v172
	v_add_f32_e32 v172, v169, v171
	v_max_f32_e64 v169, |v29|, |v29|
	v_max_f32_e64 v171, |v28|, |v28|
	v_max_f32_e32 v169, v171, v169
	v_max_f32_e64 v171, |v31|, |v31|
	v_max_f32_e64 v173, |v30|, |v30|
	v_max_f32_e32 v171, v173, v171
	v_max3_f32 v174, v170, v169, v171
	ds_swizzle_b32 v175, v174 offset:swizzle(SWAP,1)
	ds_swizzle_b32 v173, v172 offset:swizzle(SWAP,1)
	v_cvt_pk_bf16_f32 v168, v44, v45
	v_cvt_pk_bf16_f32 v169, v46, v47
	v_lshl_add_u64 v[170:171], v[150:151], 1, v[162:163]
	s_waitcnt lgkmcnt(1)
	v_max_f32_e32 v175, v175, v175
	v_max_f32_e32 v174, v174, v175
	ds_swizzle_b32 v175, v174 offset:swizzle(SWAP,2)
	s_waitcnt lgkmcnt(1)
	v_add_f32_e32 v172, v172, v173
	ds_swizzle_b32 v173, v172 offset:swizzle(SWAP,2)
	global_store_dwordx2 v[170:171], v[168:169], off offset:0 sc1 nt
	s_nop 1
	v_cvt_pk_bf16_f32 v168, v36, v37
	s_waitcnt lgkmcnt(1)
	v_max_f32_e32 v169, v175, v175
	v_max_f32_e32 v174, v174, v169
	ds_swizzle_b32 v175, v174 offset:swizzle(SWAP,4)
	s_waitcnt lgkmcnt(1)
	v_add_f32_e32 v172, v172, v173
	ds_swizzle_b32 v173, v172 offset:swizzle(SWAP,4)
	v_cvt_pk_bf16_f32 v169, v38, v39
	v_lshl_add_u64 v[170:171], v[152:153], 1, v[162:163]
	s_waitcnt lgkmcnt(1)
	v_max_f32_e32 v175, v175, v175
	v_max_f32_e32 v174, v174, v175
	s_waitcnt lgkmcnt(0)
	v_add_f32_e32 v172, v172, v173
	ds_swizzle_b32 v175, v174 offset:swizzle(SWAP,8)
	ds_swizzle_b32 v173, v172 offset:swizzle(SWAP,8)
	global_store_dwordx2 v[170:171], v[168:169], off offset:0 sc1 nt
	s_nop 1
	v_lshl_add_u64 v[162:163], v[154:155], 1, v[162:163]
	v_cvt_pk_bf16_f32 v168, v28, v29
	s_waitcnt lgkmcnt(1)
	v_max_f32_e32 v169, v175, v175
	s_waitcnt lgkmcnt(0)
	v_add_f32_e32 v170, v172, v173
	v_max_f32_e32 v172, v174, v169
	ds_swizzle_b32 v173, v172 offset:swizzle(SWAP,16)
	v_cvt_pk_bf16_f32 v169, v30, v31
	ds_swizzle_b32 v171, v170 offset:swizzle(SWAP,16)
	global_store_dwordx2 v[162:163], v[168:169], off offset:0 sc1 nt
	s_nop 1
	v_lshl_add_u64 v[160:161], v[156:157], 0, v[160:161]
	s_waitcnt lgkmcnt(1)
	v_max_f32_e32 v162, v173, v173
	v_max_f32_e32 v162, v172, v162
	v_mov_b32_e32 v168, v162
	s_nop 1
	v_permlane32_swap_b32_e32 v162, v168
	v_max3_f32 v162, v162, v168, s58
	v_div_scale_f32 v169, s[4:5], v162, v162, s59
	s_waitcnt lgkmcnt(0)
	v_add_f32_e32 v163, v170, v171
	v_rcp_f32_e32 v170, v169
	v_mov_b32_e32 v168, v163
	s_nop 1
	v_permlane32_swap_b32_e32 v163, v168
	v_fma_f32 v171, -v169, v170, 1.0
	v_fmac_f32_e32 v170, v171, v170
	v_div_scale_f32 v171, vcc, s59, v162, s59
	v_mul_f32_e32 v172, v171, v170
	v_fma_f32 v173, -v169, v172, v171
	v_fmac_f32_e32 v172, v173, v170
	v_fma_f32 v169, -v169, v172, v171
	v_div_fmas_f32 v169, v169, v170, v172
	v_div_fixup_f32 v169, v169, v162, s59
	v_mul_f32_e32 v125, v125, v169
	v_mul_f32_e32 v124, v124, v169
	v_rndne_f32_e32 v125, v125
	v_mul_f32_e32 v126, v126, v169
	v_mul_f32_e32 v127, v127, v169
	v_rndne_f32_e32 v124, v124
	v_cvt_i32_f32_e32 v125, v125
	v_rndne_f32_e32 v126, v126
	v_rndne_f32_e32 v127, v127
	v_cvt_i32_f32_e32 v124, v124
	v_cvt_i32_f32_sdwa v126, v126 dst_sel:WORD_1 dst_unused:UNUSED_PAD src0_sel:DWORD
	v_cvt_i32_f32_e32 v127, v127
	v_lshlrev_b32_e32 v125, 8, v125
	v_and_b32_e32 v125, 0xff00, v125
	v_and_b32_e32 v126, 0xff0000, v126
	v_perm_b32 v124, v127, v124, s60
	v_mul_f32_e32 v120, v120, v169
	v_or3_b32 v124, v124, v125, v126
	v_rndne_f32_e32 v120, v120
	global_store_dword v[160:161], v124, off sc1
	s_nop 1
	v_cvt_i32_f32_e32 v124, v120
	v_mul_f32_e32 v120, v121, v169
	v_rndne_f32_e32 v120, v120
	v_cvt_i32_f32_e32 v125, v120
	v_mul_f32_e32 v120, v122, v169
	v_rndne_f32_e32 v120, v120
	v_cvt_i32_f32_sdwa v122, v120 dst_sel:WORD_1 dst_unused:UNUSED_PAD src0_sel:DWORD
	v_mul_f32_e32 v120, v123, v169
	v_rndne_f32_e32 v120, v120
	v_cvt_i32_f32_e32 v123, v120
	v_lshlrev_b32_e32 v125, 8, v125
	v_mul_f32_e32 v116, v116, v169
	v_lshl_add_u64 v[120:121], v[160:161], 0, s[36:37]
	v_and_b32_e32 v125, 0xff00, v125
	v_and_b32_e32 v122, 0xff0000, v122
	v_perm_b32 v123, v123, v124, s60
	v_rndne_f32_e32 v116, v116
	v_or3_b32 v122, v123, v125, v122
	global_store_dword v[120:121], v122, off sc1
	s_nop 1
	v_cvt_i32_f32_e32 v120, v116
	v_mul_f32_e32 v116, v117, v169
	v_rndne_f32_e32 v116, v116
	v_cvt_i32_f32_e32 v121, v116
	v_mul_f32_e32 v116, v118, v169
	v_rndne_f32_e32 v116, v116
	v_cvt_i32_f32_sdwa v118, v116 dst_sel:WORD_1 dst_unused:UNUSED_PAD src0_sel:DWORD
	v_mul_f32_e32 v116, v119, v169
	v_rndne_f32_e32 v116, v116
	v_cvt_i32_f32_e32 v119, v116
	v_lshlrev_b32_e32 v121, 8, v121
	v_mul_f32_e32 v112, v112, v169
	v_lshl_add_u64 v[116:117], v[160:161], 0, s[20:21]
	v_and_b32_e32 v121, 0xff00, v121
	v_and_b32_e32 v118, 0xff0000, v118
	v_perm_b32 v119, v119, v120, s60
	v_rndne_f32_e32 v112, v112
	v_or3_b32 v118, v119, v121, v118
	global_store_dword v[116:117], v118, off sc1
	s_nop 1
	v_cvt_i32_f32_e32 v116, v112
	v_mul_f32_e32 v112, v113, v169
	v_rndne_f32_e32 v112, v112
	v_cvt_i32_f32_e32 v117, v112
	v_mul_f32_e32 v112, v114, v169
	v_rndne_f32_e32 v112, v112
	v_cvt_i32_f32_sdwa v114, v112 dst_sel:WORD_1 dst_unused:UNUSED_PAD src0_sel:DWORD
	v_mul_f32_e32 v112, v115, v169
	v_rndne_f32_e32 v112, v112
	v_cvt_i32_f32_e32 v115, v112
	v_lshlrev_b32_e32 v117, 8, v117
	v_mul_f32_e32 v108, v108, v169
	v_lshl_add_u64 v[112:113], v[160:161], 0, s[38:39]
	v_and_b32_e32 v117, 0xff00, v117
	v_and_b32_e32 v114, 0xff0000, v114
	v_perm_b32 v115, v115, v116, s60
	v_rndne_f32_e32 v108, v108
	v_or3_b32 v114, v115, v117, v114
	global_store_dword v[112:113], v114, off sc1
	s_nop 1
	v_cvt_i32_f32_e32 v112, v108
; __device__ __forceinline__ void st_wt4(void* p, unsigned v) { asm volatile("global_store_dword %0, %1, off sc1\n\ts_nop 1" :: "v"(p), "v"(v)); }
; __device__ __forceinline__ void row_to_bf16(const f32x4 (&ov)[16], bf16* __restrict__ orow, float* rs_out, unsigned* __restrict__ xq, float* as_out, int lane) {
;     ...
; #pragma unroll
;     for (int j = 0; j < 16; ++j) { const int q0 = (int)rintf(ov[j].x * qs), q1 = (int)rintf(ov[j].y * qs), q2 = (int)rintf(ov[j].z * qs), q3 = (int)rintf(ov[j].w * qs);
;         st_wt4(xq + lane + 64 * j, ((unsigned)q0 & 255u) | (((unsigned)q1 & 255u) << 8) | (((unsigned)q2 & 255u) << 16) | ((unsigned)q3 << 24)); }
	v_mul_f32_e32 v108, v109, v169
	v_rndne_f32_e32 v108, v108
	v_cvt_i32_f32_e32 v113, v108
	v_mul_f32_e32 v108, v110, v169
	v_rndne_f32_e32 v108, v108
	v_cvt_i32_f32_sdwa v110, v108 dst_sel:WORD_1 dst_unused:UNUSED_PAD src0_sel:DWORD
	v_mul_f32_e32 v108, v111, v169
	v_rndne_f32_e32 v108, v108
	v_cvt_i32_f32_e32 v111, v108
	v_lshlrev_b32_e32 v113, 8, v113
	v_mul_f32_e32 v100, v100, v169
	v_lshl_add_u64 v[108:109], v[160:161], 0, s[22:23]
	v_and_b32_e32 v113, 0xff00, v113
	v_and_b32_e32 v110, 0xff0000, v110
	v_perm_b32 v111, v111, v112, s60
	v_rndne_f32_e32 v100, v100
	v_or3_b32 v110, v111, v113, v110
	global_store_dword v[108:109], v110, off sc1
	s_nop 1
	v_cvt_i32_f32_e32 v108, v100
	v_mul_f32_e32 v100, v101, v169
	v_rndne_f32_e32 v100, v100
	v_cvt_i32_f32_e32 v109, v100
	v_mul_f32_e32 v100, v102, v169
	v_rndne_f32_e32 v100, v100
	v_cvt_i32_f32_sdwa v102, v100 dst_sel:WORD_1 dst_unused:UNUSED_PAD src0_sel:DWORD
	v_mul_f32_e32 v100, v103, v169
	v_rndne_f32_e32 v100, v100
	v_cvt_i32_f32_e32 v103, v100
	v_lshlrev_b32_e32 v109, 8, v109
	v_mul_f32_e32 v96, v96, v169
	v_lshl_add_u64 v[100:101], v[160:161], 0, s[40:41]
	v_and_b32_e32 v109, 0xff00, v109
	v_and_b32_e32 v102, 0xff0000, v102
	v_perm_b32 v103, v103, v108, s60
	v_rndne_f32_e32 v96, v96
	v_or3_b32 v102, v103, v109, v102
	global_store_dword v[100:101], v102, off sc1
	s_nop 1
	v_cvt_i32_f32_e32 v100, v96
	v_mul_f32_e32 v96, v97, v169
	v_rndne_f32_e32 v96, v96
	v_cvt_i32_f32_e32 v101, v96
	v_mul_f32_e32 v96, v98, v169
	v_rndne_f32_e32 v96, v96
	v_cvt_i32_f32_sdwa v98, v96 dst_sel:WORD_1 dst_unused:UNUSED_PAD src0_sel:DWORD
	v_mul_f32_e32 v96, v99, v169
	v_rndne_f32_e32 v96, v96
	v_cvt_i32_f32_e32 v99, v96
	v_lshlrev_b32_e32 v101, 8, v101
	v_mul_f32_e32 v88, v88, v169
	v_lshl_add_u64 v[96:97], v[160:161], 0, s[24:25]
	v_and_b32_e32 v101, 0xff00, v101
	v_and_b32_e32 v98, 0xff0000, v98
	v_perm_b32 v99, v99, v100, s60
	v_rndne_f32_e32 v88, v88
	v_or3_b32 v98, v99, v101, v98
	global_store_dword v[96:97], v98, off sc1
	s_nop 1
	v_cvt_i32_f32_e32 v96, v88
	v_mul_f32_e32 v88, v89, v169
	v_rndne_f32_e32 v88, v88
	v_cvt_i32_f32_e32 v97, v88
	v_mul_f32_e32 v88, v90, v169
	v_rndne_f32_e32 v88, v88
	v_cvt_i32_f32_sdwa v90, v88 dst_sel:WORD_1 dst_unused:UNUSED_PAD src0_sel:DWORD
	v_mul_f32_e32 v88, v91, v169
	v_rndne_f32_e32 v88, v88
	v_cvt_i32_f32_e32 v91, v88
	v_lshlrev_b32_e32 v97, 8, v97
	v_mul_f32_e32 v80, v80, v169
	v_lshl_add_u64 v[88:89], v[160:161], 0, s[42:43]
	v_and_b32_e32 v97, 0xff00, v97
	v_and_b32_e32 v90, 0xff0000, v90
	v_perm_b32 v91, v91, v96, s60
	v_rndne_f32_e32 v80, v80
	v_or3_b32 v90, v91, v97, v90
	global_store_dword v[88:89], v90, off sc1
	s_nop 1
	v_cvt_i32_f32_e32 v88, v80
	v_mul_f32_e32 v80, v81, v169
	v_rndne_f32_e32 v80, v80
	v_cvt_i32_f32_e32 v89, v80
	v_mul_f32_e32 v80, v82, v169
	v_rndne_f32_e32 v80, v80
	v_cvt_i32_f32_sdwa v82, v80 dst_sel:WORD_1 dst_unused:UNUSED_PAD src0_sel:DWORD
	v_mul_f32_e32 v80, v83, v169
	v_rndne_f32_e32 v80, v80
	v_cvt_i32_f32_e32 v83, v80
	v_lshlrev_b32_e32 v89, 8, v89
	v_mul_f32_e32 v72, v72, v169
	v_lshl_add_u64 v[80:81], v[160:161], 0, s[26:27]
	v_and_b32_e32 v89, 0xff00, v89
	v_and_b32_e32 v82, 0xff0000, v82
	v_perm_b32 v83, v83, v88, s60
	v_rndne_f32_e32 v72, v72
	v_or3_b32 v82, v83, v89, v82
	global_store_dword v[80:81], v82, off sc1
	s_nop 1
	v_cvt_i32_f32_e32 v80, v72
	v_mul_f32_e32 v72, v73, v169
	v_rndne_f32_e32 v72, v72
	v_cvt_i32_f32_e32 v81, v72
	v_mul_f32_e32 v72, v74, v169
	v_rndne_f32_e32 v72, v72
	v_cvt_i32_f32_sdwa v74, v72 dst_sel:WORD_1 dst_unused:UNUSED_PAD src0_sel:DWORD
	v_mul_f32_e32 v72, v75, v169
	v_rndne_f32_e32 v72, v72
	v_cvt_i32_f32_e32 v75, v72
	v_lshlrev_b32_e32 v81, 8, v81
	v_mul_f32_e32 v64, v64, v169
	v_lshl_add_u64 v[72:73], v[160:161], 0, s[44:45]
	v_and_b32_e32 v81, 0xff00, v81
	v_and_b32_e32 v74, 0xff0000, v74
	v_perm_b32 v75, v75, v80, s60
	v_rndne_f32_e32 v64, v64
	v_or3_b32 v74, v75, v81, v74
	global_store_dword v[72:73], v74, off sc1
	s_nop 1
	v_cvt_i32_f32_e32 v72, v64
	v_mul_f32_e32 v64, v65, v169
	v_rndne_f32_e32 v64, v64
	v_cvt_i32_f32_e32 v73, v64
	v_mul_f32_e32 v64, v66, v169
	v_rndne_f32_e32 v64, v64
	v_cvt_i32_f32_sdwa v66, v64 dst_sel:WORD_1 dst_unused:UNUSED_PAD src0_sel:DWORD
	v_mul_f32_e32 v64, v67, v169
	v_rndne_f32_e32 v64, v64
	v_cvt_i32_f32_e32 v67, v64
	v_lshlrev_b32_e32 v73, 8, v73
	v_mul_f32_e32 v60, v60, v169
	v_lshl_add_u64 v[64:65], v[160:161], 0, s[28:29]
	v_and_b32_e32 v73, 0xff00, v73
	v_and_b32_e32 v66, 0xff0000, v66
	v_perm_b32 v67, v67, v72, s60
	v_rndne_f32_e32 v60, v60
	v_or3_b32 v66, v67, v73, v66
	global_store_dword v[64:65], v66, off sc1
; __device__ __forceinline__ void st_wt4(void* p, unsigned v) { asm volatile("global_store_dword %0, %1, off sc1\n\ts_nop 1" :: "v"(p), "v"(v)); }
; __device__ __forceinline__ void row_to_bf16(const f32x4 (&ov)[16], bf16* __restrict__ orow, float* rs_out, unsigned* __restrict__ xq, float* as_out, int lane) {
;     ...
; #pragma unroll
;     for (int j = 0; j < 16; ++j) { const int q0 = (int)rintf(ov[j].x * qs), q1 = (int)rintf(ov[j].y * qs), q2 = (int)rintf(ov[j].z * qs), q3 = (int)rintf(ov[j].w * qs);
;         st_wt4(xq + lane + 64 * j, ((unsigned)q0 & 255u) | (((unsigned)q1 & 255u) << 8) | (((unsigned)q2 & 255u) << 16) | ((unsigned)q3 << 24)); }
;     if (lane == 0) { *rs_out = 1.0f / sqrtf(ss * (1.0f / DM) + EPS); *as_out = am * (1.0f / 127.0f); }
	s_nop 1
	v_cvt_i32_f32_e32 v64, v60
	v_mul_f32_e32 v60, v61, v169
	v_rndne_f32_e32 v60, v60
	v_cvt_i32_f32_e32 v65, v60
	v_mul_f32_e32 v60, v62, v169
	v_rndne_f32_e32 v60, v60
	v_cvt_i32_f32_sdwa v62, v60 dst_sel:WORD_1 dst_unused:UNUSED_PAD src0_sel:DWORD
	v_mul_f32_e32 v60, v63, v169
	v_rndne_f32_e32 v60, v60
	v_cvt_i32_f32_e32 v63, v60
	v_lshlrev_b32_e32 v65, 8, v65
	v_mul_f32_e32 v52, v52, v169
	v_lshl_add_u64 v[60:61], v[160:161], 0, s[46:47]
	v_and_b32_e32 v65, 0xff00, v65
	v_and_b32_e32 v62, 0xff0000, v62
	v_perm_b32 v63, v63, v64, s60
	v_rndne_f32_e32 v52, v52
	v_or3_b32 v62, v63, v65, v62
	global_store_dword v[60:61], v62, off sc1
	s_nop 1
	v_cvt_i32_f32_e32 v60, v52
	v_mul_f32_e32 v52, v53, v169
	v_rndne_f32_e32 v52, v52
	v_cvt_i32_f32_e32 v61, v52
	v_mul_f32_e32 v52, v54, v169
	v_rndne_f32_e32 v52, v52
	v_cvt_i32_f32_sdwa v54, v52 dst_sel:WORD_1 dst_unused:UNUSED_PAD src0_sel:DWORD
	v_mul_f32_e32 v52, v55, v169
	v_rndne_f32_e32 v52, v52
	v_cvt_i32_f32_e32 v55, v52
	v_lshlrev_b32_e32 v61, 8, v61
	v_mul_f32_e32 v44, v44, v169
	v_lshl_add_u64 v[52:53], v[160:161], 0, s[30:31]
	v_and_b32_e32 v61, 0xff00, v61
	v_and_b32_e32 v54, 0xff0000, v54
	v_perm_b32 v55, v55, v60, s60
	v_rndne_f32_e32 v44, v44
	v_or3_b32 v54, v55, v61, v54
	global_store_dword v[52:53], v54, off sc1
	s_nop 1
	v_cvt_i32_f32_e32 v52, v44
	v_mul_f32_e32 v44, v45, v169
	v_rndne_f32_e32 v44, v44
	v_cvt_i32_f32_e32 v53, v44
	v_mul_f32_e32 v44, v46, v169
	v_rndne_f32_e32 v44, v44
	v_cvt_i32_f32_sdwa v46, v44 dst_sel:WORD_1 dst_unused:UNUSED_PAD src0_sel:DWORD
	v_mul_f32_e32 v44, v47, v169
	v_rndne_f32_e32 v44, v44
	v_cvt_i32_f32_e32 v47, v44
	v_lshlrev_b32_e32 v53, 8, v53
	v_mul_f32_e32 v36, v36, v169
	v_lshl_add_u64 v[44:45], v[160:161], 0, s[48:49]
	v_and_b32_e32 v53, 0xff00, v53
	v_and_b32_e32 v46, 0xff0000, v46
	v_perm_b32 v47, v47, v52, s60
	v_rndne_f32_e32 v36, v36
	v_or3_b32 v46, v47, v53, v46
	global_store_dword v[44:45], v46, off sc1
	s_nop 1
	v_cvt_i32_f32_e32 v44, v36
	v_mul_f32_e32 v36, v37, v169
	v_rndne_f32_e32 v36, v36
	v_cvt_i32_f32_e32 v45, v36
	v_mul_f32_e32 v36, v38, v169
	v_rndne_f32_e32 v36, v36
	v_cvt_i32_f32_sdwa v38, v36 dst_sel:WORD_1 dst_unused:UNUSED_PAD src0_sel:DWORD
	v_mul_f32_e32 v36, v39, v169
	v_rndne_f32_e32 v36, v36
	v_cvt_i32_f32_e32 v39, v36
	v_lshlrev_b32_e32 v45, 8, v45
	v_mul_f32_e32 v28, v28, v169
	v_lshl_add_u64 v[36:37], v[160:161], 0, s[34:35]
	v_and_b32_e32 v45, 0xff00, v45
	v_and_b32_e32 v38, 0xff0000, v38
	v_perm_b32 v39, v39, v44, s60
	v_rndne_f32_e32 v28, v28
	v_or3_b32 v38, v39, v45, v38
	global_store_dword v[36:37], v38, off sc1
	s_nop 1
	v_cvt_i32_f32_e32 v36, v28
	v_mul_f32_e32 v28, v29, v169
	v_rndne_f32_e32 v28, v28
	v_cvt_i32_f32_e32 v37, v28
	v_mul_f32_e32 v28, v30, v169
	v_rndne_f32_e32 v28, v28
	v_cvt_i32_f32_sdwa v30, v28 dst_sel:WORD_1 dst_unused:UNUSED_PAD src0_sel:DWORD
	v_mul_f32_e32 v28, v31, v169
	v_rndne_f32_e32 v28, v28
	v_cvt_i32_f32_e32 v31, v28
	v_lshlrev_b32_e32 v37, 8, v37
	v_and_b32_e32 v37, 0xff00, v37
	v_and_b32_e32 v30, 0xff0000, v30
	v_perm_b32 v31, v31, v36, s60
	v_lshl_add_u64 v[28:29], v[160:161], 0, s[50:51]
	v_or3_b32 v30, v31, v37, v30
	global_store_dword v[28:29], v30, off sc1
	s_nop 1
	s_and_saveexec_b64 s[54:55], s[2:3]
	s_cbranch_execz .LBB0_61
	v_add_f32_e32 v28, v163, v168
	v_fmamk_f32 v28, v28, 0x39800000, v166
	v_mul_f32_e32 v29, 0x4f800000, v28
	v_cmp_gt_f32_e32 vcc, s61, v28
	s_nop 1
	v_cndmask_b32_e32 v28, v28, v29, vcc
	v_sqrt_f32_e32 v29, v28
	s_nop 0
	v_add_u32_e32 v30, -1, v29
	v_fma_f32 v36, -v30, v29, v28
	v_add_u32_e32 v31, 1, v29
	v_cmp_ge_f32_e64 s[4:5], 0, v36
	s_nop 1
	v_cndmask_b32_e64 v30, v29, v30, s[4:5]
	v_fma_f32 v29, -v31, v29, v28
	v_cmp_lt_f32_e64 s[4:5], 0, v29
	s_nop 1
	v_cndmask_b32_e64 v29, v30, v31, s[4:5]
	v_mul_f32_e32 v30, 0x37800000, v29
	v_cndmask_b32_e32 v29, v29, v30, vcc
	v_cmp_class_f32_e32 vcc, v28, v167
	s_nop 1
	v_cndmask_b32_e32 v36, v29, v28, vcc
	v_div_scale_f32 v37, s[4:5], v36, v36, 1.0
	v_rcp_f32_e32 v38, v37
	v_lshlrev_b64 v[28:29], 2, v[158:159]
	v_lshl_add_u64 v[30:31], s[18:19], 0, v[28:29]
	v_lshl_add_u64 v[28:29], s[14:15], 0, v[28:29]
	v_fma_f32 v39, -v37, v38, 1.0
	v_fmac_f32_e32 v38, v39, v38
	v_div_scale_f32 v39, vcc, 1.0, v36, 1.0
	v_mul_f32_e32 v44, v39, v38
	v_fma_f32 v45, -v37, v44, v39
	v_fmac_f32_e32 v44, v45, v38
	v_fma_f32 v37, -v37, v44, v39
	v_div_fmas_f32 v37, v37, v38, v44
	v_div_fixup_f32 v36, v37, v36, 1.0
	global_store_dword v[28:29], v36, off
	v_mul_f32_e32 v28, 0x3c010204, v162
	global_store_dword v[30:31], v28, off
	s_branch .LBB0_61

; __device__ __forceinline__ void resid_rows(bf16* __restrict__ XB, const bf16* __restrict__ Y, const float* __restrict__ PART, const float* __restrict__ g, float* __restrict__ RS, ...
;     ...
;     for (int m = gw; m < MTOK; m += NGW) {
;         const float pv = PART[(size_t)m * 64 + lane];
;         bf16* xrow = XB + (size_t)m * DM; const bf16* yrow = Y + (size_t)m * DM;
;         v2u xr[16], yr[16];
; #pragma unroll
;         for (int j = 0; j < 16; ++j) { xr[j] = *(const v2u*)(xrow + (lane + 64 * j) * 4); yr[j] = *(const v2u*)(yrow + (lane + 64 * j) * 4); }
;         const float ry = 1.0f / sqrtf(wave_sum(pv) * (1.0f / DM) + EPS);
.LBB0_814:
	v_lshl_add_u64 v[88:89], s[18:19], 0, v[64:65]
	v_lshl_add_u64 v[86:87], s[18:19], 0, v[84:85]
	v_add_co_u32_e32 v90, vcc, s7, v88
	s_mov_b64 s[4:5], 0x2d800200
	s_nop 0
	v_addc_co_u32_e32 v91, vcc, 0, v89, vcc
	global_load_dword v110, v[86:87], off
	global_load_dwordx2 v[172:173], v[90:91], off nt
	global_load_dwordx2 v[176:177], v[90:91], off offset:512 nt
	global_load_dwordx2 v[166:167], v[90:91], off offset:1024 nt
	v_add_co_u32_e32 v92, vcc, s9, v88
	v_lshl_add_u64 v[168:169], v[88:89], 0, s[4:5]
	s_nop 0
	v_addc_co_u32_e32 v93, vcc, 0, v89, vcc
	global_load_dwordx2 v[162:163], v[90:91], off offset:1536 nt
	global_load_dwordx2 v[154:155], v[90:91], off offset:2048 nt
	global_load_dwordx2 v[148:149], v[90:91], off offset:2560 nt
	global_load_dwordx2 v[142:143], v[90:91], off offset:3072 nt
	global_load_dwordx2 v[164:165], v[92:93], off offset:1536 nt
	global_load_dwordx2 v[158:159], v[92:93], off offset:2048 nt
	global_load_dwordx2 v[150:151], v[92:93], off offset:2560 nt
	global_load_dwordx2 v[144:145], v[92:93], off offset:3072 nt
	global_load_dwordx2 v[178:179], v[92:93], off nt
	global_load_dwordx2 v[180:181], v[92:93], off offset:512 nt
	global_load_dwordx2 v[182:183], v[92:93], off offset:1024 nt
	global_load_dwordx2 v[136:137], v[90:91], off offset:3584 nt
	s_mov_b64 s[4:5], 0x2d800400
	v_lshl_add_u64 v[160:161], v[88:89], 0, s[4:5]
	s_mov_b64 s[4:5], 0x2d800600
	v_lshl_add_u64 v[156:157], v[88:89], 0, s[4:5]
	s_mov_b64 s[4:5], 0x2d800800
	v_lshl_add_u64 v[152:153], v[88:89], 0, s[4:5]
	s_mov_b64 s[4:5], 0x2d800a00
	v_lshl_add_u64 v[146:147], v[88:89], 0, s[4:5]
	s_mov_b64 s[4:5], 0x2d800c00
	s_mov_b64 s[0:1], 0x2d800000
	v_lshl_add_u64 v[138:139], v[88:89], 0, s[4:5]
	s_mov_b64 s[4:5], 0x2d800e00
	v_lshl_add_u64 v[174:175], v[88:89], 0, s[0:1]
	v_lshl_add_u64 v[126:127], v[88:89], 0, s[4:5]
	v_lshl_add_u64 v[88:89], s[18:19], 0, v[66:67]
	v_add_co_u32_e32 v90, vcc, s7, v88
	v_lshl_add_u64 v[96:97], s[18:19], 0, v[68:69]
	s_nop 0
	v_addc_co_u32_e32 v91, vcc, 0, v89, vcc
	v_add_co_u32_e32 v94, vcc, s9, v88
	v_lshl_add_u64 v[86:87], v[88:89], 0, s[0:1]
	s_nop 0
	v_addc_co_u32_e32 v95, vcc, 0, v89, vcc
	v_add_co_u32_e32 v98, vcc, s7, v96
	v_lshl_add_u64 v[88:89], v[96:97], 0, s[0:1]
	s_nop 0
	v_addc_co_u32_e32 v99, vcc, 0, v97, vcc
	global_load_dwordx2 v[140:141], v[92:93], off offset:3584 nt
	global_load_dwordx2 v[130:131], v[90:91], off nt
	global_load_dwordx2 v[132:133], v[94:95], off nt
	global_load_dwordx2 v[122:123], v[98:99], off nt
	v_add_co_u32_e32 v94, vcc, s9, v96
	v_lshl_add_u64 v[92:93], s[18:19], 0, v[70:71]
	s_nop 0
	v_addc_co_u32_e32 v95, vcc, 0, v97, vcc
	v_add_co_u32_e32 v96, vcc, s7, v92
	v_lshl_add_u64 v[100:101], s[18:19], 0, v[72:73]
	s_nop 0
	v_addc_co_u32_e32 v97, vcc, 0, v93, vcc
	v_add_co_u32_e32 v98, vcc, s9, v92
	v_lshl_add_u64 v[90:91], v[92:93], 0, s[0:1]
	s_nop 0
	v_addc_co_u32_e32 v99, vcc, 0, v93, vcc
	v_add_co_u32_e32 v102, vcc, s7, v100
	v_lshl_add_u64 v[92:93], v[100:101], 0, s[0:1]
	s_nop 0
	v_addc_co_u32_e32 v103, vcc, 0, v101, vcc
	global_load_dwordx2 v[128:129], v[94:95], off nt
	global_load_dwordx2 v[114:115], v[96:97], off nt
	global_load_dwordx2 v[116:117], v[98:99], off nt
	global_load_dwordx2 v[106:107], v[102:103], off nt
	v_add_co_u32_e32 v98, vcc, s9, v100
	v_lshl_add_u64 v[96:97], s[18:19], 0, v[74:75]
	s_nop 0
	v_addc_co_u32_e32 v99, vcc, 0, v101, vcc
	v_add_co_u32_e32 v100, vcc, s7, v96
	v_lshl_add_u64 v[104:105], s[18:19], 0, v[76:77]
	s_nop 0
	v_addc_co_u32_e32 v101, vcc, 0, v97, vcc
	v_add_co_u32_e32 v102, vcc, s9, v96
	v_lshl_add_u64 v[94:95], v[96:97], 0, s[0:1]
	s_nop 0
	v_addc_co_u32_e32 v103, vcc, 0, v97, vcc
	v_add_co_u32_e32 v108, vcc, s7, v104
	s_waitcnt vmcnt(23)
	ds_swizzle_b32 v111, v110 offset:swizzle(SWAP,1)
	v_addc_co_u32_e32 v109, vcc, 0, v105, vcc
	global_load_dwordx2 v[134:135], v[98:99], off nt
	global_load_dwordx2 v[118:119], v[100:101], off nt
	global_load_dwordx2 v[120:121], v[102:103], off nt
	s_nop 0
	global_load_dwordx2 v[108:109], v[108:109], off nt
	v_add_co_u32_e32 v102, vcc, s9, v104
	s_waitcnt lgkmcnt(0)
	v_add_f32_e32 v110, v110, v111
	ds_swizzle_b32 v111, v110 offset:swizzle(SWAP,2)
	v_addc_co_u32_e32 v103, vcc, 0, v105, vcc
	v_lshl_add_u64 v[98:99], s[18:19], 0, v[78:79]
	v_lshl_add_u64 v[96:97], v[104:105], 0, s[0:1]
	s_waitcnt lgkmcnt(0)
	v_add_f32_e32 v110, v110, v111
	ds_swizzle_b32 v111, v110 offset:swizzle(SWAP,4)
	v_add_co_u32_e32 v104, vcc, s7, v98
	v_lshl_add_u64 v[170:171], s[18:19], 0, v[80:81]
	s_nop 0
	v_addc_co_u32_e32 v105, vcc, 0, v99, vcc
	s_waitcnt lgkmcnt(0)
	v_add_f32_e32 v110, v110, v111
	ds_swizzle_b32 v111, v110 offset:swizzle(SWAP,8)
	v_add_co_u32_e32 v112, vcc, s9, v98
	v_lshl_add_u64 v[100:101], v[98:99], 0, s[0:1]
	s_nop 0
	v_addc_co_u32_e32 v113, vcc, 0, v99, vcc
	s_waitcnt lgkmcnt(0)
	v_add_f32_e32 v110, v110, v111
	ds_swizzle_b32 v111, v110 offset:swizzle(SWAP,16)
	v_add_co_u32_e32 v184, vcc, s7, v170
	v_lshl_add_u64 v[98:99], v[170:171], 0, s[0:1]
	s_nop 0
	v_addc_co_u32_e32 v185, vcc, 0, v171, vcc
	s_waitcnt lgkmcnt(0)
; template <int OFF = 0, class V> __device__ __forceinline__ void st_wt16(void* p, V v) { static_assert(sizeof(V) == 16, ""); asm volatile("global_store_dwordx4 %0, %1, off offset:%2 sc1\n\ts_nop 1" :: "v"(p), "v"(v), "i"(OFF)); }
; template <int OFF = 0, class V> __device__ __forceinline__ void st_wt8(void* p, V v) { static_assert(sizeof(V) == 8, ""); asm volatile("global_store_dwordx2 %0, %1, off offset:%2 sc1\n\ts_nop 1" :: "v"(p), "v"(v), "i"(OFF)); }
; __device__ __forceinline__ unsigned pk2(float lo, float hi) { return pg8::cvt_pk_bf16(lo, hi); }
; __device__ __forceinline__ float bf_lo(unsigned w) { return __uint_as_float(w << 16); }
; __device__ __forceinline__ float bf_hi(unsigned w) { return __uint_as_float(w & 0xffff0000u); }
; __device__ __forceinline__ void resid_rows(bf16* __restrict__ XB, const bf16* __restrict__ Y, const float* __restrict__ PART, const float* __restrict__ g, float* __restrict__ RS, ...
;     ...
;         const float ry = 1.0f / sqrtf(wave_sum(pv) * (1.0f / DM) + EPS);
;         float ss = 0.f, am = 0.f; f32x4 ov[16];
; #pragma unroll
;         for (int j = 0; j < 16; ++j) { const int c = (lane + 64 * j) * 4;
;             f32x4 o; o.x = bf_lo(xr[j].x) + bf_lo(yr[j].x) * ry * gv[j].x; o.y = bf_hi(xr[j].x) + bf_hi(yr[j].x) * ry * gv[j].y; o.z = bf_lo(xr[j].y) + bf_lo(yr[j].y) * ry * gv[j].z; o.w = bf_hi(xr[j].y) + bf_hi(yr[j].y) * ry * gv[j].w;
;             ss += (o.x * o.x + o.y * o.y) + (o.z * o.z + o.w * o.w); ov[j] = o; am = fmaxf(fmaxf(am, fmaxf(fabsf(o.x), fabsf(o.y))), fmaxf(fabsf(o.z), fabsf(o.w)));
;             if (outf) st_wt16(outf + (size_t)m * DM + c, o); else { v2u ob; ob.x = pk2(o.x, o.y); ob.y = pk2(o.z, o.w); st_wt8(xrow + c, ob); } }
	v_add_f32_e32 v110, v110, v111
	v_mov_b32_e32 v111, v110
	s_nop 1
	v_permlane32_swap_b32_e32 v110, v111
	v_add_f32_e32 v110, v110, v111
	v_fmamk_f32 v110, v110, 0x39800000, v216
	s_mov_b32 s0, 0xf800000
	v_mul_f32_e32 v111, 0x4f800000, v110
	v_cmp_gt_f32_e32 vcc, s0, v110
	s_nop 1
	v_cndmask_b32_e32 v186, v110, v111, vcc
	v_sqrt_f32_e32 v187, v186
	global_load_dwordx2 v[124:125], v[102:103], off nt
	global_load_dwordx2 v[110:111], v[104:105], off nt
	s_nop 0
	global_load_dwordx2 v[112:113], v[112:113], off nt
	s_nop 0
	global_load_dwordx2 v[102:103], v[184:185], off nt
	v_add_u32_e32 v104, -1, v187
	v_fma_f32 v105, -v104, v187, v186
	v_cmp_ge_f32_e64 s[4:5], 0, v105
	v_add_u32_e32 v105, 1, v187
	v_fma_f32 v184, -v105, v187, v186
	v_cndmask_b32_e64 v104, v187, v104, s[4:5]
	v_cmp_lt_f32_e64 s[4:5], 0, v184
	s_nop 1
	v_cndmask_b32_e64 v104, v104, v105, s[4:5]
	v_mul_f32_e32 v105, 0x37800000, v104
	v_cndmask_b32_e32 v104, v104, v105, vcc
	v_cmp_class_f32_e32 vcc, v186, v239
	s_mov_b32 s4, 0x42fe0000
	s_nop 0
	v_cndmask_b32_e32 v184, v104, v186, vcc
	v_div_scale_f32 v185, s[0:1], v184, v184, 1.0
	v_rcp_f32_e32 v186, v185
	v_add_co_u32_e32 v104, vcc, s9, v170
	s_mov_b32 s0, 0x1e3ce508
	s_nop 0
	v_addc_co_u32_e32 v105, vcc, 0, v171, vcc
	v_fma_f32 v170, -v185, v186, 1.0
	v_fmac_f32_e32 v186, v170, v186
	v_div_scale_f32 v170, vcc, 1.0, v184, 1.0
	v_mul_f32_e32 v171, v170, v186
	v_fma_f32 v187, -v185, v171, v170
	v_fmac_f32_e32 v171, v187, v186
	v_fma_f32 v170, -v185, v171, v170
	v_div_fmas_f32 v170, v170, v186, v171
	v_div_fixup_f32 v184, v170, v184, 1.0
	s_waitcnt vmcnt(19)
	v_lshlrev_b32_e32 v171, 16, v178
	v_lshlrev_b32_e32 v170, 16, v172
	v_mul_f32_e32 v171, v184, v171
	v_fmac_f32_e32 v170, v60, v171
	v_and_b32_e32 v171, 0xffff0000, v172
	v_and_b32_e32 v172, 0xffff0000, v178
	v_mul_f32_e32 v172, v184, v172
	v_lshlrev_b32_e32 v178, 16, v179
	v_fmac_f32_e32 v171, v61, v172
	v_lshlrev_b32_e32 v172, 16, v173
	v_mul_f32_e32 v178, v184, v178
	v_fmac_f32_e32 v172, v62, v178
	v_and_b32_e32 v178, 0xffff0000, v179
	v_and_b32_e32 v173, 0xffff0000, v173
	v_mul_f32_e32 v178, v184, v178
	v_fmac_f32_e32 v173, v63, v178
	v_max_f32_e64 v178, |v170|, |v171|
	v_max_f32_e64 v179, |v172|, |v173|
	global_load_dwordx2 v[104:105], v[104:105], off nt
	v_max3_f32 v185, v178, 0, v179
	v_cvt_pk_bf16_f32 v178, v170, v171
	v_cvt_pk_bf16_f32 v179, v172, v173
	s_nop 0
	global_store_dwordx2 v[174:175], v[178:179], off offset:0 sc1 nt
	s_nop 1
	s_waitcnt vmcnt(19)
	v_lshlrev_b32_e32 v175, 16, v180
	v_lshlrev_b32_e32 v174, 16, v176
	v_mul_f32_e32 v175, v184, v175
	v_fmac_f32_e32 v174, v56, v175
	v_and_b32_e32 v175, 0xffff0000, v176
	v_and_b32_e32 v176, 0xffff0000, v180
	v_mul_f32_e32 v176, v184, v176
	v_lshlrev_b32_e32 v178, 16, v181
	v_fmac_f32_e32 v175, v57, v176
	v_lshlrev_b32_e32 v176, 16, v177
	v_mul_f32_e32 v178, v184, v178
	v_fmac_f32_e32 v176, v58, v178
	v_and_b32_e32 v178, 0xffff0000, v181
	v_and_b32_e32 v177, 0xffff0000, v177
	v_mul_f32_e32 v178, v184, v178
	v_fmac_f32_e32 v177, v59, v178
	v_max_f32_e64 v178, |v174|, |v175|
	v_max_f32_e64 v179, |v176|, |v177|
	v_max3_f32 v180, v185, v178, v179
	v_cvt_pk_bf16_f32 v178, v174, v175
	v_cvt_pk_bf16_f32 v179, v176, v177
	s_nop 0
	global_store_dwordx2 v[168:169], v[178:179], off offset:0 sc1 nt
	s_nop 1
	s_waitcnt vmcnt(18)
	v_lshlrev_b32_e32 v169, 16, v182
	v_lshlrev_b32_e32 v168, 16, v166
	v_mul_f32_e32 v169, v184, v169
	v_fmac_f32_e32 v168, v52, v169
	v_and_b32_e32 v169, 0xffff0000, v182
	v_and_b32_e32 v166, 0xffff0000, v166
	v_mul_f32_e32 v169, v184, v169
	v_lshlrev_b32_e32 v178, 16, v183
	v_fmac_f32_e32 v166, v53, v169
	v_lshlrev_b32_e32 v169, 16, v167
	v_mul_f32_e32 v178, v184, v178
	v_fmac_f32_e32 v169, v54, v178
	v_and_b32_e32 v178, 0xffff0000, v183
	v_and_b32_e32 v167, 0xffff0000, v167
	v_mul_f32_e32 v178, v184, v178
	v_fmac_f32_e32 v167, v55, v178
	v_max_f32_e64 v178, |v168|, |v166|
	v_max_f32_e64 v179, |v169|, |v167|
	v_max3_f32 v180, v180, v178, v179
	v_cvt_pk_bf16_f32 v178, v168, v166
	v_cvt_pk_bf16_f32 v179, v169, v167
	s_nop 0
	global_store_dwordx2 v[160:161], v[178:179], off offset:0 sc1 nt
	s_nop 1
	v_lshlrev_b32_e32 v161, 16, v164
	v_lshlrev_b32_e32 v160, 16, v162
	v_mul_f32_e32 v161, v184, v161
	v_fmac_f32_e32 v160, v48, v161
	v_and_b32_e32 v161, 0xffff0000, v162
	v_and_b32_e32 v162, 0xffff0000, v164
	v_mul_f32_e32 v162, v184, v162
	v_lshlrev_b32_e32 v164, 16, v165
	v_fmac_f32_e32 v161, v49, v162
	v_lshlrev_b32_e32 v162, 16, v163
	v_mul_f32_e32 v164, v184, v164
	v_fmac_f32_e32 v162, v50, v164
	v_and_b32_e32 v164, 0xffff0000, v165
	v_and_b32_e32 v163, 0xffff0000, v163
	v_mul_f32_e32 v164, v184, v164
	v_fmac_f32_e32 v163, v51, v164
	v_max_f32_e64 v164, |v160|, |v161|
	v_max_f32_e64 v165, |v162|, |v163|
	v_max3_f32 v178, v180, v164, v165
	v_cvt_pk_bf16_f32 v164, v160, v161
	v_cvt_pk_bf16_f32 v165, v162, v163
	s_nop 0
	global_store_dwordx2 v[156:157], v[164:165], off offset:0 sc1 nt
	s_nop 1
	v_lshlrev_b32_e32 v157, 16, v158
	v_lshlrev_b32_e32 v156, 16, v154
	v_mul_f32_e32 v157, v184, v157
	v_fmac_f32_e32 v156, v44, v157
	v_and_b32_e32 v157, 0xffff0000, v158
	v_and_b32_e32 v154, 0xffff0000, v154
	v_mul_f32_e32 v157, v184, v157
	v_lshlrev_b32_e32 v158, 16, v159
	v_fmac_f32_e32 v154, v45, v157
	v_lshlrev_b32_e32 v157, 16, v155
	v_mul_f32_e32 v158, v184, v158
	v_fmac_f32_e32 v157, v46, v158
	v_and_b32_e32 v158, 0xffff0000, v159
	v_and_b32_e32 v155, 0xffff0000, v155
	v_mul_f32_e32 v158, v184, v158
	v_fmac_f32_e32 v155, v47, v158
	v_max_f32_e64 v158, |v156|, |v154|
	v_max_f32_e64 v159, |v157|, |v155|
	v_max3_f32 v164, v178, v158, v159
	v_cvt_pk_bf16_f32 v158, v156, v154
	v_cvt_pk_bf16_f32 v159, v157, v155
; template <int OFF = 0, class V> __device__ __forceinline__ void st_wt16(void* p, V v) { static_assert(sizeof(V) == 16, ""); asm volatile("global_store_dwordx4 %0, %1, off offset:%2 sc1\n\ts_nop 1" :: "v"(p), "v"(v), "i"(OFF)); }
; template <int OFF = 0, class V> __device__ __forceinline__ void st_wt8(void* p, V v) { static_assert(sizeof(V) == 8, ""); asm volatile("global_store_dwordx2 %0, %1, off offset:%2 sc1\n\ts_nop 1" :: "v"(p), "v"(v), "i"(OFF)); }
; __device__ __forceinline__ unsigned pk2(float lo, float hi) { return pg8::cvt_pk_bf16(lo, hi); }
; __device__ __forceinline__ float bf_lo(unsigned w) { return __uint_as_float(w << 16); }
; __device__ __forceinline__ float bf_hi(unsigned w) { return __uint_as_float(w & 0xffff0000u); }
; __device__ __forceinline__ void resid_rows(bf16* __restrict__ XB, const bf16* __restrict__ Y, const float* __restrict__ PART, const float* __restrict__ g, float* __restrict__ RS, ...
;     ...
;         for (int j = 0; j < 16; ++j) { const int c = (lane + 64 * j) * 4;
;             f32x4 o; o.x = bf_lo(xr[j].x) + bf_lo(yr[j].x) * ry * gv[j].x; o.y = bf_hi(xr[j].x) + bf_hi(yr[j].x) * ry * gv[j].y; o.z = bf_lo(xr[j].y) + bf_lo(yr[j].y) * ry * gv[j].z; o.w = bf_hi(xr[j].y) + bf_hi(yr[j].y) * ry * gv[j].w;
;             ss += (o.x * o.x + o.y * o.y) + (o.z * o.z + o.w * o.w); ov[j] = o; am = fmaxf(fmaxf(am, fmaxf(fabsf(o.x), fabsf(o.y))), fmaxf(fabsf(o.z), fabsf(o.w)));
;             if (outf) st_wt16(outf + (size_t)m * DM + c, o); else { v2u ob; ob.x = pk2(o.x, o.y); ob.y = pk2(o.z, o.w); st_wt8(xrow + c, ob); } }
	s_nop 0
	global_store_dwordx2 v[152:153], v[158:159], off offset:0 sc1 nt
	s_nop 1
	v_lshlrev_b32_e32 v153, 16, v150
	v_lshlrev_b32_e32 v152, 16, v148
	v_mul_f32_e32 v153, v184, v153
	v_and_b32_e32 v150, 0xffff0000, v150
	v_fmac_f32_e32 v152, v40, v153
	v_and_b32_e32 v148, 0xffff0000, v148
	v_mul_f32_e32 v150, v184, v150
	v_lshlrev_b32_e32 v153, 16, v151
	v_and_b32_e32 v151, 0xffff0000, v151
	v_fmac_f32_e32 v148, v41, v150
	v_lshlrev_b32_e32 v150, 16, v149
	v_mul_f32_e32 v153, v184, v153
	v_and_b32_e32 v149, 0xffff0000, v149
	v_mul_f32_e32 v151, v184, v151
	v_fmac_f32_e32 v150, v42, v153
	v_fmac_f32_e32 v149, v43, v151
	v_cvt_pk_bf16_f32 v158, v152, v148
	v_cvt_pk_bf16_f32 v159, v150, v149
	v_max_f32_e64 v151, |v152|, |v148|
	global_store_dwordx2 v[146:147], v[158:159], off offset:0 sc1 nt
	s_nop 1
	v_lshlrev_b32_e32 v147, 16, v144
	v_lshlrev_b32_e32 v146, 16, v142
	v_mul_f32_e32 v147, v184, v147
	v_and_b32_e32 v144, 0xffff0000, v144
	v_fmac_f32_e32 v146, v36, v147
	v_and_b32_e32 v142, 0xffff0000, v142
	v_mul_f32_e32 v144, v184, v144
	v_lshlrev_b32_e32 v147, 16, v145
	v_and_b32_e32 v145, 0xffff0000, v145
	v_fmac_f32_e32 v142, v37, v144
	v_lshlrev_b32_e32 v144, 16, v143
	v_mul_f32_e32 v147, v184, v147
	v_and_b32_e32 v143, 0xffff0000, v143
	v_mul_f32_e32 v145, v184, v145
	v_fmac_f32_e32 v144, v38, v147
	v_fmac_f32_e32 v143, v39, v145
	v_cvt_pk_bf16_f32 v158, v146, v142
	v_cvt_pk_bf16_f32 v159, v144, v143
	v_max_f32_e64 v153, |v150|, |v149|
	global_store_dwordx2 v[138:139], v[158:159], off offset:0 sc1 nt
	s_nop 1
	s_waitcnt vmcnt(16)
	v_lshlrev_b32_e32 v139, 16, v140
	v_lshlrev_b32_e32 v138, 16, v136
	v_mul_f32_e32 v139, v184, v139
	v_fmac_f32_e32 v138, v32, v139
	v_and_b32_e32 v139, 0xffff0000, v140
	v_and_b32_e32 v136, 0xffff0000, v136
	v_mul_f32_e32 v139, v184, v139
	v_lshlrev_b32_e32 v140, 16, v141
	v_fmac_f32_e32 v136, v33, v139
	v_lshlrev_b32_e32 v139, 16, v137
	v_mul_f32_e32 v140, v184, v140
	v_fmac_f32_e32 v139, v34, v140
	v_and_b32_e32 v140, 0xffff0000, v141
	v_and_b32_e32 v137, 0xffff0000, v137
	v_mul_f32_e32 v140, v184, v140
	v_max3_f32 v151, v164, v151, v153
	v_max_f32_e64 v145, |v146|, |v142|
	v_max_f32_e64 v147, |v144|, |v143|
	v_fmac_f32_e32 v137, v35, v140
	v_max3_f32 v145, v151, v145, v147
	v_max_f32_e64 v140, |v138|, |v136|
	v_max_f32_e64 v141, |v139|, |v137|
	v_max3_f32 v145, v145, v140, v141
	v_cvt_pk_bf16_f32 v140, v138, v136
	v_cvt_pk_bf16_f32 v141, v139, v137
	s_nop 0
	global_store_dwordx2 v[126:127], v[140:141], off offset:0 sc1 nt
	s_nop 1
	s_waitcnt vmcnt(14)
	v_lshlrev_b32_e32 v127, 16, v132
	v_lshlrev_b32_e32 v126, 16, v130
	v_mul_f32_e32 v127, v184, v127
	v_fmac_f32_e32 v126, v28, v127
	v_and_b32_e32 v127, 0xffff0000, v130
	v_and_b32_e32 v130, 0xffff0000, v132
	v_mul_f32_e32 v130, v184, v130
	v_lshlrev_b32_e32 v132, 16, v133
	v_fmac_f32_e32 v127, v29, v130
	v_lshlrev_b32_e32 v130, 16, v131
	v_mul_f32_e32 v132, v184, v132
	v_fmac_f32_e32 v130, v30, v132
	v_and_b32_e32 v132, 0xffff0000, v133
	v_and_b32_e32 v131, 0xffff0000, v131
	v_mul_f32_e32 v132, v184, v132
	v_fmac_f32_e32 v131, v31, v132
	v_max_f32_e64 v132, |v126|, |v127|
	v_max_f32_e64 v133, |v130|, |v131|
	s_waitcnt vmcnt(12)
	v_lshlrev_b32_e32 v141, 16, v128
	v_max3_f32 v133, v145, v132, v133
	v_lshlrev_b32_e32 v132, 16, v122
	v_mul_f32_e32 v141, v184, v141
	v_and_b32_e32 v128, 0xffff0000, v128
	v_fmac_f32_e32 v132, v24, v141
	v_and_b32_e32 v122, 0xffff0000, v122
	v_mul_f32_e32 v128, v184, v128
	v_lshlrev_b32_e32 v141, 16, v129
	v_and_b32_e32 v129, 0xffff0000, v129
	v_fmac_f32_e32 v122, v25, v128
	v_lshlrev_b32_e32 v128, 16, v123
	v_mul_f32_e32 v141, v184, v141
	v_and_b32_e32 v123, 0xffff0000, v123
	v_mul_f32_e32 v129, v184, v129
	v_fmac_f32_e32 v128, v26, v141
	v_fmac_f32_e32 v123, v27, v129
	v_max_f32_e64 v129, |v132|, |v122|
	v_max_f32_e64 v141, |v128|, |v123|
	v_max3_f32 v133, v133, v129, v141
	s_waitcnt vmcnt(10)
	v_lshlrev_b32_e32 v141, 16, v116
	v_lshlrev_b32_e32 v129, 16, v114
	v_mul_f32_e32 v141, v184, v141
	v_and_b32_e32 v116, 0xffff0000, v116
	v_fmac_f32_e32 v129, v20, v141
	v_and_b32_e32 v114, 0xffff0000, v114
	v_mul_f32_e32 v116, v184, v116
	v_lshlrev_b32_e32 v141, 16, v117
	v_and_b32_e32 v117, 0xffff0000, v117
	v_fmac_f32_e32 v114, v21, v116
	v_lshlrev_b32_e32 v116, 16, v115
	v_mul_f32_e32 v141, v184, v141
	v_and_b32_e32 v115, 0xffff0000, v115
	v_mul_f32_e32 v117, v184, v117
	v_fmac_f32_e32 v116, v22, v141
	v_fmac_f32_e32 v115, v23, v117
	v_max_f32_e64 v117, |v129|, |v114|
	v_max_f32_e64 v141, |v116|, |v115|
	v_max3_f32 v141, v133, v117, v141
	s_waitcnt vmcnt(8)
	v_lshlrev_b32_e32 v133, 16, v134
	v_lshlrev_b32_e32 v117, 16, v106
	v_mul_f32_e32 v133, v184, v133
	v_fmac_f32_e32 v117, v16, v133
	v_and_b32_e32 v133, 0xffff0000, v134
	v_and_b32_e32 v106, 0xffff0000, v106
	v_mul_f32_e32 v133, v184, v133
	v_lshlrev_b32_e32 v134, 16, v135
	v_fmac_f32_e32 v106, v17, v133
	v_lshlrev_b32_e32 v133, 16, v107
	v_mul_f32_e32 v134, v184, v134
	v_fmac_f32_e32 v133, v18, v134
	v_and_b32_e32 v134, 0xffff0000, v135
	v_and_b32_e32 v107, 0xffff0000, v107
	v_mul_f32_e32 v134, v184, v134
	v_fmac_f32_e32 v107, v19, v134
	v_max_f32_e64 v134, |v117|, |v106|
	v_max_f32_e64 v135, |v133|, |v107|
	v_max3_f32 v135, v141, v134, v135
	s_waitcnt vmcnt(6)
	v_lshlrev_b32_e32 v141, 16, v120
	v_lshlrev_b32_e32 v134, 16, v118
	v_mul_f32_e32 v141, v184, v141
	v_and_b32_e32 v120, 0xffff0000, v120
	v_fmac_f32_e32 v134, v12, v141
	v_and_b32_e32 v118, 0xffff0000, v118
	v_mul_f32_e32 v120, v184, v120
	v_lshlrev_b32_e32 v141, 16, v121
	v_and_b32_e32 v121, 0xffff0000, v121
	v_fmac_f32_e32 v118, v13, v120
	v_lshlrev_b32_e32 v120, 16, v119
	v_mul_f32_e32 v141, v184, v141
	v_and_b32_e32 v119, 0xffff0000, v119
	v_mul_f32_e32 v121, v184, v121
	v_fmac_f32_e32 v120, v14, v141
	v_fmac_f32_e32 v119, v15, v121
	v_max_f32_e64 v121, |v134|, |v118|
	v_max_f32_e64 v141, |v120|, |v119|
	v_max3_f32 v135, v135, v121, v141
	s_waitcnt vmcnt(4)
; template <int O> __device__ __forceinline__ float xsw(float v) { return __int_as_float(__builtin_amdgcn_ds_swizzle(__float_as_int(v), (O << 10) | 0x1f)); }
; __device__ __forceinline__ float xmax32(float v) { auto rr = __builtin_amdgcn_permlane32_swap(__float_as_uint(v), __float_as_uint(v), false, false); return fmaxf(__uint_as_float(rr[0]), __uint_as_float(rr[1])); }
; template <int OFF = 0, class V> __device__ __forceinline__ void st_wt16(void* p, V v) { static_assert(sizeof(V) == 16, ""); asm volatile("global_store_dwordx4 %0, %1, off offset:%2 sc1\n\ts_nop 1" :: "v"(p), "v"(v), "i"(OFF)); }
; template <int OFF = 0, class V> __device__ __forceinline__ void st_wt8(void* p, V v) { static_assert(sizeof(V) == 8, ""); asm volatile("global_store_dwordx2 %0, %1, off offset:%2 sc1\n\ts_nop 1" :: "v"(p), "v"(v), "i"(OFF)); }
; __device__ __forceinline__ float wave_max(float v) {
;     v = fmaxf(v, xsw<1>(v)); v = fmaxf(v, xsw<2>(v)); v = fmaxf(v, xsw<4>(v)); v = fmaxf(v, xsw<8>(v)); v = fmaxf(v, xsw<16>(v));
;     return xmax32(v);
; }
; __device__ __forceinline__ void resid_rows(bf16* __restrict__ XB, const bf16* __restrict__ Y, const float* __restrict__ PART, const float* __restrict__ g, float* __restrict__ RS, ...
;     ...
;         for (int j = 0; j < 16; ++j) { const int c = (lane + 64 * j) * 4;
;             f32x4 o; o.x = bf_lo(xr[j].x) + bf_lo(yr[j].x) * ry * gv[j].x; o.y = bf_hi(xr[j].x) + bf_hi(yr[j].x) * ry * gv[j].y; o.z = bf_lo(xr[j].y) + bf_lo(yr[j].y) * ry * gv[j].z; o.w = bf_hi(xr[j].y) + bf_hi(yr[j].y) * ry * gv[j].w;
;             ss += (o.x * o.x + o.y * o.y) + (o.z * o.z + o.w * o.w); ov[j] = o; am = fmaxf(fmaxf(am, fmaxf(fabsf(o.x), fabsf(o.y))), fmaxf(fabsf(o.z), fabsf(o.w)));
;             if (outf) st_wt16(outf + (size_t)m * DM + c, o); else { v2u ob; ob.x = pk2(o.x, o.y); ob.y = pk2(o.z, o.w); st_wt8(xrow + c, ob); } }
;         if (XQ) {
;             am = fmaxf(wave_max(am), 1e-20f); const float qs = 127.0f / am;
; #pragma unroll
;             for (int j = 0; j < 16; ++j) { const int q0 = (int)rintf(ov[j].x * qs), q1 = (int)rintf(ov[j].y * qs), q2 = (int)rintf(ov[j].z * qs), q3 = (int)rintf(ov[j].w * qs);
;                 st_wt4(XQ + (size_t)m * (DM / 4) + lane + 64 * j, ((unsigned)q0 & 255u) | (((unsigned)q1 & 255u) << 8) | (((unsigned)q2 & 255u) << 16) | ((unsigned)q3 << 24)); }
	v_lshlrev_b32_e32 v141, 16, v124
	v_lshlrev_b32_e32 v121, 16, v108
	v_mul_f32_e32 v141, v184, v141
	v_and_b32_e32 v124, 0xffff0000, v124
	v_fmac_f32_e32 v121, v8, v141
	v_and_b32_e32 v108, 0xffff0000, v108
	v_mul_f32_e32 v124, v184, v124
	v_lshlrev_b32_e32 v141, 16, v125
	v_and_b32_e32 v125, 0xffff0000, v125
	v_fmac_f32_e32 v108, v9, v124
	v_lshlrev_b32_e32 v124, 16, v109
	v_mul_f32_e32 v141, v184, v141
	v_and_b32_e32 v109, 0xffff0000, v109
	v_mul_f32_e32 v125, v184, v125
	v_fmac_f32_e32 v124, v10, v141
	v_fmac_f32_e32 v109, v11, v125
	v_max_f32_e64 v125, |v121|, |v108|
	v_max_f32_e64 v141, |v124|, |v109|
	v_max3_f32 v135, v135, v125, v141
	s_waitcnt vmcnt(2)
	v_lshlrev_b32_e32 v141, 16, v112
	v_lshlrev_b32_e32 v125, 16, v110
	v_mul_f32_e32 v141, v184, v141
	v_and_b32_e32 v112, 0xffff0000, v112
	v_fmac_f32_e32 v125, v4, v141
	v_and_b32_e32 v110, 0xffff0000, v110
	v_mul_f32_e32 v112, v184, v112
	v_lshlrev_b32_e32 v141, 16, v113
	v_and_b32_e32 v113, 0xffff0000, v113
	v_fmac_f32_e32 v110, v5, v112
	v_lshlrev_b32_e32 v112, 16, v111
	v_mul_f32_e32 v141, v184, v141
	v_and_b32_e32 v111, 0xffff0000, v111
	v_mul_f32_e32 v113, v184, v113
	v_fmac_f32_e32 v112, v6, v141
	v_fmac_f32_e32 v111, v7, v113
	v_max_f32_e64 v113, |v125|, |v110|
	v_max_f32_e64 v141, |v112|, |v111|
	v_max3_f32 v135, v135, v113, v141
	s_waitcnt vmcnt(0)
	v_lshlrev_b32_e32 v141, 16, v104
	v_lshlrev_b32_e32 v113, 16, v102
	v_mul_f32_e32 v141, v184, v141
	v_and_b32_e32 v104, 0xffff0000, v104
	v_fmac_f32_e32 v113, v0, v141
	v_and_b32_e32 v102, 0xffff0000, v102
	v_mul_f32_e32 v104, v184, v104
	v_lshlrev_b32_e32 v141, 16, v105
	v_and_b32_e32 v105, 0xffff0000, v105
	v_fmac_f32_e32 v102, v1, v104
	v_lshlrev_b32_e32 v104, 16, v103
	v_mul_f32_e32 v141, v184, v141
	v_and_b32_e32 v103, 0xffff0000, v103
	v_mul_f32_e32 v105, v184, v105
	v_fmac_f32_e32 v104, v2, v141
	v_fmac_f32_e32 v103, v3, v105
	v_max_f32_e64 v105, |v113|, |v102|
	v_max_f32_e64 v141, |v104|, |v103|
	v_max3_f32 v105, v135, v105, v141
	ds_swizzle_b32 v135, v105 offset:swizzle(SWAP,1)
	v_cvt_pk_bf16_f32 v140, v126, v127
	v_cvt_pk_bf16_f32 v141, v130, v131
	s_waitcnt lgkmcnt(0)
	v_max_f32_e32 v135, v135, v135
	v_max_f32_e32 v105, v105, v135
	ds_swizzle_b32 v135, v105 offset:swizzle(SWAP,2)
	global_store_dwordx2 v[86:87], v[140:141], off offset:0 sc1 nt
	s_nop 1
	v_cvt_pk_bf16_f32 v86, v132, v122
	v_cvt_pk_bf16_f32 v87, v128, v123
	s_nop 0
	global_store_dwordx2 v[88:89], v[86:87], off offset:0 sc1 nt
	s_nop 1
	v_cvt_pk_bf16_f32 v86, v129, v114
	v_cvt_pk_bf16_f32 v87, v116, v115
	s_nop 0
	global_store_dwordx2 v[90:91], v[86:87], off offset:0 sc1 nt
	s_nop 1
	s_waitcnt lgkmcnt(0)
	v_max_f32_e32 v86, v135, v135
	v_max_f32_e32 v88, v105, v86
	ds_swizzle_b32 v89, v88 offset:swizzle(SWAP,4)
	v_cvt_pk_bf16_f32 v86, v117, v106
	v_cvt_pk_bf16_f32 v87, v133, v107
	s_nop 0
	global_store_dwordx2 v[92:93], v[86:87], off offset:0 sc1 nt
	s_nop 1
	s_waitcnt lgkmcnt(0)
	v_max_f32_e32 v87, v89, v89
	v_max_f32_e32 v88, v88, v87
	ds_swizzle_b32 v89, v88 offset:swizzle(SWAP,8)
	v_cvt_pk_bf16_f32 v86, v134, v118
	v_cvt_pk_bf16_f32 v87, v120, v119
	s_waitcnt lgkmcnt(0)
	v_max_f32_e32 v89, v89, v89
	v_max_f32_e32 v88, v88, v89
	ds_swizzle_b32 v89, v88 offset:swizzle(SWAP,16)
	global_store_dwordx2 v[94:95], v[86:87], off offset:0 sc1 nt
	s_nop 1
	v_cvt_pk_bf16_f32 v86, v121, v108
	v_cvt_pk_bf16_f32 v87, v124, v109
	s_nop 0
	global_store_dwordx2 v[96:97], v[86:87], off offset:0 sc1 nt
	s_nop 1
	v_cvt_pk_bf16_f32 v86, v125, v110
	v_cvt_pk_bf16_f32 v87, v112, v111
	s_nop 0
	global_store_dwordx2 v[100:101], v[86:87], off offset:0 sc1 nt
	s_nop 1
	s_waitcnt lgkmcnt(0)
	v_max_f32_e32 v86, v89, v89
	v_max_f32_e32 v86, v88, v86
	v_mov_b32_e32 v87, v86
	s_nop 1
	v_permlane32_swap_b32_e32 v86, v87
	v_max3_f32 v88, v86, v87, s0
	v_div_scale_f32 v89, s[0:1], v88, v88, s4
	v_rcp_f32_e32 v90, v89
	v_cvt_pk_bf16_f32 v86, v113, v102
	v_cvt_pk_bf16_f32 v87, v104, v103
	s_mov_b32 s0, 0x40c0c00
	global_store_dwordx2 v[98:99], v[86:87], off offset:0 sc1 nt
	s_nop 1
	v_fma_f32 v86, -v89, v90, 1.0
	v_fmac_f32_e32 v90, v86, v90
	v_div_scale_f32 v86, vcc, s4, v88, s4
	v_mul_f32_e32 v87, v86, v90
	v_fma_f32 v91, -v89, v87, v86
	v_fmac_f32_e32 v87, v91, v90
	v_fma_f32 v86, -v89, v87, v86
	v_div_fmas_f32 v86, v86, v90, v87
	v_div_fixup_f32 v89, v86, v88, s4
	v_mul_f32_e32 v91, v171, v89
	v_mul_f32_e32 v90, v170, v89
	v_rndne_f32_e32 v91, v91
	v_mul_f32_e32 v92, v172, v89
	v_mul_f32_e32 v93, v173, v89
	v_rndne_f32_e32 v90, v90
	v_cvt_i32_f32_e32 v91, v91
	v_rndne_f32_e32 v92, v92
	v_rndne_f32_e32 v93, v93
	v_cvt_i32_f32_e32 v90, v90
	v_cvt_i32_f32_sdwa v92, v92 dst_sel:WORD_1 dst_unused:UNUSED_PAD src0_sel:DWORD
	v_cvt_i32_f32_e32 v93, v93
	v_lshlrev_b32_e32 v91, 8, v91
	v_and_b32_e32 v91, 0xff00, v91
	v_and_b32_e32 v92, 0xff0000, v92
	v_perm_b32 v90, v93, v90, s0
	v_or3_b32 v90, v90, v91, v92
	v_lshl_add_u64 v[86:87], s[18:19], 0, v[82:83]
	global_store_dword v[86:87], v90, off sc1
	s_nop 1
	v_mul_f32_e32 v90, v174, v89
	v_rndne_f32_e32 v90, v90
	v_cvt_i32_f32_e32 v92, v90
	v_mul_f32_e32 v90, v175, v89
	v_rndne_f32_e32 v90, v90
	v_cvt_i32_f32_e32 v93, v90
	v_mul_f32_e32 v90, v176, v89
	v_rndne_f32_e32 v90, v90
	v_cvt_i32_f32_sdwa v94, v90 dst_sel:WORD_1 dst_unused:UNUSED_PAD src0_sel:DWORD
	v_mul_f32_e32 v90, v177, v89
	v_rndne_f32_e32 v90, v90
	v_cvt_i32_f32_e32 v95, v90
	s_mov_b64 s[4:5], 0x100
	v_lshlrev_b32_e32 v93, 8, v93
	v_lshl_add_u64 v[90:91], v[86:87], 0, s[4:5]
	v_and_b32_e32 v93, 0xff00, v93
	v_and_b32_e32 v94, 0xff0000, v94
	v_perm_b32 v92, v95, v92, s0
	v_or3_b32 v92, v92, v93, v94
	global_store_dword v[90:91], v92, off sc1
	s_nop 1
	v_mul_f32_e32 v90, v168, v89
; __device__ __forceinline__ void st_wt4(void* p, unsigned v) { asm volatile("global_store_dword %0, %1, off sc1\n\ts_nop 1" :: "v"(p), "v"(v)); }
; __device__ __forceinline__ void resid_rows(bf16* __restrict__ XB, const bf16* __restrict__ Y, const float* __restrict__ PART, const float* __restrict__ g, float* __restrict__ RS, ...
;     ...
; #pragma unroll
;             for (int j = 0; j < 16; ++j) { const int q0 = (int)rintf(ov[j].x * qs), q1 = (int)rintf(ov[j].y * qs), q2 = (int)rintf(ov[j].z * qs), q3 = (int)rintf(ov[j].w * qs);
;                 st_wt4(XQ + (size_t)m * (DM / 4) + lane + 64 * j, ((unsigned)q0 & 255u) | (((unsigned)q1 & 255u) << 8) | (((unsigned)q2 & 255u) << 16) | ((unsigned)q3 << 24)); }
	v_rndne_f32_e32 v90, v90
	v_cvt_i32_f32_e32 v92, v90
	v_mul_f32_e32 v90, v166, v89
	v_rndne_f32_e32 v90, v90
	v_cvt_i32_f32_e32 v93, v90
	v_mul_f32_e32 v90, v169, v89
	v_rndne_f32_e32 v90, v90
	v_cvt_i32_f32_sdwa v94, v90 dst_sel:WORD_1 dst_unused:UNUSED_PAD src0_sel:DWORD
	v_mul_f32_e32 v90, v167, v89
	v_rndne_f32_e32 v90, v90
	v_cvt_i32_f32_e32 v95, v90
	s_mov_b64 s[4:5], 0x200
	v_lshlrev_b32_e32 v93, 8, v93
	v_lshl_add_u64 v[90:91], v[86:87], 0, s[4:5]
	v_and_b32_e32 v93, 0xff00, v93
	v_and_b32_e32 v94, 0xff0000, v94
	v_perm_b32 v92, v95, v92, s0
	v_or3_b32 v92, v92, v93, v94
	global_store_dword v[90:91], v92, off sc1
	s_nop 1
	v_mul_f32_e32 v90, v160, v89
	v_rndne_f32_e32 v90, v90
	v_cvt_i32_f32_e32 v92, v90
	v_mul_f32_e32 v90, v161, v89
	v_rndne_f32_e32 v90, v90
	v_cvt_i32_f32_e32 v93, v90
	v_mul_f32_e32 v90, v162, v89
	v_rndne_f32_e32 v90, v90
	v_cvt_i32_f32_sdwa v94, v90 dst_sel:WORD_1 dst_unused:UNUSED_PAD src0_sel:DWORD
	v_mul_f32_e32 v90, v163, v89
	v_rndne_f32_e32 v90, v90
	v_cvt_i32_f32_e32 v95, v90
	s_mov_b64 s[4:5], 0x300
	v_lshlrev_b32_e32 v93, 8, v93
	v_lshl_add_u64 v[90:91], v[86:87], 0, s[4:5]
	v_and_b32_e32 v93, 0xff00, v93
	v_and_b32_e32 v94, 0xff0000, v94
	v_perm_b32 v92, v95, v92, s0
	v_or3_b32 v92, v92, v93, v94
	global_store_dword v[90:91], v92, off sc1
	s_nop 1
	v_mul_f32_e32 v90, v156, v89
	v_rndne_f32_e32 v90, v90
	v_cvt_i32_f32_e32 v92, v90
	v_mul_f32_e32 v90, v154, v89
	v_rndne_f32_e32 v90, v90
	v_cvt_i32_f32_e32 v93, v90
	v_mul_f32_e32 v90, v157, v89
	v_rndne_f32_e32 v90, v90
	v_cvt_i32_f32_sdwa v94, v90 dst_sel:WORD_1 dst_unused:UNUSED_PAD src0_sel:DWORD
	v_mul_f32_e32 v90, v155, v89
	v_rndne_f32_e32 v90, v90
	v_cvt_i32_f32_e32 v95, v90
	s_mov_b64 s[4:5], 0x400
	v_lshlrev_b32_e32 v93, 8, v93
	v_lshl_add_u64 v[90:91], v[86:87], 0, s[4:5]
	v_and_b32_e32 v93, 0xff00, v93
	v_and_b32_e32 v94, 0xff0000, v94
	v_perm_b32 v92, v95, v92, s0
	v_or3_b32 v92, v92, v93, v94
	global_store_dword v[90:91], v92, off sc1
	s_nop 1
	v_mul_f32_e32 v90, v152, v89
	v_rndne_f32_e32 v90, v90
	v_cvt_i32_f32_e32 v92, v90
	v_mul_f32_e32 v90, v148, v89
	v_rndne_f32_e32 v90, v90
	v_cvt_i32_f32_e32 v93, v90
	v_mul_f32_e32 v90, v150, v89
	v_rndne_f32_e32 v90, v90
	v_cvt_i32_f32_sdwa v94, v90 dst_sel:WORD_1 dst_unused:UNUSED_PAD src0_sel:DWORD
	v_mul_f32_e32 v90, v149, v89
	v_rndne_f32_e32 v90, v90
	v_cvt_i32_f32_e32 v95, v90
	s_mov_b64 s[4:5], 0x500
	v_lshlrev_b32_e32 v93, 8, v93
	v_lshl_add_u64 v[90:91], v[86:87], 0, s[4:5]
	v_and_b32_e32 v93, 0xff00, v93
	v_and_b32_e32 v94, 0xff0000, v94
	v_perm_b32 v92, v95, v92, s0
	v_or3_b32 v92, v92, v93, v94
	global_store_dword v[90:91], v92, off sc1
	s_nop 1
	v_mul_f32_e32 v90, v146, v89
	v_rndne_f32_e32 v90, v90
	v_cvt_i32_f32_e32 v92, v90
	v_mul_f32_e32 v90, v142, v89
	v_rndne_f32_e32 v90, v90
	v_cvt_i32_f32_e32 v93, v90
	v_mul_f32_e32 v90, v144, v89
	v_rndne_f32_e32 v90, v90
	v_cvt_i32_f32_sdwa v94, v90 dst_sel:WORD_1 dst_unused:UNUSED_PAD src0_sel:DWORD
	v_mul_f32_e32 v90, v143, v89
	v_rndne_f32_e32 v90, v90
	v_cvt_i32_f32_e32 v95, v90
	s_mov_b64 s[4:5], 0x600
	v_lshlrev_b32_e32 v93, 8, v93
	v_lshl_add_u64 v[90:91], v[86:87], 0, s[4:5]
	v_and_b32_e32 v93, 0xff00, v93
	v_and_b32_e32 v94, 0xff0000, v94
	v_perm_b32 v92, v95, v92, s0
	v_or3_b32 v92, v92, v93, v94
	global_store_dword v[90:91], v92, off sc1
	s_nop 1
	v_mul_f32_e32 v90, v138, v89
	v_rndne_f32_e32 v90, v90
	v_cvt_i32_f32_e32 v92, v90
	v_mul_f32_e32 v90, v136, v89
	v_rndne_f32_e32 v90, v90
	v_cvt_i32_f32_e32 v93, v90
	v_mul_f32_e32 v90, v139, v89
	v_rndne_f32_e32 v90, v90
	v_cvt_i32_f32_sdwa v94, v90 dst_sel:WORD_1 dst_unused:UNUSED_PAD src0_sel:DWORD
	v_mul_f32_e32 v90, v137, v89
	v_rndne_f32_e32 v90, v90
	v_cvt_i32_f32_e32 v95, v90
	s_mov_b64 s[4:5], 0x700
	v_lshlrev_b32_e32 v93, 8, v93
	v_lshl_add_u64 v[90:91], v[86:87], 0, s[4:5]
	v_and_b32_e32 v93, 0xff00, v93
	v_and_b32_e32 v94, 0xff0000, v94
	v_perm_b32 v92, v95, v92, s0
	v_or3_b32 v92, v92, v93, v94
	global_store_dword v[90:91], v92, off sc1
	s_nop 1
	v_mul_f32_e32 v90, v126, v89
	v_rndne_f32_e32 v90, v90
	v_cvt_i32_f32_e32 v92, v90
	v_mul_f32_e32 v90, v127, v89
	v_rndne_f32_e32 v90, v90
	v_cvt_i32_f32_e32 v93, v90
	v_mul_f32_e32 v90, v130, v89
	v_rndne_f32_e32 v90, v90
	v_cvt_i32_f32_sdwa v94, v90 dst_sel:WORD_1 dst_unused:UNUSED_PAD src0_sel:DWORD
	v_mul_f32_e32 v90, v131, v89
	v_rndne_f32_e32 v90, v90
	v_cvt_i32_f32_e32 v95, v90
	s_mov_b64 s[4:5], 0x800
	v_lshlrev_b32_e32 v93, 8, v93
	v_lshl_add_u64 v[90:91], v[86:87], 0, s[4:5]
	v_and_b32_e32 v93, 0xff00, v93
	v_and_b32_e32 v94, 0xff0000, v94
	v_perm_b32 v92, v95, v92, s0
	v_or3_b32 v92, v92, v93, v94
	global_store_dword v[90:91], v92, off sc1
	s_nop 1
	v_mul_f32_e32 v90, v132, v89
	v_rndne_f32_e32 v90, v90
	v_cvt_i32_f32_e32 v92, v90
	v_mul_f32_e32 v90, v122, v89
; __device__ __forceinline__ void st_wt4(void* p, unsigned v) { asm volatile("global_store_dword %0, %1, off sc1\n\ts_nop 1" :: "v"(p), "v"(v)); }
; __device__ __forceinline__ void resid_rows(bf16* __restrict__ XB, const bf16* __restrict__ Y, const float* __restrict__ PART, const float* __restrict__ g, float* __restrict__ RS, ...
;     ...
; #pragma unroll
;             for (int j = 0; j < 16; ++j) { const int q0 = (int)rintf(ov[j].x * qs), q1 = (int)rintf(ov[j].y * qs), q2 = (int)rintf(ov[j].z * qs), q3 = (int)rintf(ov[j].w * qs);
;                 st_wt4(XQ + (size_t)m * (DM / 4) + lane + 64 * j, ((unsigned)q0 & 255u) | (((unsigned)q1 & 255u) << 8) | (((unsigned)q2 & 255u) << 16) | ((unsigned)q3 << 24)); }
;             if (lane == 0) AS[m] = am * (1.0f / 127.0f); }
	v_rndne_f32_e32 v90, v90
	v_cvt_i32_f32_e32 v93, v90
	v_mul_f32_e32 v90, v128, v89
	v_rndne_f32_e32 v90, v90
	v_cvt_i32_f32_sdwa v94, v90 dst_sel:WORD_1 dst_unused:UNUSED_PAD src0_sel:DWORD
	v_mul_f32_e32 v90, v123, v89
	v_rndne_f32_e32 v90, v90
	v_cvt_i32_f32_e32 v95, v90
	s_mov_b64 s[4:5], 0x900
	v_lshlrev_b32_e32 v93, 8, v93
	v_lshl_add_u64 v[90:91], v[86:87], 0, s[4:5]
	v_and_b32_e32 v93, 0xff00, v93
	v_and_b32_e32 v94, 0xff0000, v94
	v_perm_b32 v92, v95, v92, s0
	v_or3_b32 v92, v92, v93, v94
	global_store_dword v[90:91], v92, off sc1
	s_nop 1
	v_mul_f32_e32 v90, v129, v89
	v_rndne_f32_e32 v90, v90
	v_cvt_i32_f32_e32 v92, v90
	v_mul_f32_e32 v90, v114, v89
	v_rndne_f32_e32 v90, v90
	v_cvt_i32_f32_e32 v93, v90
	v_mul_f32_e32 v90, v116, v89
	v_rndne_f32_e32 v90, v90
	v_cvt_i32_f32_sdwa v94, v90 dst_sel:WORD_1 dst_unused:UNUSED_PAD src0_sel:DWORD
	v_mul_f32_e32 v90, v115, v89
	v_rndne_f32_e32 v90, v90
	v_cvt_i32_f32_e32 v95, v90
	s_mov_b64 s[4:5], 0xa00
	v_lshlrev_b32_e32 v93, 8, v93
	v_lshl_add_u64 v[90:91], v[86:87], 0, s[4:5]
	v_and_b32_e32 v93, 0xff00, v93
	v_and_b32_e32 v94, 0xff0000, v94
	v_perm_b32 v92, v95, v92, s0
	v_or3_b32 v92, v92, v93, v94
	global_store_dword v[90:91], v92, off sc1
	s_nop 1
	v_mul_f32_e32 v90, v117, v89
	v_rndne_f32_e32 v90, v90
	v_cvt_i32_f32_e32 v92, v90
	v_mul_f32_e32 v90, v106, v89
	v_rndne_f32_e32 v90, v90
	v_cvt_i32_f32_e32 v93, v90
	v_mul_f32_e32 v90, v133, v89
	v_rndne_f32_e32 v90, v90
	v_cvt_i32_f32_sdwa v94, v90 dst_sel:WORD_1 dst_unused:UNUSED_PAD src0_sel:DWORD
	v_mul_f32_e32 v90, v107, v89
	v_rndne_f32_e32 v90, v90
	v_cvt_i32_f32_e32 v95, v90
	s_mov_b64 s[4:5], 0xb00
	v_lshlrev_b32_e32 v93, 8, v93
	v_lshl_add_u64 v[90:91], v[86:87], 0, s[4:5]
	v_and_b32_e32 v93, 0xff00, v93
	v_and_b32_e32 v94, 0xff0000, v94
	v_perm_b32 v92, v95, v92, s0
	v_or3_b32 v92, v92, v93, v94
	global_store_dword v[90:91], v92, off sc1
	s_nop 1
	v_mul_f32_e32 v90, v134, v89
	v_rndne_f32_e32 v90, v90
	v_cvt_i32_f32_e32 v92, v90
	v_mul_f32_e32 v90, v118, v89
	v_rndne_f32_e32 v90, v90
	v_cvt_i32_f32_e32 v93, v90
	v_mul_f32_e32 v90, v120, v89
	v_rndne_f32_e32 v90, v90
	v_cvt_i32_f32_sdwa v94, v90 dst_sel:WORD_1 dst_unused:UNUSED_PAD src0_sel:DWORD
	v_mul_f32_e32 v90, v119, v89
	v_rndne_f32_e32 v90, v90
	v_cvt_i32_f32_e32 v95, v90
	s_mov_b64 s[4:5], 0xc00
	v_lshlrev_b32_e32 v93, 8, v93
	v_lshl_add_u64 v[90:91], v[86:87], 0, s[4:5]
	v_and_b32_e32 v93, 0xff00, v93
	v_and_b32_e32 v94, 0xff0000, v94
	v_perm_b32 v92, v95, v92, s0
	v_or3_b32 v92, v92, v93, v94
	global_store_dword v[90:91], v92, off sc1
	s_nop 1
	v_mul_f32_e32 v90, v121, v89
	v_rndne_f32_e32 v90, v90
	v_cvt_i32_f32_e32 v92, v90
	v_mul_f32_e32 v90, v108, v89
	v_rndne_f32_e32 v90, v90
	v_cvt_i32_f32_e32 v93, v90
	v_mul_f32_e32 v90, v124, v89
	v_rndne_f32_e32 v90, v90
	v_cvt_i32_f32_sdwa v94, v90 dst_sel:WORD_1 dst_unused:UNUSED_PAD src0_sel:DWORD
	v_mul_f32_e32 v90, v109, v89
	v_rndne_f32_e32 v90, v90
	v_cvt_i32_f32_e32 v95, v90
	s_mov_b64 s[4:5], 0xd00
	v_lshlrev_b32_e32 v93, 8, v93
	v_lshl_add_u64 v[90:91], v[86:87], 0, s[4:5]
	v_and_b32_e32 v93, 0xff00, v93
	v_and_b32_e32 v94, 0xff0000, v94
	v_perm_b32 v92, v95, v92, s0
	v_or3_b32 v92, v92, v93, v94
	global_store_dword v[90:91], v92, off sc1
	s_nop 1
	v_mul_f32_e32 v90, v125, v89
	v_rndne_f32_e32 v90, v90
	v_cvt_i32_f32_e32 v92, v90
	v_mul_f32_e32 v90, v110, v89
	v_rndne_f32_e32 v90, v90
	v_cvt_i32_f32_e32 v93, v90
	v_mul_f32_e32 v90, v112, v89
	v_rndne_f32_e32 v90, v90
	v_cvt_i32_f32_sdwa v94, v90 dst_sel:WORD_1 dst_unused:UNUSED_PAD src0_sel:DWORD
	v_mul_f32_e32 v90, v111, v89
	v_rndne_f32_e32 v90, v90
	v_cvt_i32_f32_e32 v95, v90
	s_mov_b64 s[4:5], 0xe00
	v_lshlrev_b32_e32 v93, 8, v93
	v_lshl_add_u64 v[90:91], v[86:87], 0, s[4:5]
	v_and_b32_e32 v93, 0xff00, v93
	v_and_b32_e32 v94, 0xff0000, v94
	v_perm_b32 v92, v95, v92, s0
	v_or3_b32 v92, v92, v93, v94
	global_store_dword v[90:91], v92, off sc1
	s_nop 1
	v_mul_f32_e32 v91, v102, v89
	v_mul_f32_e32 v90, v113, v89
	v_rndne_f32_e32 v91, v91
	v_mul_f32_e32 v92, v104, v89
	v_mul_f32_e32 v89, v103, v89
	v_rndne_f32_e32 v90, v90
	v_cvt_i32_f32_e32 v91, v91
	v_rndne_f32_e32 v92, v92
	v_rndne_f32_e32 v89, v89
	v_cvt_i32_f32_e32 v90, v90
	v_cvt_i32_f32_sdwa v92, v92 dst_sel:WORD_1 dst_unused:UNUSED_PAD src0_sel:DWORD
	v_cvt_i32_f32_e32 v89, v89
	v_lshlrev_b32_e32 v91, 8, v91
	s_mov_b64 s[4:5], 0xf00
	v_and_b32_e32 v91, 0xff00, v91
	v_and_b32_e32 v92, 0xff0000, v92
	v_perm_b32 v89, v89, v90, s0
	v_lshl_add_u64 v[86:87], v[86:87], 0, s[4:5]
	v_or3_b32 v89, v89, v91, v92
	global_store_dword v[86:87], v89, off sc1
	s_nop 1
	s_and_saveexec_b64 s[4:5], s[2:3]
	s_cbranch_execz .LBB0_816
	s_add_u32 s0, s18, s22
	v_mul_f32_e32 v86, 0x3c010204, v88
	s_addc_u32 s1, s19, s23
	v_mov_b32_e32 v87, 0x110000
	global_store_dword v87, v86, s[0:1]

; template <int OFF = 0, class V> __device__ __forceinline__ void st_wt16(void* p, V v) { static_assert(sizeof(V) == 16, ""); asm volatile("global_store_dwordx4 %0, %1, off offset:%2 sc1\n\ts_nop 1" :: "v"(p), "v"(v), "i"(OFF)); }
; template <int OFF = 0, class V> __device__ __forceinline__ void st_wt8(void* p, V v) { static_assert(sizeof(V) == 8, ""); asm volatile("global_store_dwordx2 %0, %1, off offset:%2 sc1\n\ts_nop 1" :: "v"(p), "v"(v), "i"(OFF)); }
; __device__ __forceinline__ unsigned pk2(float lo, float hi) { return pg8::cvt_pk_bf16(lo, hi); }
; __device__ __forceinline__ float bf_lo(unsigned w) { return __uint_as_float(w << 16); }
; __device__ __forceinline__ float bf_hi(unsigned w) { return __uint_as_float(w & 0xffff0000u); }
; __device__ __forceinline__ void resid_rows(bf16* __restrict__ XB, const bf16* __restrict__ Y, const float* __restrict__ PART, const float* __restrict__ g, float* __restrict__ RS, ...
;     ...
;     for (int m = gw; m < MTOK; m += NGW) {
;         const float pv = PART[(size_t)m * 64 + lane];
;         bf16* xrow = XB + (size_t)m * DM; const bf16* yrow = Y + (size_t)m * DM;
;         v2u xr[16], yr[16];
; #pragma unroll
;         for (int j = 0; j < 16; ++j) { xr[j] = *(const v2u*)(xrow + (lane + 64 * j) * 4); yr[j] = *(const v2u*)(yrow + (lane + 64 * j) * 4); }
;         const float ry = 1.0f / sqrtf(wave_sum(pv) * (1.0f / DM) + EPS);
;         float ss = 0.f, am = 0.f; f32x4 ov[16];
; #pragma unroll
;         for (int j = 0; j < 16; ++j) { const int c = (lane + 64 * j) * 4;
;             f32x4 o; o.x = bf_lo(xr[j].x) + bf_lo(yr[j].x) * ry * gv[j].x; o.y = bf_hi(xr[j].x) + bf_hi(yr[j].x) * ry * gv[j].y; o.z = bf_lo(xr[j].y) + bf_lo(yr[j].y) * ry * gv[j].z; o.w = bf_hi(xr[j].y) + bf_hi(yr[j].y) * ry * gv[j].w;
;             ss += (o.x * o.x + o.y * o.y) + (o.z * o.z + o.w * o.w); ov[j] = o; am = fmaxf(fmaxf(am, fmaxf(fabsf(o.x), fabsf(o.y))), fmaxf(fabsf(o.z), fabsf(o.w)));
;             if (outf) st_wt16(outf + (size_t)m * DM + c, o); else { v2u ob; ob.x = pk2(o.x, o.y); ob.y = pk2(o.z, o.w); st_wt8(xrow + c, ob); } }
.LBB0_1057:
	v_lshl_add_u64 v[96:97], s[8:9], 0, v[154:155]
	v_add_co_u32_e32 v66, vcc, s12, v96
	v_lshl_add_u64 v[64:65], s[8:9], 0, v[174:175]
	s_nop 0
	v_addc_co_u32_e32 v67, vcc, 0, v97, vcc
	v_add_co_u32_e32 v68, vcc, s15, v96
	v_lshl_add_u64 v[100:101], s[8:9], 0, v[156:157]
	s_nop 0
	v_addc_co_u32_e32 v69, vcc, 0, v97, vcc
	global_load_dword v178, v[64:65], off
	global_load_dwordx2 v[198:199], v[66:67], off nt
	global_load_dwordx2 v[70:71], v[66:67], off offset:512 nt
	global_load_dwordx2 v[74:75], v[66:67], off offset:1024 nt
	global_load_dwordx2 v[78:79], v[66:67], off offset:1536 nt
	global_load_dwordx2 v[82:83], v[66:67], off offset:2048 nt
	global_load_dwordx2 v[86:87], v[66:67], off offset:2560 nt
	global_load_dwordx2 v[90:91], v[66:67], off offset:3072 nt
	global_load_dwordx2 v[80:81], v[68:69], off offset:1536 nt
	global_load_dwordx2 v[84:85], v[68:69], off offset:2048 nt
	global_load_dwordx2 v[88:89], v[68:69], off offset:2560 nt
	global_load_dwordx2 v[92:93], v[68:69], off offset:3072 nt
	global_load_dwordx2 v[202:203], v[68:69], off nt
	global_load_dwordx2 v[72:73], v[68:69], off offset:512 nt
	global_load_dwordx2 v[76:77], v[68:69], off offset:1024 nt
	global_load_dwordx2 v[94:95], v[66:67], off offset:3584 nt
	v_add_co_u32_e32 v64, vcc, s12, v100
	v_lshl_add_u64 v[104:105], s[8:9], 0, v[158:159]
	s_nop 0
	v_addc_co_u32_e32 v65, vcc, 0, v101, vcc
	v_add_co_u32_e32 v66, vcc, s15, v100
	v_lshl_add_u64 v[108:109], s[8:9], 0, v[160:161]
	s_nop 0
	v_addc_co_u32_e32 v67, vcc, 0, v101, vcc
	v_add_co_u32_e32 v102, vcc, s12, v104
	v_lshl_add_u64 v[112:113], s[8:9], 0, v[162:163]
	s_nop 0
	v_addc_co_u32_e32 v103, vcc, 0, v105, vcc
	global_load_dwordx2 v[196:197], v[68:69], off offset:3584 nt
	global_load_dwordx2 v[194:195], v[64:65], off nt
	global_load_dwordx2 v[98:99], v[66:67], off nt
	s_nop 0
	global_load_dwordx2 v[102:103], v[102:103], off nt
	v_add_co_u32_e32 v64, vcc, s15, v104
	v_lshl_add_u64 v[116:117], s[8:9], 0, v[164:165]
	s_nop 0
	v_addc_co_u32_e32 v65, vcc, 0, v105, vcc
	v_add_co_u32_e32 v66, vcc, s12, v108
	v_lshl_add_u64 v[120:121], s[8:9], 0, v[166:167]
	s_nop 0
	v_addc_co_u32_e32 v67, vcc, 0, v109, vcc
	v_add_co_u32_e32 v68, vcc, s15, v108
	v_lshl_add_u64 v[124:125], s[8:9], 0, v[168:169]
	s_nop 0
	v_addc_co_u32_e32 v69, vcc, 0, v109, vcc
	v_add_co_u32_e32 v110, vcc, s12, v112
	v_lshl_add_u64 v[176:177], s[8:9], 0, v[170:171]
	s_nop 0
	v_addc_co_u32_e32 v111, vcc, 0, v113, vcc
	global_load_dwordx2 v[192:193], v[64:65], off nt
	global_load_dwordx2 v[190:191], v[66:67], off nt
	global_load_dwordx2 v[106:107], v[68:69], off nt
	s_nop 0
	global_load_dwordx2 v[110:111], v[110:111], off nt
	v_add_co_u32_e32 v64, vcc, s15, v112
	s_mov_b32 s4, 0xf800000
	s_nop 0
	v_addc_co_u32_e32 v65, vcc, 0, v113, vcc
	v_add_co_u32_e32 v66, vcc, s12, v116
	s_nop 1
	v_addc_co_u32_e32 v67, vcc, 0, v117, vcc
	v_add_co_u32_e32 v68, vcc, s15, v116
	s_nop 1
	v_addc_co_u32_e32 v69, vcc, 0, v117, vcc
	v_add_co_u32_e32 v118, vcc, s12, v120
	s_nop 1
	v_addc_co_u32_e32 v119, vcc, 0, v121, vcc
	global_load_dwordx2 v[188:189], v[64:65], off nt
	global_load_dwordx2 v[186:187], v[66:67], off nt
	global_load_dwordx2 v[114:115], v[68:69], off nt
	s_nop 0
	global_load_dwordx2 v[118:119], v[118:119], off nt
	v_add_co_u32_e32 v64, vcc, s15, v120
	s_nop 1
	v_addc_co_u32_e32 v65, vcc, 0, v121, vcc
	v_add_co_u32_e32 v66, vcc, s12, v124
	s_nop 1
	v_addc_co_u32_e32 v67, vcc, 0, v125, vcc
	v_add_co_u32_e32 v68, vcc, s15, v124
	s_nop 1
	v_addc_co_u32_e32 v69, vcc, 0, v125, vcc
	v_add_co_u32_e32 v126, vcc, s12, v176
	s_nop 1
	v_addc_co_u32_e32 v127, vcc, 0, v177, vcc
	global_load_dwordx2 v[184:185], v[64:65], off nt
	global_load_dwordx2 v[182:183], v[66:67], off nt
	global_load_dwordx2 v[122:123], v[68:69], off nt
	s_nop 0
	global_load_dwordx2 v[126:127], v[126:127], off nt
	s_waitcnt vmcnt(31)
	ds_swizzle_b32 v66, v178 offset:swizzle(SWAP,1)
	v_add_co_u32_e32 v64, vcc, s15, v176
	s_waitcnt lgkmcnt(0)
	v_add_f32_e32 v66, v178, v66
	v_addc_co_u32_e32 v65, vcc, 0, v177, vcc
	global_load_dwordx2 v[178:179], v[64:65], off nt
	ds_swizzle_b32 v67, v66 offset:swizzle(SWAP,2)
	s_waitcnt lgkmcnt(0)
	v_add_f32_e32 v64, v66, v67
	ds_swizzle_b32 v65, v64 offset:swizzle(SWAP,4)
	s_waitcnt lgkmcnt(0)
	v_add_f32_e32 v64, v64, v65
	ds_swizzle_b32 v65, v64 offset:swizzle(SWAP,8)
	s_waitcnt lgkmcnt(0)
	v_add_f32_e32 v64, v64, v65
	ds_swizzle_b32 v65, v64 offset:swizzle(SWAP,16)
	s_waitcnt lgkmcnt(0)
	v_add_f32_e32 v64, v64, v65
	v_mov_b32_e32 v65, v64
	s_nop 1
	v_permlane32_swap_b32_e32 v64, v65
	v_add_f32_e32 v64, v64, v65
	v_fmamk_f32 v64, v64, 0x39800000, v216
	v_mul_f32_e32 v65, 0x4f800000, v64
	v_cmp_gt_f32_e32 vcc, s4, v64
	s_nop 1
	v_cndmask_b32_e32 v64, v64, v65, vcc
	v_sqrt_f32_e32 v65, v64
	s_nop 0
	v_add_u32_e32 v66, -1, v65
	v_fma_f32 v67, -v66, v65, v64
	v_cmp_ge_f32_e64 s[4:5], 0, v67
	v_add_u32_e32 v67, 1, v65
	s_nop 0
	v_cndmask_b32_e64 v66, v65, v66, s[4:5]
	v_fma_f32 v65, -v67, v65, v64
	v_cmp_lt_f32_e64 s[4:5], 0, v65
	s_nop 1
	v_cndmask_b32_e64 v65, v66, v67, s[4:5]
	v_mul_f32_e32 v66, 0x37800000, v65
	v_cndmask_b32_e32 v65, v65, v66, vcc
	v_cmp_class_f32_e32 vcc, v64, v239
	s_nop 1
	v_cndmask_b32_e32 v64, v65, v64, vcc
	v_div_scale_f32 v65, s[4:5], v64, v64, 1.0
	v_rcp_f32_e32 v66, v65
	s_nop 0
	v_fma_f32 v67, -v65, v66, 1.0
	v_fmac_f32_e32 v66, v67, v66
	v_div_scale_f32 v67, vcc, 1.0, v64, 1.0
	v_mul_f32_e32 v68, v67, v66
	v_fma_f32 v69, -v65, v68, v67
	v_fmac_f32_e32 v68, v69, v66
	v_fma_f32 v65, -v65, v68, v67
	v_div_fmas_f32 v65, v65, v66, v68
	v_div_fixup_f32 v180, v65, v64, 1.0
	s_waitcnt vmcnt(20)
	v_lshlrev_b32_e32 v66, 16, v202
	v_and_b32_e32 v67, 0xffff0000, v202
	v_lshlrev_b32_e32 v64, 16, v198
	v_and_b32_e32 v65, 0xffff0000, v198
	v_pk_mul_f32 v[66:67], v[180:181], v[66:67] op_sel_hi:[0,1]
	v_lshlrev_b32_e32 v68, 16, v203
	v_and_b32_e32 v69, 0xffff0000, v203
	v_pk_fma_f32 v[64:65], v[60:61], v[66:67], v[64:65]
	v_lshlrev_b32_e32 v66, 16, v199
	v_and_b32_e32 v67, 0xffff0000, v199
	v_pk_mul_f32 v[68:69], v[180:181], v[68:69] op_sel_hi:[0,1]
	v_pk_fma_f32 v[66:67], v[62:63], v[68:69], v[66:67]
	v_cndmask_b32_e64 v68, 0, 1, s[0:1]
	v_cmp_ne_u32_e64 s[4:5], 1, v68
	s_andn2_b64 vcc, exec, s[0:1]
	v_lshl_add_u64 v[198:199], v[128:129], 2, s[30:31]
	s_cbranch_vccnz .LBB0_1111
	global_store_dwordx4 v[198:199], v[64:67], off offset:0 sc1 nt
	s_nop 1
	s_cbranch_execnz .LBB0_1060
; template <int OFF = 0, class V> __device__ __forceinline__ void st_wt16(void* p, V v) { static_assert(sizeof(V) == 16, ""); asm volatile("global_store_dwordx4 %0, %1, off offset:%2 sc1\n\ts_nop 1" :: "v"(p), "v"(v), "i"(OFF)); }
; template <int OFF = 0, class V> __device__ __forceinline__ void st_wt8(void* p, V v) { static_assert(sizeof(V) == 8, ""); asm volatile("global_store_dwordx2 %0, %1, off offset:%2 sc1\n\ts_nop 1" :: "v"(p), "v"(v), "i"(OFF)); }
; __device__ __forceinline__ unsigned pk2(float lo, float hi) { return pg8::cvt_pk_bf16(lo, hi); }
; __device__ __forceinline__ float bf_lo(unsigned w) { return __uint_as_float(w << 16); }
; __device__ __forceinline__ float bf_hi(unsigned w) { return __uint_as_float(w & 0xffff0000u); }
; __device__ __forceinline__ void resid_rows(bf16* __restrict__ XB, const bf16* __restrict__ Y, const float* __restrict__ PART, const float* __restrict__ g, float* __restrict__ RS, ...
;     ...
;         for (int j = 0; j < 16; ++j) { const int c = (lane + 64 * j) * 4;
;             f32x4 o; o.x = bf_lo(xr[j].x) + bf_lo(yr[j].x) * ry * gv[j].x; o.y = bf_hi(xr[j].x) + bf_hi(yr[j].x) * ry * gv[j].y; o.z = bf_lo(xr[j].y) + bf_lo(yr[j].y) * ry * gv[j].z; o.w = bf_hi(xr[j].y) + bf_hi(yr[j].y) * ry * gv[j].w;
;             ss += (o.x * o.x + o.y * o.y) + (o.z * o.z + o.w * o.w); ov[j] = o; am = fmaxf(fmaxf(am, fmaxf(fabsf(o.x), fabsf(o.y))), fmaxf(fabsf(o.z), fabsf(o.w)));
;             if (outf) st_wt16(outf + (size_t)m * DM + c, o); else { v2u ob; ob.x = pk2(o.x, o.y); ob.y = pk2(o.z, o.w); st_wt8(xrow + c, ob); } }
.LBB0_1059:
	s_mov_b64 s[10:11], 0x2d800000
	v_lshl_add_u64 v[68:69], v[96:97], 0, s[10:11]
	v_cvt_pk_bf16_f32 v202, v64, v65
	v_cvt_pk_bf16_f32 v203, v66, v67
	s_nop 0
	global_store_dwordx2 v[68:69], v[202:203], off offset:0 sc1 nt
	s_nop 1
.LBB0_1060:
	v_mov_b32_e32 v181, v180
	s_waitcnt vmcnt(19)
	v_lshlrev_b32_e32 v202, 16, v72
	v_and_b32_e32 v203, 0xffff0000, v72
	v_lshlrev_b32_e32 v72, 16, v73
	v_and_b32_e32 v73, 0xffff0000, v73
	v_lshlrev_b32_e32 v68, 16, v70
	v_and_b32_e32 v69, 0xffff0000, v70
	v_pk_mul_f32 v[202:203], v[180:181], v[202:203]
	v_lshlrev_b32_e32 v70, 16, v71
	v_and_b32_e32 v71, 0xffff0000, v71
	v_pk_mul_f32 v[72:73], v[180:181], v[72:73]
	v_pk_fma_f32 v[68:69], v[56:57], v[202:203], v[68:69]
	s_and_b64 vcc, exec, s[4:5]
	v_pk_fma_f32 v[70:71], v[58:59], v[72:73], v[70:71]
	s_cbranch_vccnz .LBB0_1112
	s_mov_b64 s[10:11], 0x400
	v_lshl_add_u64 v[72:73], v[198:199], 0, s[10:11]
	global_store_dwordx4 v[72:73], v[68:71], off offset:0 sc1 nt
	s_nop 1
	s_cbranch_execnz .LBB0_1063
.LBB0_1062:
	s_mov_b64 s[10:11], 0x2d800200
	v_lshl_add_u64 v[72:73], v[96:97], 0, s[10:11]
	v_cvt_pk_bf16_f32 v202, v68, v69
	v_cvt_pk_bf16_f32 v203, v70, v71
	s_nop 0
	global_store_dwordx2 v[72:73], v[202:203], off offset:0 sc1 nt
	s_nop 1
.LBB0_1063:
	s_waitcnt vmcnt(18)
	v_lshlrev_b32_e32 v202, 16, v76
	v_and_b32_e32 v203, 0xffff0000, v76
	v_lshlrev_b32_e32 v76, 16, v77
	v_and_b32_e32 v77, 0xffff0000, v77
	v_lshlrev_b32_e32 v72, 16, v74
	v_and_b32_e32 v73, 0xffff0000, v74
	v_pk_mul_f32 v[202:203], v[180:181], v[202:203]
	v_lshlrev_b32_e32 v74, 16, v75
	v_and_b32_e32 v75, 0xffff0000, v75
	v_pk_mul_f32 v[76:77], v[180:181], v[76:77]
	v_pk_fma_f32 v[72:73], v[52:53], v[202:203], v[72:73]
	s_and_b64 vcc, exec, s[4:5]
	v_pk_fma_f32 v[74:75], v[54:55], v[76:77], v[74:75]
	s_cbranch_vccnz .LBB0_1113
	s_mov_b64 s[10:11], 0x800
	v_lshl_add_u64 v[76:77], v[198:199], 0, s[10:11]
	global_store_dwordx4 v[76:77], v[72:75], off offset:0 sc1 nt
	s_nop 1
	s_cbranch_execnz .LBB0_1066
.LBB0_1065:
	s_mov_b64 s[10:11], 0x2d800400
	v_lshl_add_u64 v[76:77], v[96:97], 0, s[10:11]
	v_cvt_pk_bf16_f32 v202, v72, v73
	v_cvt_pk_bf16_f32 v203, v74, v75
	s_nop 0
	global_store_dwordx2 v[76:77], v[202:203], off offset:0 sc1 nt
	s_nop 1
.LBB0_1066:
	v_lshlrev_b32_e32 v202, 16, v80
	v_and_b32_e32 v203, 0xffff0000, v80
	v_lshlrev_b32_e32 v80, 16, v81
	v_and_b32_e32 v81, 0xffff0000, v81
	v_lshlrev_b32_e32 v76, 16, v78
	v_and_b32_e32 v77, 0xffff0000, v78
	v_pk_mul_f32 v[202:203], v[180:181], v[202:203]
	v_lshlrev_b32_e32 v78, 16, v79
	v_and_b32_e32 v79, 0xffff0000, v79
	v_pk_mul_f32 v[80:81], v[180:181], v[80:81]
	v_pk_fma_f32 v[76:77], v[48:49], v[202:203], v[76:77]
	s_and_b64 vcc, exec, s[4:5]
	v_pk_fma_f32 v[78:79], v[50:51], v[80:81], v[78:79]
	s_cbranch_vccnz .LBB0_1114
	s_mov_b64 s[10:11], 0xc00
	v_lshl_add_u64 v[80:81], v[198:199], 0, s[10:11]
	global_store_dwordx4 v[80:81], v[76:79], off offset:0 sc1 nt
	s_nop 1
	s_cbranch_execnz .LBB0_1069
.LBB0_1068:
	s_mov_b64 s[10:11], 0x2d800600
	v_lshl_add_u64 v[80:81], v[96:97], 0, s[10:11]
	v_cvt_pk_bf16_f32 v198, v76, v77
	v_cvt_pk_bf16_f32 v199, v78, v79
	s_nop 0
	global_store_dwordx2 v[80:81], v[198:199], off offset:0 sc1 nt
	s_nop 1
.LBB0_1069:
	v_lshlrev_b32_e32 v198, 16, v84
	v_and_b32_e32 v199, 0xffff0000, v84
	v_lshlrev_b32_e32 v84, 16, v85
	v_and_b32_e32 v85, 0xffff0000, v85
	v_lshlrev_b32_e32 v80, 16, v82
	v_and_b32_e32 v81, 0xffff0000, v82
	v_pk_mul_f32 v[198:199], v[180:181], v[198:199]
	v_lshlrev_b32_e32 v82, 16, v83
	v_and_b32_e32 v83, 0xffff0000, v83
	v_pk_mul_f32 v[84:85], v[180:181], v[84:85]
	v_pk_fma_f32 v[80:81], v[44:45], v[198:199], v[80:81]
	s_and_b64 vcc, exec, s[4:5]
	v_pk_fma_f32 v[82:83], v[46:47], v[84:85], v[82:83]
	s_cbranch_vccnz .LBB0_1115
	v_lshl_add_u64 v[84:85], v[130:131], 2, s[30:31]
	global_store_dwordx4 v[84:85], v[80:83], off offset:0 sc1 nt
	s_nop 1
	s_cbranch_execnz .LBB0_1072
.LBB0_1071:
	s_mov_b64 s[10:11], 0x2d800800
	v_lshl_add_u64 v[84:85], v[96:97], 0, s[10:11]
	v_cvt_pk_bf16_f32 v198, v80, v81
	v_cvt_pk_bf16_f32 v199, v82, v83
	s_nop 0
	global_store_dwordx2 v[84:85], v[198:199], off offset:0 sc1 nt
	s_nop 1
.LBB0_1072:
	v_lshlrev_b32_e32 v198, 16, v88
	v_and_b32_e32 v199, 0xffff0000, v88
	v_lshlrev_b32_e32 v88, 16, v89
	v_and_b32_e32 v89, 0xffff0000, v89
	v_lshlrev_b32_e32 v84, 16, v86
	v_and_b32_e32 v85, 0xffff0000, v86
	v_pk_mul_f32 v[198:199], v[180:181], v[198:199]
	v_lshlrev_b32_e32 v86, 16, v87
	v_and_b32_e32 v87, 0xffff0000, v87
	v_pk_mul_f32 v[88:89], v[180:181], v[88:89]
	v_pk_fma_f32 v[84:85], v[40:41], v[198:199], v[84:85]
	s_and_b64 vcc, exec, s[4:5]
	v_pk_fma_f32 v[86:87], v[42:43], v[88:89], v[86:87]
	s_cbranch_vccnz .LBB0_1116
	v_lshl_add_u64 v[88:89], v[132:133], 2, s[30:31]
	global_store_dwordx4 v[88:89], v[84:87], off offset:0 sc1 nt
	s_nop 1
	s_cbranch_execnz .LBB0_1075
.LBB0_1074:
	s_mov_b64 s[10:11], 0x2d800a00
	v_lshl_add_u64 v[88:89], v[96:97], 0, s[10:11]
	v_cvt_pk_bf16_f32 v198, v84, v85
	v_cvt_pk_bf16_f32 v199, v86, v87
	s_nop 0
	global_store_dwordx2 v[88:89], v[198:199], off offset:0 sc1 nt
	s_nop 1
.LBB0_1075:
	v_lshlrev_b32_e32 v198, 16, v92
	v_and_b32_e32 v199, 0xffff0000, v92
	v_lshlrev_b32_e32 v92, 16, v93
	v_and_b32_e32 v93, 0xffff0000, v93
	v_lshlrev_b32_e32 v88, 16, v90
	v_and_b32_e32 v89, 0xffff0000, v90
	v_pk_mul_f32 v[198:199], v[180:181], v[198:199]
	v_lshlrev_b32_e32 v90, 16, v91
	v_and_b32_e32 v91, 0xffff0000, v91
	v_pk_mul_f32 v[92:93], v[180:181], v[92:93]
	v_pk_fma_f32 v[88:89], v[36:37], v[198:199], v[88:89]
	s_and_b64 vcc, exec, s[4:5]
	v_pk_fma_f32 v[90:91], v[38:39], v[92:93], v[90:91]
	s_cbranch_vccnz .LBB0_1117
	v_lshl_add_u64 v[92:93], v[134:135], 2, s[30:31]
	global_store_dwordx4 v[92:93], v[88:91], off offset:0 sc1 nt
	s_nop 1
	s_cbranch_execnz .LBB0_1078
; template <int OFF = 0, class V> __device__ __forceinline__ void st_wt16(void* p, V v) { static_assert(sizeof(V) == 16, ""); asm volatile("global_store_dwordx4 %0, %1, off offset:%2 sc1\n\ts_nop 1" :: "v"(p), "v"(v), "i"(OFF)); }
; template <int OFF = 0, class V> __device__ __forceinline__ void st_wt8(void* p, V v) { static_assert(sizeof(V) == 8, ""); asm volatile("global_store_dwordx2 %0, %1, off offset:%2 sc1\n\ts_nop 1" :: "v"(p), "v"(v), "i"(OFF)); }
; __device__ __forceinline__ unsigned pk2(float lo, float hi) { return pg8::cvt_pk_bf16(lo, hi); }
; __device__ __forceinline__ float bf_lo(unsigned w) { return __uint_as_float(w << 16); }
; __device__ __forceinline__ float bf_hi(unsigned w) { return __uint_as_float(w & 0xffff0000u); }
; __device__ __forceinline__ void resid_rows(bf16* __restrict__ XB, const bf16* __restrict__ Y, const float* __restrict__ PART, const float* __restrict__ g, float* __restrict__ RS, ...
;     ...
;         for (int j = 0; j < 16; ++j) { const int c = (lane + 64 * j) * 4;
;             f32x4 o; o.x = bf_lo(xr[j].x) + bf_lo(yr[j].x) * ry * gv[j].x; o.y = bf_hi(xr[j].x) + bf_hi(yr[j].x) * ry * gv[j].y; o.z = bf_lo(xr[j].y) + bf_lo(yr[j].y) * ry * gv[j].z; o.w = bf_hi(xr[j].y) + bf_hi(yr[j].y) * ry * gv[j].w;
;             ss += (o.x * o.x + o.y * o.y) + (o.z * o.z + o.w * o.w); ov[j] = o; am = fmaxf(fmaxf(am, fmaxf(fabsf(o.x), fabsf(o.y))), fmaxf(fabsf(o.z), fabsf(o.w)));
;             if (outf) st_wt16(outf + (size_t)m * DM + c, o); else { v2u ob; ob.x = pk2(o.x, o.y); ob.y = pk2(o.z, o.w); st_wt8(xrow + c, ob); } }
.LBB0_1077:
	s_mov_b64 s[10:11], 0x2d800c00
	v_lshl_add_u64 v[92:93], v[96:97], 0, s[10:11]
	v_cvt_pk_bf16_f32 v198, v88, v89
	v_cvt_pk_bf16_f32 v199, v90, v91
	s_nop 0
	global_store_dwordx2 v[92:93], v[198:199], off offset:0 sc1 nt
	s_nop 1
.LBB0_1078:
	s_waitcnt vmcnt(16)
	v_lshlrev_b32_e32 v198, 16, v196
	v_and_b32_e32 v199, 0xffff0000, v196
	v_lshlrev_b32_e32 v196, 16, v197
	v_and_b32_e32 v197, 0xffff0000, v197
	v_lshlrev_b32_e32 v92, 16, v94
	v_and_b32_e32 v93, 0xffff0000, v94
	v_pk_mul_f32 v[198:199], v[180:181], v[198:199]
	v_lshlrev_b32_e32 v94, 16, v95
	v_and_b32_e32 v95, 0xffff0000, v95
	v_pk_mul_f32 v[196:197], v[180:181], v[196:197]
	v_pk_fma_f32 v[92:93], v[32:33], v[198:199], v[92:93]
	s_and_b64 vcc, exec, s[4:5]
	v_pk_fma_f32 v[94:95], v[34:35], v[196:197], v[94:95]
	s_cbranch_vccnz .LBB0_1118
	v_lshl_add_u64 v[196:197], v[136:137], 2, s[30:31]
	global_store_dwordx4 v[196:197], v[92:95], off offset:0 sc1 nt
	s_nop 1
	s_cbranch_execnz .LBB0_1081
.LBB0_1080:
	s_mov_b64 s[10:11], 0x2d800e00
	v_lshl_add_u64 v[96:97], v[96:97], 0, s[10:11]
	v_cvt_pk_bf16_f32 v196, v92, v93
	v_cvt_pk_bf16_f32 v197, v94, v95
	s_nop 0
	global_store_dwordx2 v[96:97], v[196:197], off offset:0 sc1 nt
	s_nop 1
.LBB0_1081:
	s_waitcnt vmcnt(14)
	v_lshlrev_b32_e32 v196, 16, v98
	v_and_b32_e32 v197, 0xffff0000, v98
	v_lshlrev_b32_e32 v98, 16, v99
	v_and_b32_e32 v99, 0xffff0000, v99
	v_lshlrev_b32_e32 v96, 16, v194
	v_and_b32_e32 v97, 0xffff0000, v194
	v_pk_mul_f32 v[196:197], v[180:181], v[196:197]
	v_lshlrev_b32_e32 v194, 16, v195
	v_and_b32_e32 v195, 0xffff0000, v195
	v_pk_mul_f32 v[98:99], v[180:181], v[98:99]
	v_pk_fma_f32 v[96:97], v[28:29], v[196:197], v[96:97]
	s_and_b64 vcc, exec, s[4:5]
	v_pk_fma_f32 v[98:99], v[30:31], v[98:99], v[194:195]
	s_cbranch_vccnz .LBB0_1119
	v_lshl_add_u64 v[194:195], v[138:139], 2, s[30:31]
	global_store_dwordx4 v[194:195], v[96:99], off offset:0 sc1 nt
	s_nop 1
	s_cbranch_execnz .LBB0_1084
.LBB0_1083:
	s_mov_b64 s[10:11], 0x2d800000
	v_lshl_add_u64 v[100:101], v[100:101], 0, s[10:11]
	v_cvt_pk_bf16_f32 v194, v96, v97
	v_cvt_pk_bf16_f32 v195, v98, v99
	s_nop 0
	global_store_dwordx2 v[100:101], v[194:195], off offset:0 sc1 nt
	s_nop 1
.LBB0_1084:
	s_waitcnt vmcnt(12)
	v_lshlrev_b32_e32 v194, 16, v192
	v_and_b32_e32 v195, 0xffff0000, v192
	v_lshlrev_b32_e32 v192, 16, v193
	v_and_b32_e32 v193, 0xffff0000, v193
	v_lshlrev_b32_e32 v100, 16, v102
	v_and_b32_e32 v101, 0xffff0000, v102
	v_pk_mul_f32 v[194:195], v[180:181], v[194:195]
	v_lshlrev_b32_e32 v102, 16, v103
	v_and_b32_e32 v103, 0xffff0000, v103
	v_pk_mul_f32 v[192:193], v[180:181], v[192:193]
	v_pk_fma_f32 v[100:101], v[24:25], v[194:195], v[100:101]
	s_and_b64 vcc, exec, s[4:5]
	v_pk_fma_f32 v[102:103], v[26:27], v[192:193], v[102:103]
	s_cbranch_vccnz .LBB0_1120
	v_lshl_add_u64 v[192:193], v[140:141], 2, s[30:31]
	global_store_dwordx4 v[192:193], v[100:103], off offset:0 sc1 nt
	s_nop 1
	s_cbranch_execnz .LBB0_1087
.LBB0_1086:
	s_mov_b64 s[10:11], 0x2d800000
	v_lshl_add_u64 v[104:105], v[104:105], 0, s[10:11]
	v_cvt_pk_bf16_f32 v192, v100, v101
	v_cvt_pk_bf16_f32 v193, v102, v103
	s_nop 0
	global_store_dwordx2 v[104:105], v[192:193], off offset:0 sc1 nt
	s_nop 1
.LBB0_1087:
	s_waitcnt vmcnt(10)
	v_lshlrev_b32_e32 v192, 16, v106
	v_and_b32_e32 v193, 0xffff0000, v106
	v_lshlrev_b32_e32 v106, 16, v107
	v_and_b32_e32 v107, 0xffff0000, v107
	v_lshlrev_b32_e32 v104, 16, v190
	v_and_b32_e32 v105, 0xffff0000, v190
	v_pk_mul_f32 v[192:193], v[180:181], v[192:193]
	v_lshlrev_b32_e32 v190, 16, v191
	v_and_b32_e32 v191, 0xffff0000, v191
	v_pk_mul_f32 v[106:107], v[180:181], v[106:107]
	v_pk_fma_f32 v[104:105], v[20:21], v[192:193], v[104:105]
	s_and_b64 vcc, exec, s[4:5]
	v_pk_fma_f32 v[106:107], v[22:23], v[106:107], v[190:191]
	s_cbranch_vccnz .LBB0_1121
	v_lshl_add_u64 v[190:191], v[142:143], 2, s[30:31]
	global_store_dwordx4 v[190:191], v[104:107], off offset:0 sc1 nt
	s_nop 1
	s_cbranch_execnz .LBB0_1090
.LBB0_1089:
	s_mov_b64 s[10:11], 0x2d800000
	v_lshl_add_u64 v[108:109], v[108:109], 0, s[10:11]
	v_cvt_pk_bf16_f32 v190, v104, v105
	v_cvt_pk_bf16_f32 v191, v106, v107
	s_nop 0
	global_store_dwordx2 v[108:109], v[190:191], off offset:0 sc1 nt
	s_nop 1
.LBB0_1090:
	s_waitcnt vmcnt(8)
	v_lshlrev_b32_e32 v190, 16, v188
	v_and_b32_e32 v191, 0xffff0000, v188
	v_lshlrev_b32_e32 v188, 16, v189
	v_and_b32_e32 v189, 0xffff0000, v189
	v_lshlrev_b32_e32 v108, 16, v110
	v_and_b32_e32 v109, 0xffff0000, v110
	v_pk_mul_f32 v[190:191], v[180:181], v[190:191]
	v_lshlrev_b32_e32 v110, 16, v111
	v_and_b32_e32 v111, 0xffff0000, v111
	v_pk_mul_f32 v[188:189], v[180:181], v[188:189]
	v_pk_fma_f32 v[108:109], v[16:17], v[190:191], v[108:109]
	s_and_b64 vcc, exec, s[4:5]
	v_pk_fma_f32 v[110:111], v[18:19], v[188:189], v[110:111]
	s_cbranch_vccnz .LBB0_1122
	v_lshl_add_u64 v[188:189], v[144:145], 2, s[30:31]
	global_store_dwordx4 v[188:189], v[108:111], off offset:0 sc1 nt
	s_nop 1
	s_cbranch_execnz .LBB0_1093
; template <int OFF = 0, class V> __device__ __forceinline__ void st_wt16(void* p, V v) { static_assert(sizeof(V) == 16, ""); asm volatile("global_store_dwordx4 %0, %1, off offset:%2 sc1\n\ts_nop 1" :: "v"(p), "v"(v), "i"(OFF)); }
; template <int OFF = 0, class V> __device__ __forceinline__ void st_wt8(void* p, V v) { static_assert(sizeof(V) == 8, ""); asm volatile("global_store_dwordx2 %0, %1, off offset:%2 sc1\n\ts_nop 1" :: "v"(p), "v"(v), "i"(OFF)); }
; __device__ __forceinline__ unsigned pk2(float lo, float hi) { return pg8::cvt_pk_bf16(lo, hi); }
; __device__ __forceinline__ float bf_lo(unsigned w) { return __uint_as_float(w << 16); }
; __device__ __forceinline__ float bf_hi(unsigned w) { return __uint_as_float(w & 0xffff0000u); }
; __device__ __forceinline__ void resid_rows(bf16* __restrict__ XB, const bf16* __restrict__ Y, const float* __restrict__ PART, const float* __restrict__ g, float* __restrict__ RS, ...
;     ...
;         for (int j = 0; j < 16; ++j) { const int c = (lane + 64 * j) * 4;
;             f32x4 o; o.x = bf_lo(xr[j].x) + bf_lo(yr[j].x) * ry * gv[j].x; o.y = bf_hi(xr[j].x) + bf_hi(yr[j].x) * ry * gv[j].y; o.z = bf_lo(xr[j].y) + bf_lo(yr[j].y) * ry * gv[j].z; o.w = bf_hi(xr[j].y) + bf_hi(yr[j].y) * ry * gv[j].w;
;             ss += (o.x * o.x + o.y * o.y) + (o.z * o.z + o.w * o.w); ov[j] = o; am = fmaxf(fmaxf(am, fmaxf(fabsf(o.x), fabsf(o.y))), fmaxf(fabsf(o.z), fabsf(o.w)));
;             if (outf) st_wt16(outf + (size_t)m * DM + c, o); else { v2u ob; ob.x = pk2(o.x, o.y); ob.y = pk2(o.z, o.w); st_wt8(xrow + c, ob); } }
.LBB0_1092:
	s_mov_b64 s[10:11], 0x2d800000
	v_lshl_add_u64 v[112:113], v[112:113], 0, s[10:11]
	v_cvt_pk_bf16_f32 v188, v108, v109
	v_cvt_pk_bf16_f32 v189, v110, v111
	s_nop 0
	global_store_dwordx2 v[112:113], v[188:189], off offset:0 sc1 nt
	s_nop 1
.LBB0_1093:
	s_waitcnt vmcnt(6)
	v_lshlrev_b32_e32 v188, 16, v114
	v_and_b32_e32 v189, 0xffff0000, v114
	v_lshlrev_b32_e32 v114, 16, v115
	v_and_b32_e32 v115, 0xffff0000, v115
	v_lshlrev_b32_e32 v112, 16, v186
	v_and_b32_e32 v113, 0xffff0000, v186
	v_pk_mul_f32 v[188:189], v[180:181], v[188:189]
	v_lshlrev_b32_e32 v186, 16, v187
	v_and_b32_e32 v187, 0xffff0000, v187
	v_pk_mul_f32 v[114:115], v[180:181], v[114:115]
	v_pk_fma_f32 v[112:113], v[12:13], v[188:189], v[112:113]
	s_and_b64 vcc, exec, s[4:5]
	v_pk_fma_f32 v[114:115], v[14:15], v[114:115], v[186:187]
	s_cbranch_vccnz .LBB0_1123
	v_lshl_add_u64 v[186:187], v[146:147], 2, s[30:31]
	global_store_dwordx4 v[186:187], v[112:115], off offset:0 sc1 nt
	s_nop 1
	s_cbranch_execnz .LBB0_1096
.LBB0_1095:
	s_mov_b64 s[10:11], 0x2d800000
	v_lshl_add_u64 v[116:117], v[116:117], 0, s[10:11]
	v_cvt_pk_bf16_f32 v186, v112, v113
	v_cvt_pk_bf16_f32 v187, v114, v115
	s_nop 0
	global_store_dwordx2 v[116:117], v[186:187], off offset:0 sc1 nt
	s_nop 1
.LBB0_1096:
	s_waitcnt vmcnt(4)
	v_lshlrev_b32_e32 v186, 16, v184
	v_and_b32_e32 v187, 0xffff0000, v184
	v_lshlrev_b32_e32 v184, 16, v185
	v_and_b32_e32 v185, 0xffff0000, v185
	v_lshlrev_b32_e32 v116, 16, v118
	v_and_b32_e32 v117, 0xffff0000, v118
	v_pk_mul_f32 v[186:187], v[180:181], v[186:187]
	v_lshlrev_b32_e32 v118, 16, v119
	v_and_b32_e32 v119, 0xffff0000, v119
	v_pk_mul_f32 v[184:185], v[180:181], v[184:185]
	v_pk_fma_f32 v[116:117], v[8:9], v[186:187], v[116:117]
	s_and_b64 vcc, exec, s[4:5]
	v_pk_fma_f32 v[118:119], v[10:11], v[184:185], v[118:119]
	s_cbranch_vccnz .LBB0_1124
	v_lshl_add_u64 v[184:185], v[148:149], 2, s[30:31]
	global_store_dwordx4 v[184:185], v[116:119], off offset:0 sc1 nt
	s_nop 1
	s_cbranch_execnz .LBB0_1099
.LBB0_1098:
	s_mov_b64 s[10:11], 0x2d800000
	v_lshl_add_u64 v[120:121], v[120:121], 0, s[10:11]
	v_cvt_pk_bf16_f32 v184, v116, v117
	v_cvt_pk_bf16_f32 v185, v118, v119
	s_nop 0
	global_store_dwordx2 v[120:121], v[184:185], off offset:0 sc1 nt
	s_nop 1
.LBB0_1099:
	s_waitcnt vmcnt(2)
	v_lshlrev_b32_e32 v184, 16, v122
	v_and_b32_e32 v185, 0xffff0000, v122
	v_lshlrev_b32_e32 v122, 16, v123
	v_and_b32_e32 v123, 0xffff0000, v123
	v_lshlrev_b32_e32 v120, 16, v182
	v_and_b32_e32 v121, 0xffff0000, v182
	v_pk_mul_f32 v[184:185], v[180:181], v[184:185]
	v_lshlrev_b32_e32 v182, 16, v183
	v_and_b32_e32 v183, 0xffff0000, v183
	v_pk_mul_f32 v[122:123], v[180:181], v[122:123]
	v_pk_fma_f32 v[120:121], v[4:5], v[184:185], v[120:121]
	s_and_b64 vcc, exec, s[4:5]
	v_pk_fma_f32 v[122:123], v[6:7], v[122:123], v[182:183]
	s_cbranch_vccnz .LBB0_1125
	v_lshl_add_u64 v[182:183], v[150:151], 2, s[30:31]
	global_store_dwordx4 v[182:183], v[120:123], off offset:0 sc1 nt
	s_nop 1
	s_cbranch_execnz .LBB0_1102
.LBB0_1101:
	s_mov_b64 s[10:11], 0x2d800000
	v_lshl_add_u64 v[124:125], v[124:125], 0, s[10:11]
	v_cvt_pk_bf16_f32 v182, v120, v121
	v_cvt_pk_bf16_f32 v183, v122, v123
	s_nop 0
	global_store_dwordx2 v[124:125], v[182:183], off offset:0 sc1 nt
	s_nop 1
.LBB0_1102:
	s_waitcnt vmcnt(0)
	v_lshlrev_b32_e32 v182, 16, v178
	v_and_b32_e32 v183, 0xffff0000, v178
	v_lshlrev_b32_e32 v178, 16, v179
	v_and_b32_e32 v179, 0xffff0000, v179
	v_lshlrev_b32_e32 v124, 16, v126
	v_and_b32_e32 v125, 0xffff0000, v126
	v_pk_mul_f32 v[182:183], v[180:181], v[182:183]
	v_lshlrev_b32_e32 v126, 16, v127
	v_and_b32_e32 v127, 0xffff0000, v127
	v_pk_mul_f32 v[178:179], v[180:181], v[178:179]
	v_pk_fma_f32 v[124:125], v[0:1], v[182:183], v[124:125]
	s_and_b64 vcc, exec, s[4:5]
	v_pk_fma_f32 v[126:127], v[2:3], v[178:179], v[126:127]
	s_cbranch_vccnz .LBB0_1126
	v_lshl_add_u64 v[178:179], v[152:153], 2, s[30:31]
	global_store_dwordx4 v[178:179], v[124:127], off offset:0 sc1 nt
	s_nop 1
	s_cbranch_execnz .LBB0_1105
.LBB0_1104:
	s_mov_b64 s[4:5], 0x2d800000
	v_lshl_add_u64 v[176:177], v[176:177], 0, s[4:5]
	v_cvt_pk_bf16_f32 v178, v124, v125
	v_cvt_pk_bf16_f32 v179, v126, v127
	s_nop 0
	global_store_dwordx2 v[176:177], v[178:179], off offset:0 sc1 nt
	s_nop 1
